# gates epilogue: exec-masked om mini-branches converted to branchless v_cndmask, redundant nops removed
# speedup vs baseline: 1.0077x; 1.0028x over previous
.LBB0_453:
	s_add_u32 s12, s64, s92
	s_addc_u32 s13, s65, s93
	s_add_u32 s14, s12, 0x100
	s_addc_u32 s15, s13, 0
	s_and_b64 s[8:9], s[62:63], exec
	s_cselect_b32 s21, s61, s15
	s_cselect_b32 s20, s60, s14
	s_add_u32 s8, s58, s92
	s_addc_u32 s9, s59, s93
	s_add_u32 s14, s8, 0x100
	s_addc_u32 s15, s9, 0
	s_add_i32 s18, 0, 0x10000
	s_and_b64 s[8:9], s[62:63], exec
	s_cselect_b32 s9, s5, s15
	s_cselect_b32 s8, s7, s14
	s_add_u32 s36, s12, 0x40080
	s_addc_u32 s37, s13, 0
	s_add_i32 s24, s18, s39
	s_add_i32 m0, s40, 0xc000
	s_add_i32 s25, s40, 0xe000
	s_add_i32 s23, 0, 0x14000
	s_add_i32 s22, s24, 0x2000
	s_add_u32 vcc_lo, s8, 0x10000
	v_add_u32_e32 v140, s18, v238
	s_addc_u32 vcc_hi, s9, 0
	s_add_i32 s17, s23, s39
	ds_read_b128 v[76:79], v140
	ds_read_b128 v[84:87], v140 offset:1024
	ds_read_b128 v[88:91], v140 offset:2048
	ds_read_b128 v[140:143], v140 offset:3072
	s_add_i32 s16, s17, 0x2000
	s_add_i32 s15, 0, 0x18000
	s_add_u32 s92, s20, 0x40000
	s_addc_u32 s93, s21, 0
	s_add_i32 s14, s15, s39
	s_add_i32 s13, 0, 0x1c000
	s_add_i32 s12, s14, 0x2000
	s_add_u32 s62, s8, 0x10080
	s_addc_u32 s63, s9, 0
	s_add_i32 s19, s13, s39
	s_add_i32 s18, s19, 0x2000
	v_lshl_add_u64 v[158:159], s[36:37], 0, v[160:161]
	ds_read_b128 v[144:147], v240
	ds_read_b128 v[148:151], v240 offset:1024
	ds_read_b128 v[170:173], v240 offset:2048
	ds_read_b128 v[174:177], v240 offset:3072
	ds_read_b128 v[178:181], v240 offset:4096
	ds_read_b128 v[182:185], v240 offset:5120
	ds_read_b128 v[186:189], v240 offset:6144
	ds_read_b128 v[190:193], v240 offset:7168
	global_load_lds_dwordx4 v[158:159], off
	v_lshl_add_u64 v[158:159], s[36:37], 0, v[154:155]
	s_mov_b32 m0, s25
	s_nop 0
	global_load_lds_dwordx4 v[158:159], off
	s_waitcnt lgkmcnt(8)
	s_barrier
	s_waitcnt lgkmcnt(0)
	s_setprio 1
	s_waitcnt lgkmcnt(0)
	v_mfma_f32_16x16x32_bf16 v[136:139], v[76:79], v[144:147], v[136:139]
	v_mfma_f32_16x16x32_bf16 v[132:135], v[88:91], v[144:147], v[132:135]
	v_mfma_f32_16x16x32_bf16 v[128:131], v[76:79], v[170:173], v[128:131]
	v_mfma_f32_16x16x32_bf16 v[124:127], v[88:91], v[170:173], v[124:127]
	v_mfma_f32_16x16x32_bf16 v[120:123], v[76:79], v[178:181], v[120:123]
	v_mfma_f32_16x16x32_bf16 v[116:119], v[88:91], v[178:181], v[116:119]
	v_mfma_f32_16x16x32_bf16 v[112:115], v[76:79], v[186:189], v[112:115]
	v_mfma_f32_16x16x32_bf16 v[108:111], v[88:91], v[186:189], v[108:111]
	v_mfma_f32_16x16x32_bf16 v[136:139], v[84:87], v[148:151], v[136:139]
	v_mfma_f32_16x16x32_bf16 v[132:135], v[140:143], v[148:151], v[132:135]
	v_mfma_f32_16x16x32_bf16 v[128:131], v[84:87], v[174:177], v[128:131]
	v_mfma_f32_16x16x32_bf16 v[124:127], v[140:143], v[174:177], v[124:127]
	v_mfma_f32_16x16x32_bf16 v[120:123], v[84:87], v[182:185], v[120:123]
	v_mfma_f32_16x16x32_bf16 v[116:119], v[140:143], v[182:185], v[116:119]
	v_mfma_f32_16x16x32_bf16 v[112:115], v[84:87], v[190:193], v[112:115]
	v_mfma_f32_16x16x32_bf16 v[108:111], v[140:143], v[190:193], v[108:111]
	s_setprio 0
	s_barrier
	v_add_u32_e32 v158, s23, v238
	s_mov_b32 m0, s24
	ds_read_b128 v[194:197], v158
	ds_read_b128 v[198:201], v158 offset:1024
	ds_read_b128 v[202:205], v158 offset:2048
	ds_read_b128 v[206:209], v158 offset:3072
	v_lshl_add_u64 v[158:159], s[8:9], 0, v[152:153]
	global_load_lds_dwordx4 v[158:159], off
	v_lshl_add_u64 v[210:211], s[8:9], 0, v[156:157]
	s_mov_b32 m0, s22
	s_nop 0
	global_load_lds_dwordx4 v[210:211], off
	s_barrier
	s_waitcnt lgkmcnt(0)
	s_setprio 1
	s_waitcnt lgkmcnt(0)
	v_mfma_f32_16x16x32_bf16 v[60:63], v[194:197], v[144:147], v[60:63]
	v_mfma_f32_16x16x32_bf16 v[56:59], v[202:205], v[144:147], v[56:59]
	v_mfma_f32_16x16x32_bf16 v[52:55], v[194:197], v[170:173], v[52:55]
	v_mfma_f32_16x16x32_bf16 v[48:51], v[202:205], v[170:173], v[48:51]
	v_mfma_f32_16x16x32_bf16 v[44:47], v[194:197], v[178:181], v[44:47]
	v_mfma_f32_16x16x32_bf16 v[40:43], v[202:205], v[178:181], v[40:43]
	v_mfma_f32_16x16x32_bf16 v[36:39], v[194:197], v[186:189], v[36:39]
	v_mfma_f32_16x16x32_bf16 v[32:35], v[202:205], v[186:189], v[32:35]
	v_mfma_f32_16x16x32_bf16 v[60:63], v[198:201], v[148:151], v[60:63]
	v_mfma_f32_16x16x32_bf16 v[56:59], v[206:209], v[148:151], v[56:59]
	v_mfma_f32_16x16x32_bf16 v[52:55], v[198:201], v[174:177], v[52:55]
	v_mfma_f32_16x16x32_bf16 v[48:51], v[206:209], v[174:177], v[48:51]
	v_mfma_f32_16x16x32_bf16 v[44:47], v[198:201], v[182:185], v[44:47]
	v_mfma_f32_16x16x32_bf16 v[40:43], v[206:209], v[182:185], v[40:43]
	v_mfma_f32_16x16x32_bf16 v[36:39], v[198:201], v[190:193], v[36:39]
	v_mfma_f32_16x16x32_bf16 v[32:35], v[206:209], v[190:193], v[32:35]
	s_setprio 0
	s_mov_b32 m0, s40
	v_lshl_add_u64 v[212:213], s[20:21], 0, v[160:161]
	s_barrier
	ds_read_b128 v[144:147], v240 offset:16384
	ds_read_b128 v[148:151], v240 offset:17408
	ds_read_b128 v[170:173], v240 offset:18432
	ds_read_b128 v[174:177], v240 offset:19456
	ds_read_b128 v[178:181], v240 offset:20480
	ds_read_b128 v[182:185], v240 offset:21504
	ds_read_b128 v[186:189], v240 offset:22528
	ds_read_b128 v[190:193], v240 offset:23552
	global_load_lds_dwordx4 v[212:213], off
	v_lshl_add_u64 v[214:215], s[20:21], 0, v[154:155]
	s_mov_b32 m0, s41
	s_nop 0
	global_load_lds_dwordx4 v[214:215], off
	s_barrier
	s_waitcnt lgkmcnt(0)
	s_setprio 1
	s_waitcnt lgkmcnt(0)
	v_mfma_f32_16x16x32_bf16 v[104:107], v[76:79], v[144:147], v[104:107]
	v_mfma_f32_16x16x32_bf16 v[100:103], v[88:91], v[144:147], v[100:103]
	v_mfma_f32_16x16x32_bf16 v[96:99], v[76:79], v[170:173], v[96:99]
	v_mfma_f32_16x16x32_bf16 v[92:95], v[88:91], v[170:173], v[92:95]
	v_mfma_f32_16x16x32_bf16 v[80:83], v[76:79], v[178:181], v[80:83]
	v_mfma_f32_16x16x32_bf16 v[72:75], v[88:91], v[178:181], v[72:75]
	v_mfma_f32_16x16x32_bf16 v[68:71], v[76:79], v[186:189], v[68:71]
	v_mfma_f32_16x16x32_bf16 v[64:67], v[88:91], v[186:189], v[64:67]
	v_mfma_f32_16x16x32_bf16 v[104:107], v[84:87], v[148:151], v[104:107]
	v_mfma_f32_16x16x32_bf16 v[100:103], v[140:143], v[148:151], v[100:103]
	v_mfma_f32_16x16x32_bf16 v[96:99], v[84:87], v[174:177], v[96:99]
	v_mfma_f32_16x16x32_bf16 v[92:95], v[140:143], v[174:177], v[92:95]
	v_mfma_f32_16x16x32_bf16 v[80:83], v[84:87], v[182:185], v[80:83]
	v_mfma_f32_16x16x32_bf16 v[72:75], v[140:143], v[182:185], v[72:75]
	v_mfma_f32_16x16x32_bf16 v[68:71], v[84:87], v[190:193], v[68:71]
	v_mfma_f32_16x16x32_bf16 v[64:67], v[140:143], v[190:193], v[64:67]
	s_setprio 0
	s_barrier
	s_mov_b32 m0, s17
	v_lshl_add_u64 v[76:77], vcc, 0, v[152:153]
	global_load_lds_dwordx4 v[76:77], off
	v_lshl_add_u64 v[76:77], vcc, 0, v[156:157]
	s_mov_b32 m0, s16
	s_nop 0
	global_load_lds_dwordx4 v[76:77], off
	s_waitcnt vmcnt(6)
	s_barrier
	s_setprio 1
	v_mfma_f32_16x16x32_bf16 v[28:31], v[194:197], v[144:147], v[28:31]
	v_mfma_f32_16x16x32_bf16 v[24:27], v[202:205], v[144:147], v[24:27]
	v_mfma_f32_16x16x32_bf16 v[20:23], v[194:197], v[170:173], v[20:23]
	v_mfma_f32_16x16x32_bf16 v[16:19], v[202:205], v[170:173], v[16:19]
	v_mfma_f32_16x16x32_bf16 v[12:15], v[194:197], v[178:181], v[12:15]
	v_mfma_f32_16x16x32_bf16 v[8:11], v[202:205], v[178:181], v[8:11]
	v_mfma_f32_16x16x32_bf16 v[4:7], v[194:197], v[186:189], v[4:7]
	v_mfma_f32_16x16x32_bf16 v[0:3], v[202:205], v[186:189], v[0:3]
	v_mfma_f32_16x16x32_bf16 v[28:31], v[198:201], v[148:151], v[28:31]
	v_mfma_f32_16x16x32_bf16 v[24:27], v[206:209], v[148:151], v[24:27]
	v_mfma_f32_16x16x32_bf16 v[20:23], v[198:201], v[174:177], v[20:23]
	v_mfma_f32_16x16x32_bf16 v[16:19], v[206:209], v[174:177], v[16:19]
	v_mfma_f32_16x16x32_bf16 v[12:15], v[198:201], v[182:185], v[12:15]
	v_mfma_f32_16x16x32_bf16 v[8:11], v[206:209], v[182:185], v[8:11]
	v_mfma_f32_16x16x32_bf16 v[4:7], v[198:201], v[190:193], v[4:7]
	v_mfma_f32_16x16x32_bf16 v[0:3], v[206:209], v[190:193], v[0:3]
	s_setprio 0
	v_add_u32_e32 v140, s15, v238
	s_barrier
	ds_read_b128 v[76:79], v140
	ds_read_b128 v[84:87], v140 offset:1024
	ds_read_b128 v[88:91], v140 offset:2048
	ds_read_b128 v[140:143], v140 offset:3072
	s_mov_b32 m0, s42
	v_lshl_add_u64 v[194:195], s[92:93], 0, v[160:161]
	ds_read_b128 v[144:147], v240 offset:32768
	ds_read_b128 v[148:151], v240 offset:33792
	ds_read_b128 v[170:173], v240 offset:34816
	ds_read_b128 v[174:177], v240 offset:35840
	ds_read_b128 v[178:181], v240 offset:36864
	ds_read_b128 v[182:185], v240 offset:37888
	ds_read_b128 v[186:189], v240 offset:38912
	ds_read_b128 v[190:193], v240 offset:39936
	global_load_lds_dwordx4 v[194:195], off
	v_lshl_add_u64 v[194:195], s[92:93], 0, v[154:155]
	s_mov_b32 m0, s43
	s_nop 0
	global_load_lds_dwordx4 v[194:195], off
	s_waitcnt lgkmcnt(8)
	s_barrier
	s_waitcnt lgkmcnt(0)
	s_setprio 1
	s_waitcnt lgkmcnt(0)
	v_mfma_f32_16x16x32_bf16 v[136:139], v[76:79], v[144:147], v[136:139]
	v_mfma_f32_16x16x32_bf16 v[132:135], v[88:91], v[144:147], v[132:135]
	v_mfma_f32_16x16x32_bf16 v[128:131], v[76:79], v[170:173], v[128:131]
	v_mfma_f32_16x16x32_bf16 v[124:127], v[88:91], v[170:173], v[124:127]
	v_mfma_f32_16x16x32_bf16 v[120:123], v[76:79], v[178:181], v[120:123]
	v_mfma_f32_16x16x32_bf16 v[116:119], v[88:91], v[178:181], v[116:119]
	v_mfma_f32_16x16x32_bf16 v[112:115], v[76:79], v[186:189], v[112:115]
	v_mfma_f32_16x16x32_bf16 v[108:111], v[88:91], v[186:189], v[108:111]
	v_mfma_f32_16x16x32_bf16 v[136:139], v[84:87], v[148:151], v[136:139]
	v_mfma_f32_16x16x32_bf16 v[132:135], v[140:143], v[148:151], v[132:135]
	v_mfma_f32_16x16x32_bf16 v[128:131], v[84:87], v[174:177], v[128:131]
	v_mfma_f32_16x16x32_bf16 v[124:127], v[140:143], v[174:177], v[124:127]
	v_mfma_f32_16x16x32_bf16 v[120:123], v[84:87], v[182:185], v[120:123]
	v_mfma_f32_16x16x32_bf16 v[116:119], v[140:143], v[182:185], v[116:119]
	v_mfma_f32_16x16x32_bf16 v[112:115], v[84:87], v[190:193], v[112:115]
	v_mfma_f32_16x16x32_bf16 v[108:111], v[140:143], v[190:193], v[108:111]
	s_setprio 0
	s_barrier
	s_mov_b32 m0, s14
	v_add_u32_e32 v164, s13, v238
	v_lshl_add_u64 v[158:159], v[158:159], 0, s[74:75]
	ds_read_b128 v[194:197], v164
	ds_read_b128 v[198:201], v164 offset:1024
	ds_read_b128 v[202:205], v164 offset:2048
	ds_read_b128 v[206:209], v164 offset:3072
	global_load_lds_dwordx4 v[158:159], off
	v_lshl_add_u64 v[158:159], v[210:211], 0, s[74:75]
	s_mov_b32 m0, s12
	s_nop 0
	global_load_lds_dwordx4 v[158:159], off
	s_barrier
	s_waitcnt lgkmcnt(0)
	s_setprio 1
	s_waitcnt lgkmcnt(0)
	v_mfma_f32_16x16x32_bf16 v[60:63], v[194:197], v[144:147], v[60:63]
	v_mfma_f32_16x16x32_bf16 v[56:59], v[202:205], v[144:147], v[56:59]
	v_mfma_f32_16x16x32_bf16 v[52:55], v[194:197], v[170:173], v[52:55]
	v_mfma_f32_16x16x32_bf16 v[48:51], v[202:205], v[170:173], v[48:51]
	v_mfma_f32_16x16x32_bf16 v[44:47], v[194:197], v[178:181], v[44:47]
	v_mfma_f32_16x16x32_bf16 v[40:43], v[202:205], v[178:181], v[40:43]
	v_mfma_f32_16x16x32_bf16 v[36:39], v[194:197], v[186:189], v[36:39]
	v_mfma_f32_16x16x32_bf16 v[32:35], v[202:205], v[186:189], v[32:35]
	v_mfma_f32_16x16x32_bf16 v[60:63], v[198:201], v[148:151], v[60:63]
	v_mfma_f32_16x16x32_bf16 v[56:59], v[206:209], v[148:151], v[56:59]
	v_mfma_f32_16x16x32_bf16 v[52:55], v[198:201], v[174:177], v[52:55]
	v_mfma_f32_16x16x32_bf16 v[48:51], v[206:209], v[174:177], v[48:51]
	v_mfma_f32_16x16x32_bf16 v[44:47], v[198:201], v[182:185], v[44:47]
	v_mfma_f32_16x16x32_bf16 v[40:43], v[206:209], v[182:185], v[40:43]
	v_mfma_f32_16x16x32_bf16 v[36:39], v[198:201], v[190:193], v[36:39]
	v_mfma_f32_16x16x32_bf16 v[32:35], v[206:209], v[190:193], v[32:35]
	s_setprio 0
	s_mov_b32 m0, s38
	v_lshl_add_u64 v[158:159], v[212:213], 0, s[74:75]
	s_barrier
	ds_read_b128 v[144:147], v240 offset:49152
	ds_read_b128 v[148:151], v240 offset:50176
	ds_read_b128 v[170:173], v240 offset:51200
	ds_read_b128 v[174:177], v240 offset:52224
	ds_read_b128 v[178:181], v240 offset:53248
	ds_read_b128 v[182:185], v240 offset:54272
	ds_read_b128 v[186:189], v240 offset:55296
	ds_read_b128 v[190:193], v240 offset:56320
	global_load_lds_dwordx4 v[158:159], off
	v_lshl_add_u64 v[158:159], v[214:215], 0, s[74:75]
	s_mov_b32 m0, s81
	s_nop 0
	global_load_lds_dwordx4 v[158:159], off
	s_barrier
	s_waitcnt lgkmcnt(0)
	s_setprio 1
	s_waitcnt lgkmcnt(0)
	v_mfma_f32_16x16x32_bf16 v[104:107], v[76:79], v[144:147], v[104:107]
	v_mfma_f32_16x16x32_bf16 v[100:103], v[88:91], v[144:147], v[100:103]
	v_mfma_f32_16x16x32_bf16 v[96:99], v[76:79], v[170:173], v[96:99]
	v_mfma_f32_16x16x32_bf16 v[92:95], v[88:91], v[170:173], v[92:95]
	v_mfma_f32_16x16x32_bf16 v[80:83], v[76:79], v[178:181], v[80:83]
	v_mfma_f32_16x16x32_bf16 v[72:75], v[88:91], v[178:181], v[72:75]
	v_mfma_f32_16x16x32_bf16 v[68:71], v[76:79], v[186:189], v[68:71]
	v_mfma_f32_16x16x32_bf16 v[64:67], v[88:91], v[186:189], v[64:67]
	v_mfma_f32_16x16x32_bf16 v[104:107], v[84:87], v[148:151], v[104:107]
	v_mfma_f32_16x16x32_bf16 v[100:103], v[140:143], v[148:151], v[100:103]
	v_mfma_f32_16x16x32_bf16 v[96:99], v[84:87], v[174:177], v[96:99]
	v_mfma_f32_16x16x32_bf16 v[92:95], v[140:143], v[174:177], v[92:95]
	v_mfma_f32_16x16x32_bf16 v[80:83], v[84:87], v[182:185], v[80:83]
	v_mfma_f32_16x16x32_bf16 v[72:75], v[140:143], v[182:185], v[72:75]
	v_mfma_f32_16x16x32_bf16 v[68:71], v[84:87], v[190:193], v[68:71]
	v_mfma_f32_16x16x32_bf16 v[64:67], v[140:143], v[190:193], v[64:67]
	s_setprio 0
	s_barrier
	s_mov_b32 m0, s19
	v_lshl_add_u64 v[76:77], s[62:63], 0, v[152:153]
	global_load_lds_dwordx4 v[76:77], off
	v_lshl_add_u64 v[76:77], s[62:63], 0, v[156:157]
	s_mov_b32 m0, s18
	s_nop 0
	global_load_lds_dwordx4 v[76:77], off
	s_waitcnt vmcnt(6)
	s_barrier
	s_setprio 1
	v_mfma_f32_16x16x32_bf16 v[28:31], v[194:197], v[144:147], v[28:31]
	v_mfma_f32_16x16x32_bf16 v[24:27], v[202:205], v[144:147], v[24:27]
	v_mfma_f32_16x16x32_bf16 v[20:23], v[194:197], v[170:173], v[20:23]
	v_mfma_f32_16x16x32_bf16 v[16:19], v[202:205], v[170:173], v[16:19]
	v_mfma_f32_16x16x32_bf16 v[12:15], v[194:197], v[178:181], v[12:15]
	v_mfma_f32_16x16x32_bf16 v[8:11], v[202:205], v[178:181], v[8:11]
	v_mfma_f32_16x16x32_bf16 v[4:7], v[194:197], v[186:189], v[4:7]
	v_mfma_f32_16x16x32_bf16 v[0:3], v[202:205], v[186:189], v[0:3]
	v_mfma_f32_16x16x32_bf16 v[28:31], v[198:201], v[148:151], v[28:31]
	v_mfma_f32_16x16x32_bf16 v[24:27], v[206:209], v[148:151], v[24:27]
	v_mfma_f32_16x16x32_bf16 v[20:23], v[198:201], v[174:177], v[20:23]
	v_mfma_f32_16x16x32_bf16 v[16:19], v[206:209], v[174:177], v[16:19]
	v_mfma_f32_16x16x32_bf16 v[12:15], v[198:201], v[182:185], v[12:15]
	v_mfma_f32_16x16x32_bf16 v[8:11], v[206:209], v[182:185], v[8:11]
	v_mfma_f32_16x16x32_bf16 v[4:7], v[198:201], v[190:193], v[4:7]
	v_mfma_f32_16x16x32_bf16 v[0:3], v[206:209], v[190:193], v[0:3]
	s_setprio 0
	s_andn2_b64 vcc, exec, s[0:1]
	s_mov_b64 s[62:63], -1
	s_mov_b64 s[0:1], 0
	s_mov_b64 s[92:93], 0x100
	s_barrier
	s_cbranch_vccz .LBB0_453
	s_lshl_b32 s0, s97, 8
	s_bfe_u32 s7, s4, 0x10001
	s_add_i32 s1, s0, 0xffff8000
	s_cmpk_gt_i32 s97, 0x7f
	s_cselect_b32 s8, s1, s0
	s_lshl_b32 s0, s4, 6
	s_lshl_b32 s1, s4, 7
	s_and_b32 s0, s0, 0xffffff00
	s_and_b32 s1, s1, 0x80
	v_readlane_b32 s12, v251, 50
	s_or_b32 s5, s1, s0
	s_lshl_b32 s9, s7, 12
	v_readlane_b32 s24, v251, 62
	v_readlane_b32 s13, v251, 51
	v_readlane_b32 s14, v251, 52
	v_readlane_b32 s15, v251, 53
	v_readlane_b32 s16, v251, 54
	v_readlane_b32 s17, v251, 55
	v_readlane_b32 s18, v251, 56
	v_readlane_b32 s19, v251, 57
	v_readlane_b32 s20, v251, 58
	v_readlane_b32 s21, v251, 59
	v_readlane_b32 s22, v251, 60
	v_readlane_b32 s23, v251, 61
	v_readlane_b32 s25, v251, 63
	v_readlane_b32 s26, v252, 0
	v_readlane_b32 s27, v252, 1
	s_add_u32 s0, s24, s9
	v_or_b32_e32 v180, s5, v239
	s_addc_u32 s1, s25, 0
	v_readlane_b32 s12, v250, 62
	v_ashrrev_i32_e32 v181, 31, v180
	v_readlane_b32 s13, v250, 63
	s_add_u32 s4, s12, s9
	v_lshlrev_b64 v[84:85], 2, v[180:181]
	v_lshl_add_u64 v[172:173], s[0:1], 0, v[84:85]
	s_addc_u32 s5, s13, 0
	global_load_dwordx4 v[88:91], v[172:173], off
	v_lshl_add_u64 v[158:159], s[4:5], 0, v[84:85]
	global_load_dwordx4 v[76:79], v[158:159], off
	v_readlane_b32 s0, v251, 28
	v_readlane_b32 s1, v251, 29
	s_add_u32 s0, s0, s9
	s_addc_u32 s1, s1, 0
	v_lshl_add_u64 v[174:175], s[0:1], 0, v[84:85]
	global_load_dwordx4 v[84:87], v[174:175], off
	v_add_u32_e32 v182, s8, v162
	v_ashrrev_i32_e32 v183, 31, v182
	v_or_b32_e32 v184, 16, v182
	v_readlane_b32 s14, v251, 0
	v_lshlrev_b64 v[178:179], 11, v[182:183]
	v_ashrrev_i32_e32 v185, 31, v184
	v_lshlrev_b64 v[186:187], 10, v[182:183]
	v_readlane_b32 s62, v255, 4
	v_lshlrev_b64 v[176:177], 11, v[184:185]
	s_cmpk_lt_i32 s97, 0x80
	v_readlane_b32 s36, v249, 22
	s_mov_b32 s90, s62
	v_readlane_b32 s93, v250, 12
	v_readlane_b32 s92, v255, 6
	s_mov_b32 s14, 0x3e2aaaab
	v_readlane_b32 s15, v251, 1
	v_readlane_b32 s16, v251, 2
	v_readlane_b32 s17, v251, 3
	v_readlane_b32 s18, v251, 4
	v_readlane_b32 s19, v251, 5
	v_readlane_b32 s20, v251, 6
	v_readlane_b32 s21, v251, 7
	v_readlane_b32 s22, v251, 8
	v_readlane_b32 s23, v251, 9
	v_readlane_b32 s24, v251, 10
	v_readlane_b32 s25, v251, 11
	v_readlane_b32 s26, v251, 12
	v_readlane_b32 s27, v251, 13
	v_readlane_b32 s37, v249, 23
	v_readlane_b32 s63, v255, 5
	s_waitcnt vmcnt(0)
	v_add_f32_e32 v136, v136, v88
	v_mul_f32_e32 v136, 0xbfb8aa3b, v136
	v_add_f32_e32 v132, v132, v76
	v_exp_f32_e32 v136, v136
	v_mul_f32_e32 v132, 0xbfb8aa3b, v132
	v_exp_f32_e32 v132, v132
	v_add_f32_e32 v136, 1.0, v136
	v_add_f32_e32 v132, 1.0, v132
	s_mov_b64 vcc, s[0:1]
	v_rcp_f32_e32 v140, v136
	v_rcp_f32_e32 v136, v132
	v_mul_f32_e32 v132, 0xc1000000, v140
	v_mul_f32_e32 v132, v84, v132
	v_add_f32_e32 v183, v132, v132
	v_cmp_nlt_f32_e64 s[4:5], s51, v183
	s_mov_b64 s[0:1], -1
	s_cbranch_scc0 .LBB0_712
	v_lshl_add_u64 v[140:141], v[180:181], 1, s[28:29]
	v_lshl_add_u64 v[142:143], v[140:141], 0, v[178:179]
	v_lshl_add_u64 v[146:147], v[140:141], 0, v[176:177]
	global_load_dwordx2 v[144:145], v[142:143], off
	s_nop 0
	global_load_dwordx2 v[142:143], v[146:147], off
	s_and_saveexec_b64 s[0:1], s[4:5]
	s_xor_b64 s[0:1], exec, s[0:1]
	v_mul_f32_e32 v146, 0x3fb8aa3b, v183
	v_exp_f32_e32 v146, v146
	s_nop 0
	v_sub_f32_e32 v147, 1.0, v146
	s_andn2_saveexec_b64 s[0:1], s[0:1]
	v_fma_f32 v146, v183, s14, 0.5
	v_fma_f32 v146, v183, v146, 1.0
	v_mul_f32_e64 v147, v146, -v183
	s_or_b64 exec, exec, s[0:1]
	v_add_f32_e32 v146, v137, v89
	v_mul_f32_e32 v146, 0xbfb8aa3b, v146
	v_exp_f32_e32 v146, v146
	s_nop 0
	v_add_f32_e32 v146, 1.0, v146
	v_rcp_f32_e32 v146, v146
	s_nop 0
	v_mul_f32_e32 v146, 0xc1000000, v146
	v_mul_f32_e32 v146, v85, v146
	v_add_f32_e32 v148, v146, v146
	v_mul_f32_e32 v247, 0x3fb8aa3b, v148
	v_exp_f32_e32 v247, v247
	v_fma_f32 v149, v148, s14, 0.5
	v_fma_f32 v149, v148, v149, 1.0
	v_cmp_nlt_f32_e32 vcc, s51, v148
	v_mul_f32_e64 v149, v149, -v148
	v_sub_f32_e32 v247, 1.0, v247
	v_cndmask_b32_e32 v149, v149, v247, vcc
	v_add_f32_e32 v148, v138, v90
	v_mul_f32_e32 v148, 0xbfb8aa3b, v148
	v_exp_f32_e32 v148, v148
	s_nop 0
	v_add_f32_e32 v148, 1.0, v148
	v_rcp_f32_e32 v148, v148
	s_nop 0
	v_mul_f32_e32 v148, 0xc1000000, v148
	v_mul_f32_e32 v148, v86, v148
	v_add_f32_e32 v150, v148, v148
	v_mul_f32_e32 v247, 0x3fb8aa3b, v150
	v_exp_f32_e32 v247, v247
	v_fma_f32 v168, v150, s14, 0.5
	v_fma_f32 v168, v150, v168, 1.0
	v_cmp_nlt_f32_e32 vcc, s51, v150
	v_mul_f32_e64 v168, v168, -v150
	v_sub_f32_e32 v247, 1.0, v247
	v_cndmask_b32_e32 v168, v168, v247, vcc
	v_add_f32_e32 v150, v139, v91
	v_mul_f32_e32 v150, 0xbfb8aa3b, v150
	v_exp_f32_e32 v150, v150
	s_nop 0
	v_add_f32_e32 v150, 1.0, v150
	v_rcp_f32_e32 v150, v150
	s_nop 0
	v_mul_f32_e32 v150, 0xc1000000, v150
	v_mul_f32_e32 v150, v87, v150
	v_add_f32_e32 v170, v150, v150
	v_mul_f32_e32 v247, 0x3fb8aa3b, v170
	v_exp_f32_e32 v247, v247
	v_fma_f32 v151, v170, s14, 0.5
	v_fma_f32 v151, v170, v151, 1.0
	v_cmp_nlt_f32_e32 vcc, s51, v170
	v_mul_f32_e64 v151, v151, -v170
	v_sub_f32_e32 v247, 1.0, v247
	v_cndmask_b32_e32 v151, v151, v247, vcc
	v_add_f32_e32 v164, v134, v78
	v_mul_f32_e32 v164, 0xbfb8aa3b, v164
	v_exp_f32_e32 v164, v164
	v_max_f32_e32 v149, 0, v149
	v_add_f32_e32 v164, 1.0, v164
	v_max_f32_e32 v147, 0, v147
	v_readlane_b32 s8, v253, 8
	v_readlane_b32 s9, v253, 9
	v_max_f32_e32 v166, 0, v168
	v_rcp_f32_e32 v164, v164
	s_waitcnt vmcnt(0)
	v_lshlrev_b32_e32 v165, 16, v145
	v_sqrt_f32_e32 v166, v166
	v_cvt_pk_bf16_f32 v146, v132, v146
	v_mul_f32_e32 v164, v164, v166
	v_mul_f32_e32 v164, v164, v165
	v_add_f32_e32 v165, v135, v79
	v_mul_f32_e32 v165, 0xbfb8aa3b, v165
	v_exp_f32_e32 v165, v165
	s_nop 0
	v_add_f32_e32 v165, 1.0, v165
	v_rcp_f32_e32 v165, v165
	v_add_f32_e32 v166, v133, v77
	v_mul_f32_e32 v166, 0xbfb8aa3b, v166
	v_exp_f32_e32 v166, v166
	s_nop 0
	v_add_f32_e32 v166, 1.0, v166
	s_lshl_b32 s0, s7, 26
	s_add_u32 s58, s8, s0
	s_addc_u32 s59, s9, 0
	v_rcp_f32_e32 v166, v166
	v_and_b32_e32 v167, 0xffff0000, v144
	v_sqrt_f32_e32 v149, v149
	v_lshlrev_b32_e32 v144, 16, v144
	v_mul_f32_e32 v149, v166, v149
	v_sqrt_f32_e32 v147, v147
	s_add_u32 s0, s68, s0
	s_addc_u32 s1, s69, 0
	v_mul_f32_e32 v147, v136, v147
	v_mul_f32_e32 v166, v147, v144
	v_and_b32_e32 v144, 0xffff0000, v145
	v_max_f32_e32 v145, 0, v151
	v_mul_f32_e32 v149, v149, v167
	v_sqrt_f32_e32 v145, v145
	s_nop 0
	v_mul_f32_e32 v145, v165, v145
	v_mul_f32_e32 v151, v145, v144
	v_lshl_add_u64 v[144:145], v[186:187], 0, v[180:181]
	v_lshlrev_b64 v[144:145], 1, v[144:145]
	v_lshl_add_u64 v[190:191], s[58:59], 0, v[144:145]
	v_lshl_add_u64 v[194:195], s[0:1], 0, v[144:145]
	v_add_f32_e32 v144, v128, v88
	v_mul_f32_e32 v144, 0xbfb8aa3b, v144
	v_exp_f32_e32 v144, v144
	v_cvt_pk_bf16_f32 v147, v148, v150
	global_store_dwordx2 v[190:191], v[146:147], off
	v_cvt_pk_bf16_f32 v146, v166, v149
	v_add_f32_e32 v144, 1.0, v144
	v_cvt_pk_bf16_f32 v147, v164, v151
	global_store_dwordx2 v[194:195], v[146:147], off
	v_rcp_f32_e32 v144, v144
	s_nop 0
	v_mul_f32_e32 v144, 0xc1000000, v144
	v_mul_f32_e32 v144, v84, v144
	v_add_f32_e32 v145, v144, v144
	v_mul_f32_e32 v247, 0x3fb8aa3b, v145
	v_exp_f32_e32 v247, v247
	v_fma_f32 v146, v145, s14, 0.5
	v_fma_f32 v146, v145, v146, 1.0
	v_cmp_nlt_f32_e32 vcc, s51, v145
	v_mul_f32_e64 v146, v146, -v145
	v_sub_f32_e32 v247, 1.0, v247
	v_cndmask_b32_e32 v146, v146, v247, vcc
	v_add_f32_e32 v145, v129, v89
	v_mul_f32_e32 v145, 0xbfb8aa3b, v145
	v_exp_f32_e32 v145, v145
	s_nop 0
	v_add_f32_e32 v145, 1.0, v145
	v_rcp_f32_e32 v145, v145
	s_nop 0
	v_mul_f32_e32 v145, 0xc1000000, v145
	v_mul_f32_e32 v145, v85, v145
	v_add_f32_e32 v147, v145, v145
	v_mul_f32_e32 v247, 0x3fb8aa3b, v147
	v_exp_f32_e32 v247, v247
	v_fma_f32 v150, v147, s14, 0.5
	v_fma_f32 v150, v147, v150, 1.0
	v_cmp_nlt_f32_e32 vcc, s51, v147
	v_mul_f32_e64 v150, v150, -v147
	v_sub_f32_e32 v247, 1.0, v247
	v_cndmask_b32_e32 v150, v150, v247, vcc
	v_add_f32_e32 v147, v130, v90
	v_mul_f32_e32 v147, 0xbfb8aa3b, v147
	v_exp_f32_e32 v147, v147
	s_nop 0
	v_add_f32_e32 v147, 1.0, v147
	v_rcp_f32_e32 v147, v147
	s_nop 0
	v_mul_f32_e32 v147, 0xc1000000, v147
	v_mul_f32_e32 v147, v86, v147
	v_add_f32_e32 v148, v147, v147
	v_mul_f32_e32 v247, 0x3fb8aa3b, v148
	v_exp_f32_e32 v247, v247
	v_fma_f32 v151, v148, s14, 0.5
	v_fma_f32 v151, v148, v151, 1.0
	v_cmp_nlt_f32_e32 vcc, s51, v148
	v_mul_f32_e64 v151, v151, -v148
	v_sub_f32_e32 v247, 1.0, v247
	v_cndmask_b32_e32 v151, v151, v247, vcc
	v_add_f32_e32 v148, v131, v91
	v_mul_f32_e32 v148, 0xbfb8aa3b, v148
	v_exp_f32_e32 v148, v148
	s_nop 0
	v_add_f32_e32 v148, 1.0, v148
	v_rcp_f32_e32 v148, v148
	s_nop 0
	v_mul_f32_e32 v148, 0xc1000000, v148
	v_mul_f32_e32 v148, v87, v148
	v_add_f32_e32 v168, v148, v148
	v_mul_f32_e32 v247, 0x3fb8aa3b, v168
	v_exp_f32_e32 v247, v247
	v_fma_f32 v149, v168, s14, 0.5
	v_fma_f32 v149, v168, v149, 1.0
	v_cmp_nlt_f32_e32 vcc, s51, v168
	v_mul_f32_e64 v149, v149, -v168
	v_sub_f32_e32 v247, 1.0, v247
	v_cndmask_b32_e32 v149, v149, v247, vcc
	v_add_f32_e32 v164, v126, v78
	v_mul_f32_e32 v164, 0xbfb8aa3b, v164
	v_exp_f32_e32 v164, v164
	v_max_f32_e32 v151, 0, v151
	v_add_f32_e32 v164, 1.0, v164
	v_max_f32_e32 v150, 0, v150
	v_max_f32_e32 v146, 0, v146
	v_rcp_f32_e32 v164, v164
	v_lshlrev_b32_e32 v165, 16, v143
	v_sqrt_f32_e32 v151, v151
	v_cvt_pk_bf16_f32 v144, v144, v145
	v_cvt_pk_bf16_f32 v145, v147, v148
	v_mul_f32_e32 v151, v164, v151
	v_mul_f32_e32 v164, v151, v165
	v_add_f32_e32 v151, v127, v79
	v_mul_f32_e32 v151, 0xbfb8aa3b, v151
	v_exp_f32_e32 v151, v151
	s_nop 0
	v_add_f32_e32 v151, 1.0, v151
	v_rcp_f32_e32 v165, v151
	v_add_f32_e32 v151, v125, v77
	v_mul_f32_e32 v151, 0xbfb8aa3b, v151
	v_exp_f32_e32 v151, v151
	s_nop 0
	v_add_f32_e32 v151, 1.0, v151
	v_rcp_f32_e32 v151, v151
	v_and_b32_e32 v166, 0xffff0000, v142
	v_sqrt_f32_e32 v150, v150
	v_lshlrev_b32_e32 v142, 16, v142
	v_mul_f32_e32 v150, v151, v150
	v_mul_f32_e32 v166, v150, v166
	v_add_f32_e32 v150, v124, v76
	v_mul_f32_e32 v150, 0xbfb8aa3b, v150
	v_exp_f32_e32 v150, v150
	s_nop 0
	v_add_f32_e32 v150, 1.0, v150
	v_rcp_f32_e32 v150, v150
	v_sqrt_f32_e32 v146, v146
	s_nop 0
	v_mul_f32_e32 v146, v150, v146
	v_mul_f32_e32 v146, v146, v142
	v_and_b32_e32 v142, 0xffff0000, v143
	v_max_f32_e32 v143, 0, v149
	v_lshlrev_b64 v[150:151], 10, v[184:185]
	v_sqrt_f32_e32 v143, v143
	s_nop 0
	v_mul_f32_e32 v143, v165, v143
	v_mul_f32_e32 v149, v143, v142
	v_lshl_add_u64 v[142:143], v[150:151], 0, v[180:181]
	v_lshlrev_b64 v[142:143], 1, v[142:143]
	v_lshl_add_u64 v[188:189], s[58:59], 0, v[142:143]
	global_store_dwordx2 v[188:189], v[144:145], off
	v_cvt_pk_bf16_f32 v144, v146, v166
	v_or_b32_e32 v146, 32, v182
	v_ashrrev_i32_e32 v147, 31, v146
	v_lshl_add_u64 v[192:193], s[0:1], 0, v[142:143]
	v_lshlrev_b64 v[196:197], 11, v[146:147]
	v_cvt_pk_bf16_f32 v145, v164, v149
	global_store_dwordx2 v[192:193], v[144:145], off
	v_lshl_add_u64 v[142:143], v[140:141], 0, v[196:197]
	global_load_dwordx2 v[148:149], v[142:143], off
	v_or_b32_e32 v142, 48, v182
	v_ashrrev_i32_e32 v143, 31, v142
	v_lshlrev_b64 v[198:199], 11, v[142:143]
	v_lshl_add_u64 v[144:145], v[140:141], 0, v[198:199]
	global_load_dwordx2 v[144:145], v[144:145], off
	v_add_f32_e32 v150, v120, v88
	v_mul_f32_e32 v150, 0xbfb8aa3b, v150
	v_exp_f32_e32 v150, v150
	s_nop 0
	v_add_f32_e32 v150, 1.0, v150
	v_rcp_f32_e32 v150, v150
	s_nop 0
	v_mul_f32_e32 v150, 0xc1000000, v150
	v_mul_f32_e32 v150, v84, v150
	v_add_f32_e32 v151, v150, v150
	v_mul_f32_e32 v247, 0x3fb8aa3b, v151
	v_exp_f32_e32 v247, v247
	v_fma_f32 v168, v151, s14, 0.5
	v_fma_f32 v168, v151, v168, 1.0
	v_cmp_nlt_f32_e32 vcc, s51, v151
	v_mul_f32_e64 v168, v168, -v151
	v_sub_f32_e32 v247, 1.0, v247
	v_cndmask_b32_e32 v168, v168, v247, vcc
	v_add_f32_e32 v151, v121, v89
	v_mul_f32_e32 v151, 0xbfb8aa3b, v151
	v_exp_f32_e32 v151, v151
	s_nop 0
	v_add_f32_e32 v151, 1.0, v151
	v_rcp_f32_e32 v151, v151
	s_nop 0
	v_mul_f32_e32 v151, 0xc1000000, v151
	v_mul_f32_e32 v151, v85, v151
	v_add_f32_e32 v170, v151, v151
	v_mul_f32_e32 v247, 0x3fb8aa3b, v170
	v_exp_f32_e32 v247, v247
	v_fma_f32 v201, v170, s14, 0.5
	v_fma_f32 v201, v170, v201, 1.0
	v_cmp_nlt_f32_e32 vcc, s51, v170
	v_mul_f32_e64 v201, v201, -v170
	v_sub_f32_e32 v247, 1.0, v247
	v_cndmask_b32_e32 v201, v201, v247, vcc
	v_add_f32_e32 v164, v122, v90
	v_mul_f32_e32 v164, 0xbfb8aa3b, v164
	v_exp_f32_e32 v164, v164
	s_nop 0
	v_add_f32_e32 v164, 1.0, v164
	v_rcp_f32_e32 v164, v164
	s_nop 0
	v_mul_f32_e32 v164, 0xc1000000, v164
	v_mul_f32_e32 v170, v86, v164
	v_add_f32_e32 v171, v170, v170
	v_mul_f32_e32 v247, 0x3fb8aa3b, v171
	v_exp_f32_e32 v247, v247
	v_fma_f32 v202, v171, s14, 0.5
	v_fma_f32 v202, v171, v202, 1.0
	v_cmp_nlt_f32_e32 vcc, s51, v171
	v_mul_f32_e64 v202, v202, -v171
	v_sub_f32_e32 v247, 1.0, v247
	v_cndmask_b32_e32 v202, v202, v247, vcc
	v_add_f32_e32 v164, v123, v91
	v_mul_f32_e32 v164, 0xbfb8aa3b, v164
	v_exp_f32_e32 v164, v164
	s_nop 0
	v_add_f32_e32 v164, 1.0, v164
	v_rcp_f32_e32 v164, v164
	s_nop 0
	v_mul_f32_e32 v164, 0xc1000000, v164
	v_mul_f32_e32 v171, v87, v164
	v_add_f32_e32 v203, v171, v171
	v_mul_f32_e32 v247, 0x3fb8aa3b, v203
	v_exp_f32_e32 v247, v247
	v_fma_f32 v200, v203, s14, 0.5
	v_fma_f32 v200, v203, v200, 1.0
	v_cmp_nlt_f32_e32 vcc, s51, v203
	v_mul_f32_e64 v200, v200, -v203
	v_sub_f32_e32 v247, 1.0, v247
	v_cndmask_b32_e32 v200, v200, v247, vcc
	v_add_f32_e32 v164, v118, v78
	v_mul_f32_e32 v164, 0xbfb8aa3b, v164
	v_exp_f32_e32 v164, v164
	v_max_f32_e32 v201, 0, v201
	v_add_f32_e32 v164, 1.0, v164
	v_max_f32_e32 v168, 0, v168
	v_lshlrev_b64 v[146:147], 10, v[146:147]
	v_lshl_add_u64 v[146:147], v[146:147], 0, v[180:181]
	v_max_f32_e32 v166, 0, v202
	v_rcp_f32_e32 v164, v164
	s_waitcnt vmcnt(0)
	v_lshlrev_b32_e32 v165, 16, v149
	v_sqrt_f32_e32 v166, v166
	v_lshlrev_b64 v[146:147], 1, v[146:147]
	v_lshl_add_u64 v[206:207], s[0:1], 0, v[146:147]
	v_mul_f32_e32 v164, v164, v166
	v_mul_f32_e32 v164, v164, v165
	v_add_f32_e32 v165, v119, v79
	v_mul_f32_e32 v165, 0xbfb8aa3b, v165
	v_exp_f32_e32 v165, v165
	s_nop 0
	v_add_f32_e32 v165, 1.0, v165
	v_rcp_f32_e32 v165, v165
	v_add_f32_e32 v166, v117, v77
	v_mul_f32_e32 v166, 0xbfb8aa3b, v166
	v_exp_f32_e32 v166, v166
	s_nop 0
	v_add_f32_e32 v166, 1.0, v166
	v_rcp_f32_e32 v166, v166
	v_and_b32_e32 v167, 0xffff0000, v148
	v_sqrt_f32_e32 v201, v201
	v_lshlrev_b32_e32 v148, 16, v148
	v_mul_f32_e32 v166, v166, v201
	v_mul_f32_e32 v166, v166, v167
	v_add_f32_e32 v167, v116, v76
	v_mul_f32_e32 v167, 0xbfb8aa3b, v167
	v_exp_f32_e32 v167, v167
	s_nop 0
	v_add_f32_e32 v167, 1.0, v167
	v_rcp_f32_e32 v167, v167
	v_lshl_add_u64 v[202:203], s[58:59], 0, v[146:147]
	v_sqrt_f32_e32 v168, v168
	v_add_f32_e32 v146, v112, v88
	v_mul_f32_e32 v146, 0xbfb8aa3b, v146
	v_mul_f32_e32 v167, v167, v168
	v_mul_f32_e32 v167, v167, v148
	v_and_b32_e32 v148, 0xffff0000, v149
	v_max_f32_e32 v149, 0, v200
	v_exp_f32_e32 v146, v146
	v_sqrt_f32_e32 v149, v149
	v_add_f32_e32 v146, 1.0, v146
	v_mul_f32_e32 v149, v165, v149
	v_mul_f32_e32 v165, v149, v148
	v_cvt_pk_bf16_f32 v148, v150, v151
	v_cvt_pk_bf16_f32 v149, v170, v171
	global_store_dwordx2 v[202:203], v[148:149], off
	v_cvt_pk_bf16_f32 v148, v167, v166
	v_cvt_pk_bf16_f32 v149, v164, v165
	global_store_dwordx2 v[206:207], v[148:149], off
	v_rcp_f32_e32 v146, v146
	s_nop 0
	v_mul_f32_e32 v146, 0xc1000000, v146
	v_mul_f32_e32 v146, v84, v146
	v_add_f32_e32 v147, v146, v146
	v_mul_f32_e32 v247, 0x3fb8aa3b, v147
	v_exp_f32_e32 v247, v247
	v_fma_f32 v148, v147, s14, 0.5
	v_fma_f32 v148, v147, v148, 1.0
	v_cmp_nlt_f32_e32 vcc, s51, v147
	v_mul_f32_e64 v148, v148, -v147
	v_sub_f32_e32 v247, 1.0, v247
	v_cndmask_b32_e32 v148, v148, v247, vcc
	v_add_f32_e32 v147, v113, v89
	v_mul_f32_e32 v147, 0xbfb8aa3b, v147
	v_exp_f32_e32 v147, v147
	s_nop 0
	v_add_f32_e32 v147, 1.0, v147
	v_rcp_f32_e32 v147, v147
	s_nop 0
	v_mul_f32_e32 v147, 0xc1000000, v147
	v_mul_f32_e32 v147, v85, v147
	v_add_f32_e32 v149, v147, v147
	v_mul_f32_e32 v247, 0x3fb8aa3b, v149
	v_exp_f32_e32 v247, v247
	v_fma_f32 v168, v149, s14, 0.5
	v_fma_f32 v168, v149, v168, 1.0
	v_cmp_nlt_f32_e32 vcc, s51, v149
	v_mul_f32_e64 v168, v168, -v149
	v_sub_f32_e32 v247, 1.0, v247
	v_cndmask_b32_e32 v168, v168, v247, vcc
	v_add_f32_e32 v149, v114, v90
	v_mul_f32_e32 v149, 0xbfb8aa3b, v149
	v_exp_f32_e32 v149, v149
	s_nop 0
	v_add_f32_e32 v149, 1.0, v149
	v_rcp_f32_e32 v149, v149
	s_nop 0
	v_mul_f32_e32 v149, 0xc1000000, v149
	v_mul_f32_e32 v149, v86, v149
	v_add_f32_e32 v150, v149, v149
	v_mul_f32_e32 v247, 0x3fb8aa3b, v150
	v_exp_f32_e32 v247, v247
	v_fma_f32 v170, v150, s14, 0.5
	v_fma_f32 v170, v150, v170, 1.0
	v_cmp_nlt_f32_e32 vcc, s51, v150
	v_mul_f32_e64 v170, v170, -v150
	v_sub_f32_e32 v247, 1.0, v247
	v_cndmask_b32_e32 v170, v170, v247, vcc
	v_add_f32_e32 v150, v115, v91
	v_mul_f32_e32 v150, 0xbfb8aa3b, v150
	v_exp_f32_e32 v150, v150
	s_nop 0
	v_add_f32_e32 v150, 1.0, v150
	v_rcp_f32_e32 v150, v150
	s_nop 0
	v_mul_f32_e32 v150, 0xc1000000, v150
	v_mul_f32_e32 v150, v87, v150
	v_add_f32_e32 v171, v150, v150
	v_mul_f32_e32 v247, 0x3fb8aa3b, v171
	v_exp_f32_e32 v247, v247
	v_fma_f32 v151, v171, s14, 0.5
	v_fma_f32 v151, v171, v151, 1.0
	v_cmp_nlt_f32_e32 vcc, s51, v171
	v_mul_f32_e64 v151, v151, -v171
	v_sub_f32_e32 v247, 1.0, v247
	v_cndmask_b32_e32 v151, v151, v247, vcc
	v_add_f32_e32 v164, v110, v78
	v_mul_f32_e32 v164, 0xbfb8aa3b, v164
	v_exp_f32_e32 v164, v164
	v_max_f32_e32 v168, 0, v168
	v_add_f32_e32 v164, 1.0, v164
	v_max_f32_e32 v148, 0, v148
	v_lshlrev_b64 v[142:143], 10, v[142:143]
	v_lshl_add_u64 v[142:143], v[142:143], 0, v[180:181]
	v_max_f32_e32 v166, 0, v170
	v_rcp_f32_e32 v164, v164
	v_lshlrev_b32_e32 v165, 16, v145
	v_sqrt_f32_e32 v166, v166
	v_lshlrev_b64 v[142:143], 1, v[142:143]
	v_lshl_add_u64 v[204:205], s[0:1], 0, v[142:143]
	v_mul_f32_e32 v164, v164, v166
	v_mul_f32_e32 v164, v164, v165
	v_add_f32_e32 v165, v111, v79
	v_mul_f32_e32 v165, 0xbfb8aa3b, v165
	v_exp_f32_e32 v165, v165
	s_nop 0
	v_add_f32_e32 v165, 1.0, v165
	v_rcp_f32_e32 v165, v165
	v_add_f32_e32 v166, v109, v77
	v_mul_f32_e32 v166, 0xbfb8aa3b, v166
	v_exp_f32_e32 v166, v166
	s_nop 0
	v_add_f32_e32 v166, 1.0, v166
	v_rcp_f32_e32 v166, v166
	v_and_b32_e32 v167, 0xffff0000, v144
	v_sqrt_f32_e32 v168, v168
	v_lshlrev_b32_e32 v144, 16, v144
	v_mul_f32_e32 v166, v166, v168
	v_mul_f32_e32 v166, v166, v167
	v_add_f32_e32 v167, v108, v76
	v_mul_f32_e32 v167, 0xbfb8aa3b, v167
	v_exp_f32_e32 v167, v167
	s_nop 0
	v_add_f32_e32 v167, 1.0, v167
	v_rcp_f32_e32 v167, v167
	v_lshl_add_u64 v[200:201], s[58:59], 0, v[142:143]
	v_sqrt_f32_e32 v148, v148
	s_nop 0
	v_mul_f32_e32 v148, v167, v148
	v_mul_f32_e32 v148, v148, v144
	v_and_b32_e32 v144, 0xffff0000, v145
	v_max_f32_e32 v145, 0, v151
	v_sqrt_f32_e32 v145, v145
	s_nop 0
	v_mul_f32_e32 v145, v165, v145
	v_mul_f32_e32 v151, v145, v144
	v_cvt_pk_bf16_f32 v144, v146, v147
	v_add_u32_e32 v146, 0x80, v182
	v_ashrrev_i32_e32 v147, 31, v146
	v_cvt_pk_bf16_f32 v145, v149, v150
	v_lshlrev_b64 v[208:209], 11, v[146:147]
	global_store_dwordx2 v[200:201], v[144:145], off
	v_cvt_pk_bf16_f32 v144, v148, v166
	v_cvt_pk_bf16_f32 v145, v164, v151
	global_store_dwordx2 v[204:205], v[144:145], off
	v_lshl_add_u64 v[142:143], v[140:141], 0, v[208:209]
	global_load_dwordx2 v[148:149], v[142:143], off
	v_add_u32_e32 v142, 0x90, v182
	v_ashrrev_i32_e32 v143, 31, v142
	v_lshlrev_b64 v[210:211], 11, v[142:143]
	v_lshl_add_u64 v[144:145], v[140:141], 0, v[210:211]
	global_load_dwordx2 v[144:145], v[144:145], off
	v_add_f32_e32 v150, v104, v88
	v_mul_f32_e32 v150, 0xbfb8aa3b, v150
	v_exp_f32_e32 v150, v150
	s_nop 0
	v_add_f32_e32 v150, 1.0, v150
	v_rcp_f32_e32 v150, v150
	s_nop 0
	v_mul_f32_e32 v150, 0xc1000000, v150
	v_mul_f32_e32 v150, v84, v150
	v_add_f32_e32 v151, v150, v150
	v_mul_f32_e32 v247, 0x3fb8aa3b, v151
	v_exp_f32_e32 v247, v247
	v_fma_f32 v168, v151, s14, 0.5
	v_fma_f32 v168, v151, v168, 1.0
	v_cmp_nlt_f32_e32 vcc, s51, v151
	v_mul_f32_e64 v168, v168, -v151
	v_sub_f32_e32 v247, 1.0, v247
	v_cndmask_b32_e32 v168, v168, v247, vcc
	v_add_f32_e32 v151, v105, v89
	v_mul_f32_e32 v151, 0xbfb8aa3b, v151
	v_exp_f32_e32 v151, v151
	s_nop 0
	v_add_f32_e32 v151, 1.0, v151
	v_rcp_f32_e32 v151, v151
	s_nop 0
	v_mul_f32_e32 v151, 0xc1000000, v151
	v_mul_f32_e32 v151, v85, v151
	v_add_f32_e32 v170, v151, v151
	v_mul_f32_e32 v247, 0x3fb8aa3b, v170
	v_exp_f32_e32 v247, v247
	v_fma_f32 v213, v170, s14, 0.5
	v_fma_f32 v213, v170, v213, 1.0
	v_cmp_nlt_f32_e32 vcc, s51, v170
	v_mul_f32_e64 v213, v213, -v170
	v_sub_f32_e32 v247, 1.0, v247
	v_cndmask_b32_e32 v213, v213, v247, vcc
	v_add_f32_e32 v164, v106, v90
	v_mul_f32_e32 v164, 0xbfb8aa3b, v164
	v_exp_f32_e32 v164, v164
	s_nop 0
	v_add_f32_e32 v164, 1.0, v164
	v_rcp_f32_e32 v164, v164
	s_nop 0
	v_mul_f32_e32 v164, 0xc1000000, v164
	v_mul_f32_e32 v170, v86, v164
	v_add_f32_e32 v171, v170, v170
	v_mul_f32_e32 v247, 0x3fb8aa3b, v171
	v_exp_f32_e32 v247, v247
	v_fma_f32 v214, v171, s14, 0.5
	v_fma_f32 v214, v171, v214, 1.0
	v_cmp_nlt_f32_e32 vcc, s51, v171
	v_mul_f32_e64 v214, v214, -v171
	v_sub_f32_e32 v247, 1.0, v247
	v_cndmask_b32_e32 v214, v214, v247, vcc
	v_add_f32_e32 v164, v107, v91
	v_mul_f32_e32 v164, 0xbfb8aa3b, v164
	v_exp_f32_e32 v164, v164
	s_nop 0
	v_add_f32_e32 v164, 1.0, v164
	v_rcp_f32_e32 v164, v164
	s_nop 0
	v_mul_f32_e32 v164, 0xc1000000, v164
	v_mul_f32_e32 v171, v87, v164
	v_add_f32_e32 v215, v171, v171
	v_mul_f32_e32 v247, 0x3fb8aa3b, v215
	v_exp_f32_e32 v247, v247
	v_fma_f32 v212, v215, s14, 0.5
	v_fma_f32 v212, v215, v212, 1.0
	v_cmp_nlt_f32_e32 vcc, s51, v215
	v_mul_f32_e64 v212, v212, -v215
	v_sub_f32_e32 v247, 1.0, v247
	v_cndmask_b32_e32 v212, v212, v247, vcc
	v_add_f32_e32 v164, v102, v78
	v_mul_f32_e32 v164, 0xbfb8aa3b, v164
	v_exp_f32_e32 v164, v164
	v_max_f32_e32 v213, 0, v213
	v_add_f32_e32 v164, 1.0, v164
	v_max_f32_e32 v168, 0, v168
	v_lshlrev_b64 v[146:147], 10, v[146:147]
	v_lshl_add_u64 v[146:147], v[146:147], 0, v[180:181]
	v_max_f32_e32 v166, 0, v214
	v_rcp_f32_e32 v164, v164
	s_waitcnt vmcnt(0)
	v_lshlrev_b32_e32 v165, 16, v149
	v_sqrt_f32_e32 v166, v166
	v_lshlrev_b64 v[146:147], 1, v[146:147]
	v_lshl_add_u64 v[218:219], s[0:1], 0, v[146:147]
	v_mul_f32_e32 v164, v164, v166
	v_mul_f32_e32 v164, v164, v165
	v_add_f32_e32 v165, v103, v79
	v_mul_f32_e32 v165, 0xbfb8aa3b, v165
	v_exp_f32_e32 v165, v165
	s_nop 0
	v_add_f32_e32 v165, 1.0, v165
	v_rcp_f32_e32 v165, v165
	v_add_f32_e32 v166, v101, v77
	v_mul_f32_e32 v166, 0xbfb8aa3b, v166
	v_exp_f32_e32 v166, v166
	s_nop 0
	v_add_f32_e32 v166, 1.0, v166
	v_rcp_f32_e32 v166, v166
	v_and_b32_e32 v167, 0xffff0000, v148
	v_sqrt_f32_e32 v213, v213
	v_lshlrev_b32_e32 v148, 16, v148
	v_mul_f32_e32 v166, v166, v213
	v_mul_f32_e32 v166, v166, v167
	v_add_f32_e32 v167, v100, v76
	v_mul_f32_e32 v167, 0xbfb8aa3b, v167
	v_exp_f32_e32 v167, v167
	s_nop 0
	v_add_f32_e32 v167, 1.0, v167
	v_rcp_f32_e32 v167, v167
	v_lshl_add_u64 v[214:215], s[58:59], 0, v[146:147]
	v_sqrt_f32_e32 v168, v168
	v_add_f32_e32 v146, v96, v88
	v_mul_f32_e32 v146, 0xbfb8aa3b, v146
	v_mul_f32_e32 v167, v167, v168
	v_mul_f32_e32 v167, v167, v148
	v_and_b32_e32 v148, 0xffff0000, v149
	v_max_f32_e32 v149, 0, v212
	v_exp_f32_e32 v146, v146
	v_sqrt_f32_e32 v149, v149
	v_add_f32_e32 v146, 1.0, v146
	v_mul_f32_e32 v149, v165, v149
	v_mul_f32_e32 v165, v149, v148
	v_cvt_pk_bf16_f32 v148, v150, v151
	v_cvt_pk_bf16_f32 v149, v170, v171
	global_store_dwordx2 v[214:215], v[148:149], off
	v_cvt_pk_bf16_f32 v148, v167, v166
	v_cvt_pk_bf16_f32 v149, v164, v165
	global_store_dwordx2 v[218:219], v[148:149], off
	v_rcp_f32_e32 v146, v146
	s_nop 0
	v_mul_f32_e32 v146, 0xc1000000, v146
	v_mul_f32_e32 v146, v84, v146
	v_add_f32_e32 v147, v146, v146
	v_mul_f32_e32 v247, 0x3fb8aa3b, v147
	v_exp_f32_e32 v247, v247
	v_fma_f32 v148, v147, s14, 0.5
	v_fma_f32 v148, v147, v148, 1.0
	v_cmp_nlt_f32_e32 vcc, s51, v147
	v_mul_f32_e64 v148, v148, -v147
	v_sub_f32_e32 v247, 1.0, v247
	v_cndmask_b32_e32 v148, v148, v247, vcc
	v_add_f32_e32 v147, v97, v89
	v_mul_f32_e32 v147, 0xbfb8aa3b, v147
	v_exp_f32_e32 v147, v147
	s_nop 0
	v_add_f32_e32 v147, 1.0, v147
	v_rcp_f32_e32 v147, v147
	s_nop 0
	v_mul_f32_e32 v147, 0xc1000000, v147
	v_mul_f32_e32 v147, v85, v147
	v_add_f32_e32 v149, v147, v147
	v_mul_f32_e32 v247, 0x3fb8aa3b, v149
	v_exp_f32_e32 v247, v247
	v_fma_f32 v168, v149, s14, 0.5
	v_fma_f32 v168, v149, v168, 1.0
	v_cmp_nlt_f32_e32 vcc, s51, v149
	v_mul_f32_e64 v168, v168, -v149
	v_sub_f32_e32 v247, 1.0, v247
	v_cndmask_b32_e32 v168, v168, v247, vcc
	v_add_f32_e32 v149, v98, v90
	v_mul_f32_e32 v149, 0xbfb8aa3b, v149
	v_exp_f32_e32 v149, v149
	s_nop 0
	v_add_f32_e32 v149, 1.0, v149
	v_rcp_f32_e32 v149, v149
	s_nop 0
	v_mul_f32_e32 v149, 0xc1000000, v149
	v_mul_f32_e32 v149, v86, v149
	v_add_f32_e32 v150, v149, v149
	v_mul_f32_e32 v247, 0x3fb8aa3b, v150
	v_exp_f32_e32 v247, v247
	v_fma_f32 v170, v150, s14, 0.5
	v_fma_f32 v170, v150, v170, 1.0
	v_cmp_nlt_f32_e32 vcc, s51, v150
	v_mul_f32_e64 v170, v170, -v150
	v_sub_f32_e32 v247, 1.0, v247
	v_cndmask_b32_e32 v170, v170, v247, vcc
	v_add_f32_e32 v150, v99, v91
	v_mul_f32_e32 v150, 0xbfb8aa3b, v150
	v_exp_f32_e32 v150, v150
	s_nop 0
	v_add_f32_e32 v150, 1.0, v150
	v_rcp_f32_e32 v150, v150
	s_nop 0
	v_mul_f32_e32 v150, 0xc1000000, v150
	v_mul_f32_e32 v150, v87, v150
	v_add_f32_e32 v171, v150, v150
	v_mul_f32_e32 v247, 0x3fb8aa3b, v171
	v_exp_f32_e32 v247, v247
	v_fma_f32 v151, v171, s14, 0.5
	v_fma_f32 v151, v171, v151, 1.0
	v_cmp_nlt_f32_e32 vcc, s51, v171
	v_mul_f32_e64 v151, v151, -v171
	v_sub_f32_e32 v247, 1.0, v247
	v_cndmask_b32_e32 v151, v151, v247, vcc
	v_add_f32_e32 v164, v94, v78
	v_mul_f32_e32 v164, 0xbfb8aa3b, v164
	v_exp_f32_e32 v164, v164
	v_max_f32_e32 v168, 0, v168
	v_add_f32_e32 v164, 1.0, v164
	v_max_f32_e32 v148, 0, v148
	v_lshlrev_b64 v[142:143], 10, v[142:143]
	v_lshl_add_u64 v[142:143], v[142:143], 0, v[180:181]
	v_max_f32_e32 v166, 0, v170
	v_rcp_f32_e32 v164, v164
	v_lshlrev_b32_e32 v165, 16, v145
	v_sqrt_f32_e32 v166, v166
	v_lshlrev_b64 v[142:143], 1, v[142:143]
	v_lshl_add_u64 v[216:217], s[0:1], 0, v[142:143]
	v_mul_f32_e32 v164, v164, v166
	v_mul_f32_e32 v164, v164, v165
	v_add_f32_e32 v165, v95, v79
	v_mul_f32_e32 v165, 0xbfb8aa3b, v165
	v_exp_f32_e32 v165, v165
	s_nop 0
	v_add_f32_e32 v165, 1.0, v165
	v_rcp_f32_e32 v165, v165
	v_add_f32_e32 v166, v93, v77
	v_mul_f32_e32 v166, 0xbfb8aa3b, v166
	v_exp_f32_e32 v166, v166
	s_nop 0
	v_add_f32_e32 v166, 1.0, v166
	v_rcp_f32_e32 v166, v166
	v_and_b32_e32 v167, 0xffff0000, v144
	v_sqrt_f32_e32 v168, v168
	v_lshlrev_b32_e32 v144, 16, v144
	v_mul_f32_e32 v166, v166, v168
	v_mul_f32_e32 v166, v166, v167
	v_add_f32_e32 v167, v92, v76
	v_mul_f32_e32 v167, 0xbfb8aa3b, v167
	v_exp_f32_e32 v167, v167
	s_nop 0
	v_add_f32_e32 v167, 1.0, v167
	v_rcp_f32_e32 v167, v167
	v_lshl_add_u64 v[212:213], s[58:59], 0, v[142:143]
	v_sqrt_f32_e32 v148, v148
	s_nop 0
	v_mul_f32_e32 v148, v167, v148
	v_mul_f32_e32 v148, v148, v144
	v_and_b32_e32 v144, 0xffff0000, v145
	v_max_f32_e32 v145, 0, v151
	v_sqrt_f32_e32 v145, v145
	s_nop 0
	v_mul_f32_e32 v145, v165, v145
	v_mul_f32_e32 v151, v145, v144
	v_cvt_pk_bf16_f32 v144, v146, v147
	v_cvt_pk_bf16_f32 v145, v149, v150
	global_store_dwordx2 v[212:213], v[144:145], off
	v_cvt_pk_bf16_f32 v144, v148, v166
	v_cvt_pk_bf16_f32 v145, v164, v151
	global_store_dwordx2 v[216:217], v[144:145], off
	v_add_u32_e32 v144, 0xa0, v182
	v_ashrrev_i32_e32 v145, 31, v144
	v_lshlrev_b64 v[220:221], 11, v[144:145]
	v_lshl_add_u64 v[142:143], v[140:141], 0, v[220:221]
	global_load_dwordx2 v[146:147], v[142:143], off
	v_add_u32_e32 v142, 0xb0, v182
	v_ashrrev_i32_e32 v143, 31, v142
	v_lshlrev_b64 v[222:223], 11, v[142:143]
	v_lshl_add_u64 v[140:141], v[140:141], 0, v[222:223]
	global_load_dwordx2 v[140:141], v[140:141], off
	v_add_f32_e32 v148, v80, v88
	v_mul_f32_e32 v148, 0xbfb8aa3b, v148
	v_exp_f32_e32 v148, v148
	s_nop 0
	v_add_f32_e32 v148, 1.0, v148
	v_rcp_f32_e32 v148, v148
	s_nop 0
	v_mul_f32_e32 v148, 0xc1000000, v148
	v_mul_f32_e32 v148, v84, v148
	v_add_f32_e32 v149, v148, v148
	v_mul_f32_e32 v247, 0x3fb8aa3b, v149
	v_exp_f32_e32 v247, v247
	v_fma_f32 v150, v149, s14, 0.5
	v_fma_f32 v150, v149, v150, 1.0
	v_cmp_nlt_f32_e32 vcc, s51, v149
	v_mul_f32_e64 v150, v150, -v149
	v_sub_f32_e32 v247, 1.0, v247
	v_cndmask_b32_e32 v150, v150, v247, vcc
	v_add_f32_e32 v149, v81, v89
	v_mul_f32_e32 v149, 0xbfb8aa3b, v149
	v_exp_f32_e32 v149, v149
	s_nop 0
	v_add_f32_e32 v149, 1.0, v149
	v_rcp_f32_e32 v149, v149
	s_nop 0
	v_mul_f32_e32 v149, 0xc1000000, v149
	v_mul_f32_e32 v149, v85, v149
	v_add_f32_e32 v151, v149, v149
	v_mul_f32_e32 v247, 0x3fb8aa3b, v151
	v_exp_f32_e32 v247, v247
	v_fma_f32 v171, v151, s14, 0.5
	v_fma_f32 v171, v151, v171, 1.0
	v_cmp_nlt_f32_e32 vcc, s51, v151
	v_mul_f32_e64 v171, v171, -v151
	v_sub_f32_e32 v247, 1.0, v247
	v_cndmask_b32_e32 v171, v171, v247, vcc
	v_add_f32_e32 v151, v82, v90
	v_mul_f32_e32 v151, 0xbfb8aa3b, v151
	v_exp_f32_e32 v151, v151
	s_nop 0
	v_add_f32_e32 v151, 1.0, v151
	v_rcp_f32_e32 v151, v151
	s_nop 0
	v_mul_f32_e32 v151, 0xc1000000, v151
	v_mul_f32_e32 v151, v86, v151
	v_add_f32_e32 v168, v151, v151
	v_mul_f32_e32 v247, 0x3fb8aa3b, v168
	v_exp_f32_e32 v247, v247
	v_fma_f32 v224, v168, s14, 0.5
	v_fma_f32 v224, v168, v224, 1.0
	v_cmp_nlt_f32_e32 vcc, s51, v168
	v_mul_f32_e64 v224, v224, -v168
	v_sub_f32_e32 v247, 1.0, v247
	v_cndmask_b32_e32 v224, v224, v247, vcc
	v_add_f32_e32 v164, v83, v91
	v_mul_f32_e32 v164, 0xbfb8aa3b, v164
	v_exp_f32_e32 v164, v164
	s_nop 0
	v_add_f32_e32 v164, 1.0, v164
	v_rcp_f32_e32 v164, v164
	s_nop 0
	v_mul_f32_e32 v164, 0xc1000000, v164
	v_mul_f32_e32 v168, v87, v164
	v_add_f32_e32 v225, v168, v168
	v_mul_f32_e32 v247, 0x3fb8aa3b, v225
	v_exp_f32_e32 v247, v247
	v_fma_f32 v170, v225, s14, 0.5
	v_fma_f32 v170, v225, v170, 1.0
	v_cmp_nlt_f32_e32 vcc, s51, v225
	v_mul_f32_e64 v170, v170, -v225
	v_sub_f32_e32 v247, 1.0, v247
	v_cndmask_b32_e32 v170, v170, v247, vcc
	v_add_f32_e32 v164, v74, v78
	v_mul_f32_e32 v164, 0xbfb8aa3b, v164
	v_exp_f32_e32 v164, v164
	v_max_f32_e32 v171, 0, v171
	v_add_f32_e32 v164, 1.0, v164
	v_max_f32_e32 v150, 0, v150
	v_lshlrev_b64 v[144:145], 10, v[144:145]
	v_lshl_add_u64 v[144:145], v[144:145], 0, v[180:181]
	v_max_f32_e32 v166, 0, v224
	v_rcp_f32_e32 v164, v164
	s_waitcnt vmcnt(0)
	v_lshlrev_b32_e32 v165, 16, v147
	v_sqrt_f32_e32 v166, v166
	v_lshlrev_b64 v[144:145], 1, v[144:145]
	v_mul_f32_e32 v164, v164, v166
	v_mul_f32_e32 v164, v164, v165
	v_add_f32_e32 v165, v75, v79
	v_mul_f32_e32 v165, 0xbfb8aa3b, v165
	v_exp_f32_e32 v165, v165
	s_nop 0
	v_add_f32_e32 v165, 1.0, v165
	v_rcp_f32_e32 v165, v165
	v_add_f32_e32 v166, v73, v77
	v_mul_f32_e32 v166, 0xbfb8aa3b, v166
	v_exp_f32_e32 v166, v166
	s_nop 0
	v_add_f32_e32 v166, 1.0, v166
	v_rcp_f32_e32 v166, v166
	v_and_b32_e32 v167, 0xffff0000, v146
	v_sqrt_f32_e32 v171, v171
	v_lshlrev_b32_e32 v146, 16, v146
	v_mul_f32_e32 v166, v166, v171
	v_mul_f32_e32 v166, v166, v167
	v_add_f32_e32 v167, v72, v76
	v_mul_f32_e32 v167, 0xbfb8aa3b, v167
	v_exp_f32_e32 v167, v167
	s_nop 0
	v_add_f32_e32 v167, 1.0, v167
	v_rcp_f32_e32 v167, v167
	v_lshl_add_u64 v[224:225], s[58:59], 0, v[144:145]
	v_sqrt_f32_e32 v150, v150
	v_lshl_add_u64 v[226:227], s[0:1], 0, v[144:145]
	v_add_f32_e32 v144, v68, v88
	v_mul_f32_e32 v150, v167, v150
	v_mul_f32_e32 v150, v150, v146
	v_and_b32_e32 v146, 0xffff0000, v147
	v_max_f32_e32 v147, 0, v170
	v_mul_f32_e32 v144, 0xbfb8aa3b, v144
	v_exp_f32_e32 v144, v144
	v_sqrt_f32_e32 v147, v147
	v_add_f32_e32 v144, 1.0, v144
	v_mul_f32_e32 v147, v165, v147
	v_mul_f32_e32 v165, v147, v146
	v_cvt_pk_bf16_f32 v146, v148, v149
	v_cvt_pk_bf16_f32 v147, v151, v168
	global_store_dwordx2 v[224:225], v[146:147], off
	v_cvt_pk_bf16_f32 v146, v150, v166
	v_cvt_pk_bf16_f32 v147, v164, v165
	global_store_dwordx2 v[226:227], v[146:147], off
	v_rcp_f32_e32 v144, v144
	s_nop 0
	v_mul_f32_e32 v144, 0xc1000000, v144
	v_mul_f32_e32 v144, v84, v144
	v_add_f32_e32 v145, v144, v144
	v_mul_f32_e32 v247, 0x3fb8aa3b, v145
	v_exp_f32_e32 v247, v247
	v_fma_f32 v146, v145, s14, 0.5
	v_fma_f32 v146, v145, v146, 1.0
	v_cmp_nlt_f32_e32 vcc, s51, v145
	v_mul_f32_e64 v146, v146, -v145
	v_sub_f32_e32 v247, 1.0, v247
	v_cndmask_b32_e32 v146, v146, v247, vcc
	v_add_f32_e32 v145, v69, v89
	v_mul_f32_e32 v145, 0xbfb8aa3b, v145
	v_exp_f32_e32 v145, v145
	s_nop 0
	v_add_f32_e32 v145, 1.0, v145
	v_rcp_f32_e32 v145, v145
	s_nop 0
	v_mul_f32_e32 v145, 0xc1000000, v145
	v_mul_f32_e32 v145, v85, v145
	v_add_f32_e32 v147, v145, v145
	v_mul_f32_e32 v247, 0x3fb8aa3b, v147
	v_exp_f32_e32 v247, v247
	v_fma_f32 v150, v147, s14, 0.5
	v_fma_f32 v150, v147, v150, 1.0
	v_cmp_nlt_f32_e32 vcc, s51, v147
	v_mul_f32_e64 v150, v150, -v147
	v_sub_f32_e32 v247, 1.0, v247
	v_cndmask_b32_e32 v150, v150, v247, vcc
	v_add_f32_e32 v147, v70, v90
	v_mul_f32_e32 v147, 0xbfb8aa3b, v147
	v_exp_f32_e32 v147, v147
	s_nop 0
	v_add_f32_e32 v147, 1.0, v147
	v_rcp_f32_e32 v147, v147
	s_nop 0
	v_mul_f32_e32 v147, 0xc1000000, v147
	v_mul_f32_e32 v147, v86, v147
	v_add_f32_e32 v148, v147, v147
	v_mul_f32_e32 v247, 0x3fb8aa3b, v148
	v_exp_f32_e32 v247, v247
	v_fma_f32 v151, v148, s14, 0.5
	v_fma_f32 v151, v148, v151, 1.0
	v_cmp_nlt_f32_e32 vcc, s51, v148
	v_mul_f32_e64 v151, v151, -v148
	v_sub_f32_e32 v247, 1.0, v247
	v_cndmask_b32_e32 v151, v151, v247, vcc
	v_add_f32_e32 v148, v71, v91
	v_mul_f32_e32 v148, 0xbfb8aa3b, v148
	v_exp_f32_e32 v148, v148
	s_nop 0
	v_add_f32_e32 v148, 1.0, v148
	v_rcp_f32_e32 v148, v148
	s_nop 0
	v_mul_f32_e32 v148, 0xc1000000, v148
	v_mul_f32_e32 v148, v87, v148
	v_add_f32_e32 v168, v148, v148
	v_mul_f32_e32 v247, 0x3fb8aa3b, v168
	v_exp_f32_e32 v247, v247
	v_fma_f32 v149, v168, s14, 0.5
	v_fma_f32 v149, v168, v149, 1.0
	v_cmp_nlt_f32_e32 vcc, s51, v168
	v_mul_f32_e64 v149, v149, -v168
	v_sub_f32_e32 v247, 1.0, v247
	v_cndmask_b32_e32 v149, v149, v247, vcc
	v_add_f32_e32 v164, v66, v78
	v_mul_f32_e32 v164, 0xbfb8aa3b, v164
	v_exp_f32_e32 v164, v164
	v_max_f32_e32 v151, 0, v151
	v_add_f32_e32 v164, 1.0, v164
	v_max_f32_e32 v150, 0, v150
	v_max_f32_e32 v146, 0, v146
	v_rcp_f32_e32 v164, v164
	v_lshlrev_b32_e32 v165, 16, v141
	v_sqrt_f32_e32 v151, v151
	v_lshlrev_b64 v[142:143], 10, v[142:143]
	v_lshl_add_u64 v[234:235], s[28:29], 0, v[178:179]
	v_mul_f32_e32 v151, v164, v151
	v_add_f32_e32 v164, v67, v79
	v_mul_f32_e32 v164, 0xbfb8aa3b, v164
	v_exp_f32_e32 v164, v164
	v_mul_f32_e32 v151, v151, v165
	v_add_f32_e32 v164, 1.0, v164
	v_rcp_f32_e32 v164, v164
	v_add_f32_e32 v165, v65, v77
	v_mul_f32_e32 v165, 0xbfb8aa3b, v165
	v_exp_f32_e32 v165, v165
	s_nop 0
	v_add_f32_e32 v165, 1.0, v165
	v_rcp_f32_e32 v165, v165
	v_and_b32_e32 v166, 0xffff0000, v140
	v_sqrt_f32_e32 v150, v150
	v_lshlrev_b32_e32 v140, 16, v140
	v_mul_f32_e32 v150, v165, v150
	v_add_f32_e32 v165, v64, v76
	v_mul_f32_e32 v165, 0xbfb8aa3b, v165
	v_exp_f32_e32 v165, v165
	v_mul_f32_e32 v150, v150, v166
	v_add_f32_e32 v165, 1.0, v165
	v_rcp_f32_e32 v165, v165
	v_or_b32_e32 v170, 64, v180
	v_sqrt_f32_e32 v146, v146
	v_ashrrev_i32_e32 v171, 31, v170
	v_lshlrev_b64 v[232:233], 1, v[170:171]
	v_mul_f32_e32 v146, v165, v146
	v_mul_f32_e32 v146, v146, v140
	v_and_b32_e32 v140, 0xffff0000, v141
	v_max_f32_e32 v141, 0, v149
	v_lshl_add_u64 v[170:171], v[234:235], 0, v[232:233]
	v_sqrt_f32_e32 v141, v141
	s_nop 0
	v_mul_f32_e32 v141, v164, v141
	v_mul_f32_e32 v149, v141, v140
	v_lshl_add_u64 v[140:141], v[142:143], 0, v[180:181]
	v_lshlrev_b64 v[140:141], 1, v[140:141]
	v_cvt_pk_bf16_f32 v142, v144, v145
	v_cvt_pk_bf16_f32 v143, v147, v148
	v_lshl_add_u64 v[228:229], s[58:59], 0, v[140:141]
	v_lshl_add_u64 v[230:231], s[0:1], 0, v[140:141]
	global_store_dwordx2 v[228:229], v[142:143], off
	v_cvt_pk_bf16_f32 v142, v146, v150
	v_cvt_pk_bf16_f32 v143, v151, v149
	global_store_dwordx2 v[230:231], v[142:143], off
	global_load_dwordx4 v[148:151], v[172:173], off offset:256
	s_nop 0
	global_load_dwordx4 v[140:143], v[158:159], off offset:256
	global_load_dwordx4 v[144:147], v[174:175], off offset:256
	global_load_dwordx2 v[236:237], v[170:171], off
	v_lshl_add_u64 v[170:171], s[28:29], 0, v[176:177]
	v_lshl_add_u64 v[170:171], v[170:171], 0, v[232:233]
	global_load_dwordx2 v[234:235], v[170:171], off
	s_waitcnt vmcnt(0)
	v_add_f32_e32 v164, v60, v148
	v_mul_f32_e32 v164, 0xbfb8aa3b, v164
	v_exp_f32_e32 v164, v164
	s_nop 0
	v_add_f32_e32 v164, 1.0, v164
	v_rcp_f32_e32 v164, v164
	s_nop 0
	v_mul_f32_e32 v164, 0xc1000000, v164
	v_mul_f32_e32 v168, v144, v164
	v_add_f32_e32 v170, v168, v168
	v_mul_f32_e32 v247, 0x3fb8aa3b, v170
	v_exp_f32_e32 v247, v247
	v_fma_f32 v171, v170, s14, 0.5
	v_fma_f32 v171, v170, v171, 1.0
	v_cmp_nlt_f32_e32 vcc, s51, v170
	v_mul_f32_e64 v171, v171, -v170
	v_sub_f32_e32 v247, 1.0, v247
	v_cndmask_b32_e32 v171, v171, v247, vcc
	v_add_f32_e32 v164, v61, v149
	v_mul_f32_e32 v164, 0xbfb8aa3b, v164
	v_exp_f32_e32 v164, v164
	s_nop 0
	v_add_f32_e32 v164, 1.0, v164
	v_rcp_f32_e32 v164, v164
	s_nop 0
	v_mul_f32_e32 v164, 0xc1000000, v164
	v_mul_f32_e32 v170, v145, v164
	v_add_f32_e32 v241, v170, v170
	v_mul_f32_e32 v247, 0x3fb8aa3b, v241
	v_exp_f32_e32 v247, v247
	v_fma_f32 v244, v241, s14, 0.5
	v_fma_f32 v244, v241, v244, 1.0
	v_cmp_nlt_f32_e32 vcc, s51, v241
	v_mul_f32_e64 v244, v244, -v241
	v_sub_f32_e32 v247, 1.0, v247
	v_cndmask_b32_e32 v244, v244, v247, vcc
	v_add_f32_e32 v164, v62, v150
	v_mul_f32_e32 v164, 0xbfb8aa3b, v164
	v_exp_f32_e32 v164, v164
	s_nop 0
	v_add_f32_e32 v164, 1.0, v164
	v_rcp_f32_e32 v164, v164
	s_nop 0
	v_mul_f32_e32 v164, 0xc1000000, v164
	v_mul_f32_e32 v241, v146, v164
	v_add_f32_e32 v242, v241, v241
	v_mul_f32_e32 v247, 0x3fb8aa3b, v242
	v_exp_f32_e32 v247, v247
	v_fma_f32 v245, v242, s14, 0.5
	v_fma_f32 v245, v242, v245, 1.0
	v_cmp_nlt_f32_e32 vcc, s51, v242
	v_mul_f32_e64 v245, v245, -v242
	v_sub_f32_e32 v247, 1.0, v247
	v_cndmask_b32_e32 v245, v245, v247, vcc
	v_add_f32_e32 v164, v63, v151
	v_mul_f32_e32 v164, 0xbfb8aa3b, v164
	v_exp_f32_e32 v164, v164
	s_nop 0
	v_add_f32_e32 v164, 1.0, v164
	v_rcp_f32_e32 v164, v164
	s_nop 0
	v_mul_f32_e32 v164, 0xc1000000, v164
	v_mul_f32_e32 v242, v147, v164
	v_add_f32_e32 v246, v242, v242
	v_mul_f32_e32 v247, 0x3fb8aa3b, v246
	v_exp_f32_e32 v247, v247
	v_fma_f32 v243, v246, s14, 0.5
	v_fma_f32 v243, v246, v243, 1.0
	v_cmp_nlt_f32_e32 vcc, s51, v246
	v_mul_f32_e64 v243, v243, -v246
	v_sub_f32_e32 v247, 1.0, v247
	v_cndmask_b32_e32 v243, v243, v247, vcc
	v_add_f32_e32 v164, v58, v142
	v_mul_f32_e32 v164, 0xbfb8aa3b, v164
	v_exp_f32_e32 v164, v164
	v_max_f32_e32 v171, 0, v171
	v_cvt_pk_bf16_f32 v170, v168, v170
	v_add_f32_e32 v164, 1.0, v164
	v_max_f32_e32 v166, 0, v245
	v_rcp_f32_e32 v164, v164
	v_lshlrev_b32_e32 v165, 16, v237
	v_sqrt_f32_e32 v166, v166
	s_nop 0
	v_mul_f32_e32 v164, v164, v166
	v_mul_f32_e32 v164, v164, v165
	v_add_f32_e32 v165, v59, v143
	v_mul_f32_e32 v165, 0xbfb8aa3b, v165
	v_exp_f32_e32 v165, v165
	s_nop 0
	v_add_f32_e32 v165, 1.0, v165
	v_rcp_f32_e32 v165, v165
	v_add_f32_e32 v166, v57, v141
	v_mul_f32_e32 v166, 0xbfb8aa3b, v166
	v_exp_f32_e32 v166, v166
	s_nop 0
	v_add_f32_e32 v166, 1.0, v166
	v_max_f32_e32 v169, 0, v244
	v_rcp_f32_e32 v166, v166
	v_and_b32_e32 v167, 0xffff0000, v236
	v_sqrt_f32_e32 v169, v169
	s_nop 0
	v_mul_f32_e32 v166, v166, v169
	v_add_f32_e32 v169, v56, v140
	v_mul_f32_e32 v169, 0xbfb8aa3b, v169
	v_exp_f32_e32 v169, v169
	v_mul_f32_e32 v166, v166, v167
	v_lshlrev_b32_e32 v167, 16, v236
	v_add_f32_e32 v169, 1.0, v169
	v_rcp_f32_e32 v169, v169
	v_sqrt_f32_e32 v171, v171
	s_nop 0
	v_mul_f32_e32 v169, v169, v171
	v_max_f32_e32 v171, 0, v243
	v_mul_f32_e32 v167, v169, v167
	v_and_b32_e32 v169, 0xffff0000, v237
	v_sqrt_f32_e32 v171, v171
	s_nop 0
	v_mul_f32_e32 v165, v165, v171
	v_cvt_pk_bf16_f32 v171, v241, v242
	v_mul_f32_e32 v165, v165, v169
	global_store_dwordx2 v[190:191], v[170:171], off offset:128
	v_cvt_pk_bf16_f32 v170, v167, v166
	v_cvt_pk_bf16_f32 v171, v164, v165
	v_add_f32_e32 v164, v52, v148
	v_mul_f32_e32 v164, 0xbfb8aa3b, v164
	v_exp_f32_e32 v164, v164
	global_store_dwordx2 v[194:195], v[170:171], off offset:128
	v_add_f32_e32 v164, 1.0, v164
	v_rcp_f32_e32 v164, v164
	s_nop 0
	v_mul_f32_e32 v164, 0xc1000000, v164
	v_mul_f32_e32 v168, v144, v164
	v_add_f32_e32 v170, v168, v168
	v_mul_f32_e32 v247, 0x3fb8aa3b, v170
	v_exp_f32_e32 v247, v247
	v_fma_f32 v171, v170, s14, 0.5
	v_fma_f32 v171, v170, v171, 1.0
	v_cmp_nlt_f32_e32 vcc, s51, v170
	v_mul_f32_e64 v171, v171, -v170
	v_sub_f32_e32 v247, 1.0, v247
	v_cndmask_b32_e32 v171, v171, v247, vcc
	v_add_f32_e32 v164, v53, v149
	v_mul_f32_e32 v164, 0xbfb8aa3b, v164
	v_exp_f32_e32 v164, v164
	s_nop 0
	v_add_f32_e32 v164, 1.0, v164
	v_rcp_f32_e32 v164, v164
	s_nop 0
	v_mul_f32_e32 v164, 0xc1000000, v164
	v_mul_f32_e32 v170, v145, v164
	v_add_f32_e32 v190, v170, v170
	v_mul_f32_e32 v247, 0x3fb8aa3b, v190
	v_exp_f32_e32 v247, v247
	v_fma_f32 v195, v190, s14, 0.5
	v_fma_f32 v195, v190, v195, 1.0
	v_cmp_nlt_f32_e32 vcc, s51, v190
	v_mul_f32_e64 v195, v195, -v190
	v_sub_f32_e32 v247, 1.0, v247
	v_cndmask_b32_e32 v195, v195, v247, vcc
	v_add_f32_e32 v164, v54, v150
	v_mul_f32_e32 v164, 0xbfb8aa3b, v164
	v_exp_f32_e32 v164, v164
	s_nop 0
	v_add_f32_e32 v164, 1.0, v164
	v_rcp_f32_e32 v164, v164
	s_nop 0
	v_mul_f32_e32 v164, 0xc1000000, v164
	v_mul_f32_e32 v190, v146, v164
	v_add_f32_e32 v191, v190, v190
	v_mul_f32_e32 v247, 0x3fb8aa3b, v191
	v_exp_f32_e32 v247, v247
	v_fma_f32 v236, v191, s14, 0.5
	v_fma_f32 v236, v191, v236, 1.0
	v_cmp_nlt_f32_e32 vcc, s51, v191
	v_mul_f32_e64 v236, v236, -v191
	v_sub_f32_e32 v247, 1.0, v247
	v_cndmask_b32_e32 v236, v236, v247, vcc
	v_add_f32_e32 v164, v55, v151
	v_mul_f32_e32 v164, 0xbfb8aa3b, v164
	v_exp_f32_e32 v164, v164
	s_nop 0
	v_add_f32_e32 v164, 1.0, v164
	v_rcp_f32_e32 v164, v164
	s_nop 0
	v_mul_f32_e32 v164, 0xc1000000, v164
	v_mul_f32_e32 v191, v147, v164
	v_add_f32_e32 v237, v191, v191
	v_mul_f32_e32 v247, 0x3fb8aa3b, v237
	v_exp_f32_e32 v247, v247
	v_fma_f32 v194, v237, s14, 0.5
	v_fma_f32 v194, v237, v194, 1.0
	v_cmp_nlt_f32_e32 vcc, s51, v237
	v_mul_f32_e64 v194, v194, -v237
	v_sub_f32_e32 v247, 1.0, v247
	v_cndmask_b32_e32 v194, v194, v247, vcc
	v_add_f32_e32 v164, v50, v142
	v_mul_f32_e32 v164, 0xbfb8aa3b, v164
	v_exp_f32_e32 v164, v164
	v_max_f32_e32 v171, 0, v171
	v_cvt_pk_bf16_f32 v170, v168, v170
	v_add_f32_e32 v164, 1.0, v164
	v_max_f32_e32 v166, 0, v236
	v_rcp_f32_e32 v164, v164
	v_lshlrev_b32_e32 v165, 16, v235
	v_sqrt_f32_e32 v166, v166
	s_nop 0
	v_mul_f32_e32 v164, v164, v166
	v_mul_f32_e32 v164, v164, v165
	v_add_f32_e32 v165, v51, v143
	v_mul_f32_e32 v165, 0xbfb8aa3b, v165
	v_exp_f32_e32 v165, v165
	s_nop 0
	v_add_f32_e32 v165, 1.0, v165
	v_rcp_f32_e32 v165, v165
	v_add_f32_e32 v166, v49, v141
	v_mul_f32_e32 v166, 0xbfb8aa3b, v166
	v_exp_f32_e32 v166, v166
	s_nop 0
	v_add_f32_e32 v166, 1.0, v166
	v_max_f32_e32 v169, 0, v195
	v_rcp_f32_e32 v166, v166
	v_and_b32_e32 v167, 0xffff0000, v234
	v_sqrt_f32_e32 v169, v169
	s_nop 0
	v_mul_f32_e32 v166, v166, v169
	v_add_f32_e32 v169, v48, v140
	v_mul_f32_e32 v169, 0xbfb8aa3b, v169
	v_exp_f32_e32 v169, v169
	v_mul_f32_e32 v166, v166, v167
	v_lshlrev_b32_e32 v167, 16, v234
	v_add_f32_e32 v169, 1.0, v169
	v_rcp_f32_e32 v169, v169
	v_sqrt_f32_e32 v171, v171
	s_nop 0
	v_mul_f32_e32 v169, v169, v171
	v_max_f32_e32 v171, 0, v194
	v_mul_f32_e32 v167, v169, v167
	v_and_b32_e32 v169, 0xffff0000, v235
	v_sqrt_f32_e32 v171, v171
	s_nop 0
	v_mul_f32_e32 v165, v165, v171
	v_cvt_pk_bf16_f32 v171, v190, v191
	v_mul_f32_e32 v165, v165, v169
	global_store_dwordx2 v[188:189], v[170:171], off offset:128
	v_cvt_pk_bf16_f32 v170, v167, v166
	v_cvt_pk_bf16_f32 v171, v164, v165
	global_store_dwordx2 v[192:193], v[170:171], off offset:128
	v_lshl_add_u64 v[170:171], s[28:29], 0, v[196:197]
	v_lshl_add_u64 v[170:171], v[170:171], 0, v[232:233]
	global_load_dwordx2 v[190:191], v[170:171], off
	v_lshl_add_u64 v[170:171], s[28:29], 0, v[198:199]
	v_lshl_add_u64 v[170:171], v[170:171], 0, v[232:233]
	global_load_dwordx2 v[188:189], v[170:171], off
	v_add_f32_e32 v164, v44, v148
	v_mul_f32_e32 v164, 0xbfb8aa3b, v164
	v_exp_f32_e32 v164, v164
	s_nop 0
	v_add_f32_e32 v164, 1.0, v164
	v_rcp_f32_e32 v164, v164
	s_nop 0
	v_mul_f32_e32 v164, 0xc1000000, v164
	v_mul_f32_e32 v168, v144, v164
	v_add_f32_e32 v170, v168, v168
	v_mul_f32_e32 v247, 0x3fb8aa3b, v170
	v_exp_f32_e32 v247, v247
	v_fma_f32 v171, v170, s14, 0.5
	v_fma_f32 v171, v170, v171, 1.0
	v_cmp_nlt_f32_e32 vcc, s51, v170
	v_mul_f32_e64 v171, v171, -v170
	v_sub_f32_e32 v247, 1.0, v247
	v_cndmask_b32_e32 v171, v171, v247, vcc
	v_add_f32_e32 v164, v45, v149
	v_mul_f32_e32 v164, 0xbfb8aa3b, v164
	v_exp_f32_e32 v164, v164
	s_nop 0
	v_add_f32_e32 v164, 1.0, v164
	v_rcp_f32_e32 v164, v164
	s_nop 0
	v_mul_f32_e32 v164, 0xc1000000, v164
	v_mul_f32_e32 v170, v145, v164
	v_add_f32_e32 v192, v170, v170
	v_mul_f32_e32 v247, 0x3fb8aa3b, v192
	v_exp_f32_e32 v247, v247
	v_fma_f32 v195, v192, s14, 0.5
	v_fma_f32 v195, v192, v195, 1.0
	v_cmp_nlt_f32_e32 vcc, s51, v192
	v_mul_f32_e64 v195, v195, -v192
	v_sub_f32_e32 v247, 1.0, v247
	v_cndmask_b32_e32 v195, v195, v247, vcc
	v_add_f32_e32 v164, v46, v150
	v_mul_f32_e32 v164, 0xbfb8aa3b, v164
	v_exp_f32_e32 v164, v164
	s_nop 0
	v_add_f32_e32 v164, 1.0, v164
	v_rcp_f32_e32 v164, v164
	s_nop 0
	v_mul_f32_e32 v164, 0xc1000000, v164
	v_mul_f32_e32 v192, v146, v164
	v_add_f32_e32 v193, v192, v192
	v_mul_f32_e32 v247, 0x3fb8aa3b, v193
	v_exp_f32_e32 v247, v247
	v_fma_f32 v196, v193, s14, 0.5
	v_fma_f32 v196, v193, v196, 1.0
	v_cmp_nlt_f32_e32 vcc, s51, v193
	v_mul_f32_e64 v196, v196, -v193
	v_sub_f32_e32 v247, 1.0, v247
	v_cndmask_b32_e32 v196, v196, v247, vcc
	v_add_f32_e32 v164, v47, v151
	v_mul_f32_e32 v164, 0xbfb8aa3b, v164
	v_exp_f32_e32 v164, v164
	s_nop 0
	v_add_f32_e32 v164, 1.0, v164
	v_rcp_f32_e32 v164, v164
	s_nop 0
	v_mul_f32_e32 v164, 0xc1000000, v164
	v_mul_f32_e32 v193, v147, v164
	v_add_f32_e32 v197, v193, v193
	v_mul_f32_e32 v247, 0x3fb8aa3b, v197
	v_exp_f32_e32 v247, v247
	v_fma_f32 v194, v197, s14, 0.5
	v_fma_f32 v194, v197, v194, 1.0
	v_cmp_nlt_f32_e32 vcc, s51, v197
	v_mul_f32_e64 v194, v194, -v197
	v_sub_f32_e32 v247, 1.0, v247
	v_cndmask_b32_e32 v194, v194, v247, vcc
	v_add_f32_e32 v164, v42, v142
	v_mul_f32_e32 v164, 0xbfb8aa3b, v164
	v_exp_f32_e32 v164, v164
	v_max_f32_e32 v171, 0, v171
	v_cvt_pk_bf16_f32 v170, v168, v170
	v_add_f32_e32 v164, 1.0, v164
	v_max_f32_e32 v166, 0, v196
	v_rcp_f32_e32 v164, v164
	s_waitcnt vmcnt(0)
	v_lshlrev_b32_e32 v165, 16, v191
	v_sqrt_f32_e32 v166, v166
	s_nop 0
	v_mul_f32_e32 v164, v164, v166
	v_mul_f32_e32 v164, v164, v165
	v_add_f32_e32 v165, v43, v143
	v_mul_f32_e32 v165, 0xbfb8aa3b, v165
	v_exp_f32_e32 v165, v165
	s_nop 0
	v_add_f32_e32 v165, 1.0, v165
	v_rcp_f32_e32 v165, v165
	v_add_f32_e32 v166, v41, v141
	v_mul_f32_e32 v166, 0xbfb8aa3b, v166
	v_exp_f32_e32 v166, v166
	s_nop 0
	v_add_f32_e32 v166, 1.0, v166
	v_max_f32_e32 v169, 0, v195
	v_rcp_f32_e32 v166, v166
	v_and_b32_e32 v167, 0xffff0000, v190
	v_sqrt_f32_e32 v169, v169
	s_nop 0
	v_mul_f32_e32 v166, v166, v169
	v_add_f32_e32 v169, v40, v140
	v_mul_f32_e32 v169, 0xbfb8aa3b, v169
	v_exp_f32_e32 v169, v169
	v_mul_f32_e32 v166, v166, v167
	v_lshlrev_b32_e32 v167, 16, v190
	v_add_f32_e32 v169, 1.0, v169
	v_rcp_f32_e32 v169, v169
	v_sqrt_f32_e32 v171, v171
	s_nop 0
	v_mul_f32_e32 v169, v169, v171
	v_max_f32_e32 v171, 0, v194
	v_mul_f32_e32 v167, v169, v167
	v_and_b32_e32 v169, 0xffff0000, v191
	v_sqrt_f32_e32 v171, v171
	s_nop 0
	v_mul_f32_e32 v165, v165, v171
	v_cvt_pk_bf16_f32 v171, v192, v193
	v_mul_f32_e32 v165, v165, v169
	global_store_dwordx2 v[202:203], v[170:171], off offset:128
	v_cvt_pk_bf16_f32 v170, v167, v166
	v_cvt_pk_bf16_f32 v171, v164, v165
	v_add_f32_e32 v164, v36, v148
	v_mul_f32_e32 v164, 0xbfb8aa3b, v164
	v_exp_f32_e32 v164, v164
	global_store_dwordx2 v[206:207], v[170:171], off offset:128
	v_add_f32_e32 v164, 1.0, v164
	v_rcp_f32_e32 v164, v164
	s_nop 0
	v_mul_f32_e32 v164, 0xc1000000, v164
	v_mul_f32_e32 v168, v144, v164
	v_add_f32_e32 v170, v168, v168
	v_mul_f32_e32 v247, 0x3fb8aa3b, v170
	v_exp_f32_e32 v247, v247
	v_fma_f32 v171, v170, s14, 0.5
	v_fma_f32 v171, v170, v171, 1.0
	v_cmp_nlt_f32_e32 vcc, s51, v170
	v_mul_f32_e64 v171, v171, -v170
	v_sub_f32_e32 v247, 1.0, v247
	v_cndmask_b32_e32 v171, v171, v247, vcc
	v_add_f32_e32 v164, v37, v149
	v_mul_f32_e32 v164, 0xbfb8aa3b, v164
	v_exp_f32_e32 v164, v164
	s_nop 0
	v_add_f32_e32 v164, 1.0, v164
	v_rcp_f32_e32 v164, v164
	s_nop 0
	v_mul_f32_e32 v164, 0xc1000000, v164
	v_mul_f32_e32 v170, v145, v164
	v_add_f32_e32 v190, v170, v170
	v_mul_f32_e32 v247, 0x3fb8aa3b, v190
	v_exp_f32_e32 v247, v247
	v_fma_f32 v193, v190, s14, 0.5
	v_fma_f32 v193, v190, v193, 1.0
	v_cmp_nlt_f32_e32 vcc, s51, v190
	v_mul_f32_e64 v193, v193, -v190
	v_sub_f32_e32 v247, 1.0, v247
	v_cndmask_b32_e32 v193, v193, v247, vcc
	v_add_f32_e32 v164, v38, v150
	v_mul_f32_e32 v164, 0xbfb8aa3b, v164
	v_exp_f32_e32 v164, v164
	s_nop 0
	v_add_f32_e32 v164, 1.0, v164
	v_rcp_f32_e32 v164, v164
	s_nop 0
	v_mul_f32_e32 v164, 0xc1000000, v164
	v_mul_f32_e32 v190, v146, v164
	v_add_f32_e32 v191, v190, v190
	v_mul_f32_e32 v247, 0x3fb8aa3b, v191
	v_exp_f32_e32 v247, v247
	v_fma_f32 v194, v191, s14, 0.5
	v_fma_f32 v194, v191, v194, 1.0
	v_cmp_nlt_f32_e32 vcc, s51, v191
	v_mul_f32_e64 v194, v194, -v191
	v_sub_f32_e32 v247, 1.0, v247
	v_cndmask_b32_e32 v194, v194, v247, vcc
	v_add_f32_e32 v164, v39, v151
	v_mul_f32_e32 v164, 0xbfb8aa3b, v164
	v_exp_f32_e32 v164, v164
	s_nop 0
	v_add_f32_e32 v164, 1.0, v164
	v_rcp_f32_e32 v164, v164
	s_nop 0
	v_mul_f32_e32 v164, 0xc1000000, v164
	v_mul_f32_e32 v191, v147, v164
	v_add_f32_e32 v195, v191, v191
	v_mul_f32_e32 v247, 0x3fb8aa3b, v195
	v_exp_f32_e32 v247, v247
	v_fma_f32 v192, v195, s14, 0.5
	v_fma_f32 v192, v195, v192, 1.0
	v_cmp_nlt_f32_e32 vcc, s51, v195
	v_mul_f32_e64 v192, v192, -v195
	v_sub_f32_e32 v247, 1.0, v247
	v_cndmask_b32_e32 v192, v192, v247, vcc
	v_add_f32_e32 v164, v34, v142
	v_mul_f32_e32 v164, 0xbfb8aa3b, v164
	v_exp_f32_e32 v164, v164
	v_max_f32_e32 v171, 0, v171
	v_cvt_pk_bf16_f32 v170, v168, v170
	v_add_f32_e32 v164, 1.0, v164
	v_max_f32_e32 v166, 0, v194
	v_rcp_f32_e32 v164, v164
	v_lshlrev_b32_e32 v165, 16, v189
	v_sqrt_f32_e32 v166, v166
	s_nop 0
	v_mul_f32_e32 v164, v164, v166
	v_mul_f32_e32 v164, v164, v165
	v_add_f32_e32 v165, v35, v143
	v_mul_f32_e32 v165, 0xbfb8aa3b, v165
	v_exp_f32_e32 v165, v165
	s_nop 0
	v_add_f32_e32 v165, 1.0, v165
	v_rcp_f32_e32 v165, v165
	v_add_f32_e32 v166, v33, v141
	v_mul_f32_e32 v166, 0xbfb8aa3b, v166
	v_exp_f32_e32 v166, v166
	s_nop 0
	v_add_f32_e32 v166, 1.0, v166
	v_max_f32_e32 v169, 0, v193
	v_rcp_f32_e32 v166, v166
	v_and_b32_e32 v167, 0xffff0000, v188
	v_sqrt_f32_e32 v169, v169
	s_nop 0
	v_mul_f32_e32 v166, v166, v169
	v_add_f32_e32 v169, v32, v140
	v_mul_f32_e32 v169, 0xbfb8aa3b, v169
	v_exp_f32_e32 v169, v169
	v_mul_f32_e32 v166, v166, v167
	v_lshlrev_b32_e32 v167, 16, v188
	v_add_f32_e32 v169, 1.0, v169
	v_rcp_f32_e32 v169, v169
	v_sqrt_f32_e32 v171, v171
	s_nop 0
	v_mul_f32_e32 v169, v169, v171
	v_max_f32_e32 v171, 0, v192
	v_mul_f32_e32 v167, v169, v167
	v_and_b32_e32 v169, 0xffff0000, v189
	v_sqrt_f32_e32 v171, v171
	s_nop 0
	v_mul_f32_e32 v165, v165, v171
	v_cvt_pk_bf16_f32 v171, v190, v191
	v_mul_f32_e32 v165, v165, v169
	global_store_dwordx2 v[200:201], v[170:171], off offset:128
	v_cvt_pk_bf16_f32 v170, v167, v166
	v_cvt_pk_bf16_f32 v171, v164, v165
	global_store_dwordx2 v[204:205], v[170:171], off offset:128
	v_lshl_add_u64 v[170:171], s[28:29], 0, v[208:209]
	v_lshl_add_u64 v[170:171], v[170:171], 0, v[232:233]
	global_load_dwordx2 v[190:191], v[170:171], off
	v_lshl_add_u64 v[170:171], s[28:29], 0, v[210:211]
	v_lshl_add_u64 v[170:171], v[170:171], 0, v[232:233]
	global_load_dwordx2 v[188:189], v[170:171], off
	v_add_f32_e32 v164, v28, v148
	v_mul_f32_e32 v164, 0xbfb8aa3b, v164
	v_exp_f32_e32 v164, v164
	s_nop 0
	v_add_f32_e32 v164, 1.0, v164
	v_rcp_f32_e32 v164, v164
	s_nop 0
	v_mul_f32_e32 v164, 0xc1000000, v164
	v_mul_f32_e32 v168, v144, v164
	v_add_f32_e32 v170, v168, v168
	v_mul_f32_e32 v247, 0x3fb8aa3b, v170
	v_exp_f32_e32 v247, v247
	v_fma_f32 v171, v170, s14, 0.5
	v_fma_f32 v171, v170, v171, 1.0
	v_cmp_nlt_f32_e32 vcc, s51, v170
	v_mul_f32_e64 v171, v171, -v170
	v_sub_f32_e32 v247, 1.0, v247
	v_cndmask_b32_e32 v171, v171, v247, vcc
	v_add_f32_e32 v164, v29, v149
	v_mul_f32_e32 v164, 0xbfb8aa3b, v164
	v_exp_f32_e32 v164, v164
	s_nop 0
	v_add_f32_e32 v164, 1.0, v164
	v_rcp_f32_e32 v164, v164
	s_nop 0
	v_mul_f32_e32 v164, 0xc1000000, v164
	v_mul_f32_e32 v170, v145, v164
	v_add_f32_e32 v192, v170, v170
	v_mul_f32_e32 v247, 0x3fb8aa3b, v192
	v_exp_f32_e32 v247, v247
	v_fma_f32 v195, v192, s14, 0.5
	v_fma_f32 v195, v192, v195, 1.0
	v_cmp_nlt_f32_e32 vcc, s51, v192
	v_mul_f32_e64 v195, v195, -v192
	v_sub_f32_e32 v247, 1.0, v247
	v_cndmask_b32_e32 v195, v195, v247, vcc
	v_add_f32_e32 v164, v30, v150
	v_mul_f32_e32 v164, 0xbfb8aa3b, v164
	v_exp_f32_e32 v164, v164
	s_nop 0
	v_add_f32_e32 v164, 1.0, v164
	v_rcp_f32_e32 v164, v164
	s_nop 0
	v_mul_f32_e32 v164, 0xc1000000, v164
	v_mul_f32_e32 v192, v146, v164
	v_add_f32_e32 v193, v192, v192
	v_mul_f32_e32 v247, 0x3fb8aa3b, v193
	v_exp_f32_e32 v247, v247
	v_fma_f32 v196, v193, s14, 0.5
	v_fma_f32 v196, v193, v196, 1.0
	v_cmp_nlt_f32_e32 vcc, s51, v193
	v_mul_f32_e64 v196, v196, -v193
	v_sub_f32_e32 v247, 1.0, v247
	v_cndmask_b32_e32 v196, v196, v247, vcc
	v_add_f32_e32 v164, v31, v151
	v_mul_f32_e32 v164, 0xbfb8aa3b, v164
	v_exp_f32_e32 v164, v164
	s_nop 0
	v_add_f32_e32 v164, 1.0, v164
	v_rcp_f32_e32 v164, v164
	s_nop 0
	v_mul_f32_e32 v164, 0xc1000000, v164
	v_mul_f32_e32 v193, v147, v164
	v_add_f32_e32 v197, v193, v193
	v_mul_f32_e32 v247, 0x3fb8aa3b, v197
	v_exp_f32_e32 v247, v247
	v_fma_f32 v194, v197, s14, 0.5
	v_fma_f32 v194, v197, v194, 1.0
	v_cmp_nlt_f32_e32 vcc, s51, v197
	v_mul_f32_e64 v194, v194, -v197
	v_sub_f32_e32 v247, 1.0, v247
	v_cndmask_b32_e32 v194, v194, v247, vcc
	v_add_f32_e32 v164, v26, v142
	v_mul_f32_e32 v164, 0xbfb8aa3b, v164
	v_exp_f32_e32 v164, v164
	v_max_f32_e32 v171, 0, v171
	v_cvt_pk_bf16_f32 v170, v168, v170
	v_add_f32_e32 v164, 1.0, v164
	v_max_f32_e32 v166, 0, v196
	v_rcp_f32_e32 v164, v164
	s_waitcnt vmcnt(0)
	v_lshlrev_b32_e32 v165, 16, v191
	v_sqrt_f32_e32 v166, v166
	s_nop 0
	v_mul_f32_e32 v164, v164, v166
	v_mul_f32_e32 v164, v164, v165
	v_add_f32_e32 v165, v27, v143
	v_mul_f32_e32 v165, 0xbfb8aa3b, v165
	v_exp_f32_e32 v165, v165
	s_nop 0
	v_add_f32_e32 v165, 1.0, v165
	v_rcp_f32_e32 v165, v165
	v_add_f32_e32 v166, v25, v141
	v_mul_f32_e32 v166, 0xbfb8aa3b, v166
	v_exp_f32_e32 v166, v166
	s_nop 0
	v_add_f32_e32 v166, 1.0, v166
	v_max_f32_e32 v169, 0, v195
	v_rcp_f32_e32 v166, v166
	v_and_b32_e32 v167, 0xffff0000, v190
	v_sqrt_f32_e32 v169, v169
	s_nop 0
	v_mul_f32_e32 v166, v166, v169
	v_add_f32_e32 v169, v24, v140
	v_mul_f32_e32 v169, 0xbfb8aa3b, v169
	v_exp_f32_e32 v169, v169
	v_mul_f32_e32 v166, v166, v167
	v_lshlrev_b32_e32 v167, 16, v190
	v_add_f32_e32 v169, 1.0, v169
	v_rcp_f32_e32 v169, v169
	v_sqrt_f32_e32 v171, v171
	s_nop 0
	v_mul_f32_e32 v169, v169, v171
	v_max_f32_e32 v171, 0, v194
	v_mul_f32_e32 v167, v169, v167
	v_and_b32_e32 v169, 0xffff0000, v191
	v_sqrt_f32_e32 v171, v171
	s_nop 0
	v_mul_f32_e32 v165, v165, v171
	v_cvt_pk_bf16_f32 v171, v192, v193
	v_mul_f32_e32 v165, v165, v169
	global_store_dwordx2 v[214:215], v[170:171], off offset:128
	v_cvt_pk_bf16_f32 v170, v167, v166
	v_cvt_pk_bf16_f32 v171, v164, v165
	v_add_f32_e32 v164, v20, v148
	v_mul_f32_e32 v164, 0xbfb8aa3b, v164
	v_exp_f32_e32 v164, v164
	global_store_dwordx2 v[218:219], v[170:171], off offset:128
	v_add_f32_e32 v164, 1.0, v164
	v_rcp_f32_e32 v164, v164
	s_nop 0
	v_mul_f32_e32 v164, 0xc1000000, v164
	v_mul_f32_e32 v168, v144, v164
	v_add_f32_e32 v170, v168, v168
	v_mul_f32_e32 v247, 0x3fb8aa3b, v170
	v_exp_f32_e32 v247, v247
	v_fma_f32 v171, v170, s14, 0.5
	v_fma_f32 v171, v170, v171, 1.0
	v_cmp_nlt_f32_e32 vcc, s51, v170
	v_mul_f32_e64 v171, v171, -v170
	v_sub_f32_e32 v247, 1.0, v247
	v_cndmask_b32_e32 v171, v171, v247, vcc
	v_add_f32_e32 v164, v21, v149
	v_mul_f32_e32 v164, 0xbfb8aa3b, v164
	v_exp_f32_e32 v164, v164
	s_nop 0
	v_add_f32_e32 v164, 1.0, v164
	v_rcp_f32_e32 v164, v164
	s_nop 0
	v_mul_f32_e32 v164, 0xc1000000, v164
	v_mul_f32_e32 v170, v145, v164
	v_add_f32_e32 v190, v170, v170
	v_mul_f32_e32 v247, 0x3fb8aa3b, v190
	v_exp_f32_e32 v247, v247
	v_fma_f32 v193, v190, s14, 0.5
	v_fma_f32 v193, v190, v193, 1.0
	v_cmp_nlt_f32_e32 vcc, s51, v190
	v_mul_f32_e64 v193, v193, -v190
	v_sub_f32_e32 v247, 1.0, v247
	v_cndmask_b32_e32 v193, v193, v247, vcc
	v_add_f32_e32 v164, v22, v150
	v_mul_f32_e32 v164, 0xbfb8aa3b, v164
	v_exp_f32_e32 v164, v164
	s_nop 0
	v_add_f32_e32 v164, 1.0, v164
	v_rcp_f32_e32 v164, v164
	s_nop 0
	v_mul_f32_e32 v164, 0xc1000000, v164
	v_mul_f32_e32 v190, v146, v164
	v_add_f32_e32 v191, v190, v190
	v_mul_f32_e32 v247, 0x3fb8aa3b, v191
	v_exp_f32_e32 v247, v247
	v_fma_f32 v194, v191, s14, 0.5
	v_fma_f32 v194, v191, v194, 1.0
	v_cmp_nlt_f32_e32 vcc, s51, v191
	v_mul_f32_e64 v194, v194, -v191
	v_sub_f32_e32 v247, 1.0, v247
	v_cndmask_b32_e32 v194, v194, v247, vcc
	v_add_f32_e32 v164, v23, v151
	v_mul_f32_e32 v164, 0xbfb8aa3b, v164
	v_exp_f32_e32 v164, v164
	s_nop 0
	v_add_f32_e32 v164, 1.0, v164
	v_rcp_f32_e32 v164, v164
	s_nop 0
	v_mul_f32_e32 v164, 0xc1000000, v164
	v_mul_f32_e32 v191, v147, v164
	v_add_f32_e32 v195, v191, v191
	v_mul_f32_e32 v247, 0x3fb8aa3b, v195
	v_exp_f32_e32 v247, v247
	v_fma_f32 v192, v195, s14, 0.5
	v_fma_f32 v192, v195, v192, 1.0
	v_cmp_nlt_f32_e32 vcc, s51, v195
	v_mul_f32_e64 v192, v192, -v195
	v_sub_f32_e32 v247, 1.0, v247
	v_cndmask_b32_e32 v192, v192, v247, vcc
	v_add_f32_e32 v164, v18, v142
	v_mul_f32_e32 v164, 0xbfb8aa3b, v164
	v_exp_f32_e32 v164, v164
	v_max_f32_e32 v171, 0, v171
	v_cvt_pk_bf16_f32 v170, v168, v170
	v_add_f32_e32 v164, 1.0, v164
	v_max_f32_e32 v166, 0, v194
	v_rcp_f32_e32 v164, v164
	v_lshlrev_b32_e32 v165, 16, v189
	v_sqrt_f32_e32 v166, v166
	s_nop 0
	v_mul_f32_e32 v164, v164, v166
	v_mul_f32_e32 v164, v164, v165
	v_add_f32_e32 v165, v19, v143
	v_mul_f32_e32 v165, 0xbfb8aa3b, v165
	v_exp_f32_e32 v165, v165
	s_nop 0
	v_add_f32_e32 v165, 1.0, v165
	v_rcp_f32_e32 v165, v165
	v_add_f32_e32 v166, v17, v141
	v_mul_f32_e32 v166, 0xbfb8aa3b, v166
	v_exp_f32_e32 v166, v166
	s_nop 0
	v_add_f32_e32 v166, 1.0, v166
	v_max_f32_e32 v169, 0, v193
	v_rcp_f32_e32 v166, v166
	v_and_b32_e32 v167, 0xffff0000, v188
	v_sqrt_f32_e32 v169, v169
	s_nop 0
	v_mul_f32_e32 v166, v166, v169
	v_add_f32_e32 v169, v16, v140
	v_mul_f32_e32 v169, 0xbfb8aa3b, v169
	v_exp_f32_e32 v169, v169
	v_mul_f32_e32 v166, v166, v167
	v_lshlrev_b32_e32 v167, 16, v188
	v_add_f32_e32 v169, 1.0, v169
	v_rcp_f32_e32 v169, v169
	v_sqrt_f32_e32 v171, v171
	s_nop 0
	v_mul_f32_e32 v169, v169, v171
	v_max_f32_e32 v171, 0, v192
	v_mul_f32_e32 v167, v169, v167
	v_and_b32_e32 v169, 0xffff0000, v189
	v_sqrt_f32_e32 v171, v171
	s_nop 0
	v_mul_f32_e32 v165, v165, v171
	v_cvt_pk_bf16_f32 v171, v190, v191
	v_mul_f32_e32 v165, v165, v169
	global_store_dwordx2 v[212:213], v[170:171], off offset:128
	v_cvt_pk_bf16_f32 v170, v167, v166
	v_cvt_pk_bf16_f32 v171, v164, v165
	global_store_dwordx2 v[216:217], v[170:171], off offset:128
	v_lshl_add_u64 v[170:171], s[28:29], 0, v[220:221]
	v_lshl_add_u64 v[170:171], v[170:171], 0, v[232:233]
	global_load_dwordx2 v[190:191], v[170:171], off
	v_lshl_add_u64 v[170:171], s[28:29], 0, v[222:223]
	v_lshl_add_u64 v[170:171], v[170:171], 0, v[232:233]
	global_load_dwordx2 v[188:189], v[170:171], off
	v_add_f32_e32 v164, v12, v148
	v_mul_f32_e32 v164, 0xbfb8aa3b, v164
	v_exp_f32_e32 v164, v164
	s_nop 0
	v_add_f32_e32 v164, 1.0, v164
	v_rcp_f32_e32 v164, v164
	s_nop 0
	v_mul_f32_e32 v164, 0xc1000000, v164
	v_mul_f32_e32 v168, v144, v164
	v_add_f32_e32 v170, v168, v168
	v_mul_f32_e32 v247, 0x3fb8aa3b, v170
	v_exp_f32_e32 v247, v247
	v_fma_f32 v171, v170, s14, 0.5
	v_fma_f32 v171, v170, v171, 1.0
	v_cmp_nlt_f32_e32 vcc, s51, v170
	v_mul_f32_e64 v171, v171, -v170
	v_sub_f32_e32 v247, 1.0, v247
	v_cndmask_b32_e32 v171, v171, v247, vcc
	v_add_f32_e32 v164, v13, v149
	v_mul_f32_e32 v164, 0xbfb8aa3b, v164
	v_exp_f32_e32 v164, v164
	s_nop 0
	v_add_f32_e32 v164, 1.0, v164
	v_rcp_f32_e32 v164, v164
	s_nop 0
	v_mul_f32_e32 v164, 0xc1000000, v164
	v_mul_f32_e32 v170, v145, v164
	v_add_f32_e32 v192, v170, v170
	v_mul_f32_e32 v247, 0x3fb8aa3b, v192
	v_exp_f32_e32 v247, v247
	v_fma_f32 v195, v192, s14, 0.5
	v_fma_f32 v195, v192, v195, 1.0
	v_cmp_nlt_f32_e32 vcc, s51, v192
	v_mul_f32_e64 v195, v195, -v192
	v_sub_f32_e32 v247, 1.0, v247
	v_cndmask_b32_e32 v195, v195, v247, vcc
	v_add_f32_e32 v164, v14, v150
	v_mul_f32_e32 v164, 0xbfb8aa3b, v164
	v_exp_f32_e32 v164, v164
	s_nop 0
	v_add_f32_e32 v164, 1.0, v164
	v_rcp_f32_e32 v164, v164
	s_nop 0
	v_mul_f32_e32 v164, 0xc1000000, v164
	v_mul_f32_e32 v192, v146, v164
	v_add_f32_e32 v193, v192, v192
	v_mul_f32_e32 v247, 0x3fb8aa3b, v193
	v_exp_f32_e32 v247, v247
	v_fma_f32 v196, v193, s14, 0.5
	v_fma_f32 v196, v193, v196, 1.0
	v_cmp_nlt_f32_e32 vcc, s51, v193
	v_mul_f32_e64 v196, v196, -v193
	v_sub_f32_e32 v247, 1.0, v247
	v_cndmask_b32_e32 v196, v196, v247, vcc
	v_add_f32_e32 v164, v15, v151
	v_mul_f32_e32 v164, 0xbfb8aa3b, v164
	v_exp_f32_e32 v164, v164
	s_nop 0
	v_add_f32_e32 v164, 1.0, v164
	v_rcp_f32_e32 v164, v164
	s_nop 0
	v_mul_f32_e32 v164, 0xc1000000, v164
	v_mul_f32_e32 v193, v147, v164
	v_add_f32_e32 v197, v193, v193
	v_mul_f32_e32 v247, 0x3fb8aa3b, v197
	v_exp_f32_e32 v247, v247
	v_fma_f32 v194, v197, s14, 0.5
	v_fma_f32 v194, v197, v194, 1.0
	v_cmp_nlt_f32_e32 vcc, s51, v197
	v_mul_f32_e64 v194, v194, -v197
	v_sub_f32_e32 v247, 1.0, v247
	v_cndmask_b32_e32 v194, v194, v247, vcc
	v_add_f32_e32 v164, v10, v142
	v_mul_f32_e32 v164, 0xbfb8aa3b, v164
	v_exp_f32_e32 v164, v164
	v_max_f32_e32 v171, 0, v171
	v_add_f32_e32 v148, v4, v148
	v_add_f32_e32 v164, 1.0, v164
	v_mul_f32_e32 v148, 0xbfb8aa3b, v148
	v_exp_f32_e32 v148, v148
	v_cvt_pk_bf16_f32 v170, v168, v170
	v_max_f32_e32 v166, 0, v196
	v_rcp_f32_e32 v164, v164
	s_waitcnt vmcnt(0)
	v_lshlrev_b32_e32 v165, 16, v191
	v_sqrt_f32_e32 v166, v166
	v_add_f32_e32 v148, 1.0, v148
	v_mul_f32_e32 v164, v164, v166
	v_mul_f32_e32 v164, v164, v165
	v_add_f32_e32 v165, v11, v143
	v_mul_f32_e32 v165, 0xbfb8aa3b, v165
	v_exp_f32_e32 v165, v165
	s_nop 0
	v_add_f32_e32 v165, 1.0, v165
	v_rcp_f32_e32 v165, v165
	v_add_f32_e32 v166, v9, v141
	v_mul_f32_e32 v166, 0xbfb8aa3b, v166
	v_exp_f32_e32 v166, v166
	s_nop 0
	v_add_f32_e32 v166, 1.0, v166
	v_max_f32_e32 v169, 0, v195
	v_rcp_f32_e32 v166, v166
	v_and_b32_e32 v167, 0xffff0000, v190
	v_sqrt_f32_e32 v169, v169
	s_nop 0
	v_mul_f32_e32 v166, v166, v169
	v_add_f32_e32 v169, v8, v140
	v_mul_f32_e32 v169, 0xbfb8aa3b, v169
	v_exp_f32_e32 v169, v169
	v_mul_f32_e32 v166, v166, v167
	v_lshlrev_b32_e32 v167, 16, v190
	v_add_f32_e32 v169, 1.0, v169
	v_rcp_f32_e32 v169, v169
	v_sqrt_f32_e32 v171, v171
	s_nop 0
	v_mul_f32_e32 v169, v169, v171
	v_max_f32_e32 v171, 0, v194
	v_mul_f32_e32 v167, v169, v167
	v_and_b32_e32 v169, 0xffff0000, v191
	v_sqrt_f32_e32 v171, v171
	s_nop 0
	v_mul_f32_e32 v165, v165, v171
	v_cvt_pk_bf16_f32 v171, v192, v193
	v_mul_f32_e32 v165, v165, v169
	global_store_dwordx2 v[224:225], v[170:171], off offset:128
	v_cvt_pk_bf16_f32 v170, v167, v166
	v_cvt_pk_bf16_f32 v171, v164, v165
	global_store_dwordx2 v[226:227], v[170:171], off offset:128
	v_rcp_f32_e32 v148, v148
	s_nop 0
	v_mul_f32_e32 v148, 0xc1000000, v148
	v_mul_f32_e32 v144, v144, v148
	v_add_f32_e32 v168, v144, v144
	v_mul_f32_e32 v247, 0x3fb8aa3b, v168
	v_exp_f32_e32 v247, v247
	v_fma_f32 v148, v168, s14, 0.5
	v_fma_f32 v148, v168, v148, 1.0
	v_cmp_nlt_f32_e32 vcc, s51, v168
	v_mul_f32_e64 v148, v148, -v168
	v_sub_f32_e32 v247, 1.0, v247
	v_cndmask_b32_e32 v148, v148, v247, vcc
	v_add_f32_e32 v149, v5, v149
	v_mul_f32_e32 v149, 0xbfb8aa3b, v149
	v_exp_f32_e32 v149, v149
	s_nop 0
	v_add_f32_e32 v149, 1.0, v149
	v_rcp_f32_e32 v149, v149
	s_nop 0
	v_mul_f32_e32 v149, 0xc1000000, v149
	v_mul_f32_e32 v145, v145, v149
	v_add_f32_e32 v149, v145, v145
	v_mul_f32_e32 v247, 0x3fb8aa3b, v149
	v_exp_f32_e32 v247, v247
	v_fma_f32 v168, v149, s14, 0.5
	v_fma_f32 v168, v149, v168, 1.0
	v_cmp_nlt_f32_e32 vcc, s51, v149
	v_mul_f32_e64 v168, v168, -v149
	v_sub_f32_e32 v247, 1.0, v247
	v_cndmask_b32_e32 v168, v168, v247, vcc
	v_add_f32_e32 v149, v6, v150
	v_mul_f32_e32 v149, 0xbfb8aa3b, v149
	v_exp_f32_e32 v149, v149
	s_nop 0
	v_add_f32_e32 v149, 1.0, v149
	v_rcp_f32_e32 v149, v149
	s_nop 0
	v_mul_f32_e32 v149, 0xc1000000, v149
	v_mul_f32_e32 v146, v146, v149
	v_add_f32_e32 v149, v146, v146
	v_mul_f32_e32 v247, 0x3fb8aa3b, v149
	v_exp_f32_e32 v247, v247
	v_fma_f32 v150, v149, s14, 0.5
	v_fma_f32 v150, v149, v150, 1.0
	v_cmp_nlt_f32_e32 vcc, s51, v149
	v_mul_f32_e64 v150, v150, -v149
	v_sub_f32_e32 v247, 1.0, v247
	v_cndmask_b32_e32 v150, v150, v247, vcc
	v_add_f32_e32 v149, v7, v151
	v_mul_f32_e32 v149, 0xbfb8aa3b, v149
	v_exp_f32_e32 v149, v149
	s_nop 0
	v_add_f32_e32 v149, 1.0, v149
	v_rcp_f32_e32 v149, v149
	s_nop 0
	v_mul_f32_e32 v149, 0xc1000000, v149
	v_mul_f32_e32 v147, v147, v149
	v_add_f32_e32 v151, v147, v147
	v_mul_f32_e32 v247, 0x3fb8aa3b, v151
	v_exp_f32_e32 v247, v247
	v_fma_f32 v149, v151, s14, 0.5
	v_fma_f32 v149, v151, v149, 1.0
	v_cmp_nlt_f32_e32 vcc, s51, v151
	v_mul_f32_e64 v149, v149, -v151
	v_sub_f32_e32 v247, 1.0, v247
	v_cndmask_b32_e32 v149, v149, v247, vcc
	v_add_f32_e32 v143, v3, v143
	v_mul_f32_e32 v143, 0xbfb8aa3b, v143
	v_exp_f32_e32 v143, v143
	v_add_f32_e32 v142, v2, v142
	v_mul_f32_e32 v142, 0xbfb8aa3b, v142
	v_exp_f32_e32 v142, v142
	v_add_f32_e32 v143, 1.0, v143
	v_add_f32_e32 v142, 1.0, v142
	v_add_f32_e32 v141, v1, v141
	v_mul_f32_e32 v141, 0xbfb8aa3b, v141
	v_exp_f32_e32 v141, v141
	v_max_f32_e32 v150, 0, v150
	v_add_f32_e32 v141, 1.0, v141
	v_cmp_gt_f32_e32 vcc, s53, v150
	v_rcp_f32_e32 v142, v142
	v_add_f32_e32 v140, v0, v140
	v_cndmask_b32_e64 v164, 0, 32, vcc
	v_ldexp_f32 v150, v150, v164
	v_cndmask_b32_e64 v164, 0, -16, vcc
	v_rcp_f32_e32 v141, v141
	v_max_f32_e32 v165, 0, v168
	v_sqrt_f32_e32 v150, v150
	v_mul_f32_e32 v140, 0xbfb8aa3b, v140
	v_sqrt_f32_e32 v165, v165
	v_exp_f32_e32 v140, v140
	v_ldexp_f32 v150, v150, v164
	v_rcp_f32_e32 v143, v143
	v_lshlrev_b32_e32 v151, 16, v189
	v_mul_f32_e32 v142, v142, v150
	v_mul_f32_e32 v142, v142, v151
	v_and_b32_e32 v151, 0xffff0000, v188
	v_mul_f32_e32 v141, v141, v165
	v_add_f32_e32 v140, 1.0, v140
	v_mul_f32_e32 v151, v141, v151
	v_lshlrev_b32_e32 v150, 16, v188
	v_and_b32_e32 v164, 0xffff0000, v189
	s_mov_b64 s[0:1], 0
	v_rcp_f32_e32 v140, v140
	v_max_f32_e32 v141, 0, v148
	v_sqrt_f32_e32 v141, v141
	s_nop 0
	v_mul_f32_e32 v140, v140, v141
	v_mul_f32_e32 v148, v140, v150
	v_max_f32_e32 v140, 0, v149
	v_sqrt_f32_e32 v140, v140
	s_nop 0
	v_mul_f32_e32 v140, v143, v140
	v_mul_f32_e32 v143, v140, v164
	v_cvt_pk_bf16_f32 v140, v144, v145
	v_cvt_pk_bf16_f32 v141, v146, v147
	global_store_dwordx2 v[228:229], v[140:141], off offset:128
	v_cvt_pk_bf16_f32 v140, v148, v151
	v_cvt_pk_bf16_f32 v141, v142, v143
	global_store_dwordx2 v[230:231], v[140:141], off offset:128
.LBB0_712:
	s_and_b64 vcc, exec, s[0:1]
	s_cbranch_vccz .LBB0_447
	v_readlane_b32 s0, v253, 45
	v_readlane_b32 s1, v253, 46
	s_nop 1
	v_lshl_add_u64 v[140:141], v[180:181], 1, s[0:1]
	v_lshl_add_u64 v[142:143], v[140:141], 0, v[178:179]
	v_lshl_add_u64 v[146:147], v[140:141], 0, v[176:177]
	global_load_dwordx2 v[144:145], v[142:143], off
	s_nop 0
	global_load_dwordx2 v[142:143], v[146:147], off
	s_and_saveexec_b64 s[0:1], s[4:5]
	s_xor_b64 s[0:1], exec, s[0:1]
	v_mul_f32_e32 v146, 0x3fb8aa3b, v183
	v_exp_f32_e32 v146, v146
	s_nop 0
	v_sub_f32_e32 v146, 1.0, v146
	s_andn2_saveexec_b64 s[0:1], s[0:1]
	v_fma_f32 v146, v183, s14, 0.5
	v_fma_f32 v146, v183, v146, 1.0
	v_mul_f32_e64 v146, v146, -v183
	s_or_b64 exec, exec, s[0:1]
	v_add_f32_e32 v137, v137, v89
	v_mul_f32_e32 v137, 0xbfb8aa3b, v137
	v_exp_f32_e32 v137, v137
	s_nop 0
	v_add_f32_e32 v137, 1.0, v137
	v_rcp_f32_e32 v137, v137
	s_nop 0
	v_mul_f32_e32 v137, 0xc1000000, v137
	v_mul_f32_e32 v137, v85, v137
	v_add_f32_e32 v148, v137, v137
	v_mul_f32_e32 v247, 0x3fb8aa3b, v148
	v_exp_f32_e32 v247, v247
	v_fma_f32 v147, v148, s14, 0.5
	v_fma_f32 v147, v148, v147, 1.0
	v_cmp_nlt_f32_e32 vcc, s51, v148
	v_mul_f32_e64 v147, v147, -v148
	v_sub_f32_e32 v247, 1.0, v247
	v_cndmask_b32_e32 v147, v147, v247, vcc
	v_add_f32_e32 v138, v138, v90
	v_mul_f32_e32 v138, 0xbfb8aa3b, v138
	v_exp_f32_e32 v138, v138
	s_nop 0
	v_add_f32_e32 v138, 1.0, v138
	v_rcp_f32_e32 v138, v138
	s_nop 0
	v_mul_f32_e32 v138, 0xc1000000, v138
	v_mul_f32_e32 v138, v86, v138
	v_add_f32_e32 v148, v138, v138
	v_mul_f32_e32 v247, 0x3fb8aa3b, v148
	v_exp_f32_e32 v247, v247
	v_fma_f32 v149, v148, s14, 0.5
	v_fma_f32 v149, v148, v149, 1.0
	v_cmp_nlt_f32_e32 vcc, s51, v148
	v_mul_f32_e64 v149, v149, -v148
	v_sub_f32_e32 v247, 1.0, v247
	v_cndmask_b32_e32 v149, v149, v247, vcc
	v_add_f32_e32 v139, v139, v91
	v_mul_f32_e32 v139, 0xbfb8aa3b, v139
	v_exp_f32_e32 v139, v139
	s_nop 0
	v_add_f32_e32 v139, 1.0, v139
	v_rcp_f32_e32 v139, v139
	s_nop 0
	v_mul_f32_e32 v139, 0xc1000000, v139
	v_mul_f32_e32 v139, v87, v139
	v_add_f32_e32 v150, v139, v139
	v_mul_f32_e32 v247, 0x3fb8aa3b, v150
	v_exp_f32_e32 v247, v247
	v_fma_f32 v148, v150, s14, 0.5
	v_fma_f32 v148, v150, v148, 1.0
	v_cmp_nlt_f32_e32 vcc, s51, v150
	v_mul_f32_e64 v148, v148, -v150
	v_sub_f32_e32 v247, 1.0, v247
	v_cndmask_b32_e32 v148, v148, v247, vcc
	v_add_f32_e32 v134, v134, v78
	v_mul_f32_e32 v134, 0xbfb8aa3b, v134
	v_exp_f32_e32 v134, v134
	v_max_f32_e32 v149, 0, v149
	v_add_f32_e32 v133, v133, v77
	v_add_f32_e32 v134, 1.0, v134
	v_mul_f32_e32 v133, 0xbfb8aa3b, v133
	v_exp_f32_e32 v133, v133
	v_rcp_f32_e32 v134, v134
	s_waitcnt vmcnt(0)
	v_lshlrev_b32_e32 v150, 16, v145
	v_sqrt_f32_e32 v149, v149
	v_add_f32_e32 v133, 1.0, v133
	v_max_f32_e32 v147, 0, v147
	v_mul_f32_e32 v134, v134, v149
	v_mul_f32_e32 v149, v134, v150
	v_add_f32_e32 v134, v135, v79
	v_mul_f32_e32 v134, 0xbfb8aa3b, v134
	v_exp_f32_e32 v134, v134
	v_add_f32_e32 v128, v128, v88
	v_mul_f32_e32 v128, 0xbfb8aa3b, v128
	v_exp_f32_e32 v128, v128
	v_add_f32_e32 v134, 1.0, v134
	v_add_f32_e32 v128, 1.0, v128
	v_rcp_f32_e32 v134, v134
	s_lshl_b32 s0, s7, 21
	v_readlane_b32 s1, v251, 24
	s_add_u32 s4, s1, s0
	v_rcp_f32_e32 v133, v133
	v_and_b32_e32 v135, 0xffff0000, v144
	v_sqrt_f32_e32 v147, v147
	v_readlane_b32 s1, v251, 25
	s_addc_u32 s5, s1, 0
	v_mul_f32_e32 v133, v133, v147
	v_mul_f32_e32 v147, v133, v135
	v_max_f32_e32 v135, 0, v146
	v_lshlrev_b32_e32 v133, 16, v144
	v_readlane_b32 s1, v251, 26
	v_sqrt_f32_e32 v135, v135
	s_add_u32 s0, s1, s0
	v_readlane_b32 s1, v251, 27
	v_mul_f32_e32 v135, v136, v135
	v_mul_f32_e32 v144, v135, v133
	v_max_f32_e32 v135, 0, v148
	v_and_b32_e32 v133, 0xffff0000, v145
	s_addc_u32 s1, s1, 0
	v_sqrt_f32_e32 v135, v135
	s_nop 0
	v_mul_f32_e32 v134, v134, v135
	v_mul_f32_e32 v145, v134, v133
	v_lshl_add_u64 v[134:135], v[186:187], 0, v[180:181]
	v_lshlrev_b64 v[134:135], 1, v[134:135]
	v_cvt_pk_bf16_f32 v136, v132, v137
	v_lshl_add_u64 v[132:133], s[4:5], 0, v[134:135]
	v_cvt_pk_bf16_f32 v137, v138, v139
	global_store_dwordx2 v[132:133], v[136:137], off
	v_cvt_pk_bf16_f32 v136, v144, v147
	v_lshl_add_u64 v[134:135], s[0:1], 0, v[134:135]
	v_cvt_pk_bf16_f32 v137, v149, v145
	global_store_dwordx2 v[134:135], v[136:137], off
	v_rcp_f32_e32 v128, v128
	s_nop 0
	v_mul_f32_e32 v128, 0xc1000000, v128
	v_mul_f32_e32 v128, v84, v128
	v_add_f32_e32 v137, v128, v128
	v_mul_f32_e32 v247, 0x3fb8aa3b, v137
	v_exp_f32_e32 v247, v247
	v_fma_f32 v136, v137, s14, 0.5
	v_fma_f32 v136, v137, v136, 1.0
	v_cmp_nlt_f32_e32 vcc, s51, v137
	v_mul_f32_e64 v136, v136, -v137
	v_sub_f32_e32 v247, 1.0, v247
	v_cndmask_b32_e32 v136, v136, v247, vcc
	v_add_f32_e32 v129, v129, v89
	v_mul_f32_e32 v129, 0xbfb8aa3b, v129
	v_exp_f32_e32 v129, v129
	s_nop 0
	v_add_f32_e32 v129, 1.0, v129
	v_rcp_f32_e32 v129, v129
	s_nop 0
	v_mul_f32_e32 v129, 0xc1000000, v129
	v_mul_f32_e32 v129, v85, v129
	v_add_f32_e32 v137, v129, v129
	v_mul_f32_e32 v247, 0x3fb8aa3b, v137
	v_exp_f32_e32 v247, v247
	v_fma_f32 v138, v137, s14, 0.5
	v_fma_f32 v138, v137, v138, 1.0
	v_cmp_nlt_f32_e32 vcc, s51, v137
	v_mul_f32_e64 v138, v138, -v137
	v_sub_f32_e32 v247, 1.0, v247
	v_cndmask_b32_e32 v138, v138, v247, vcc
	v_add_f32_e32 v130, v130, v90
	v_mul_f32_e32 v130, 0xbfb8aa3b, v130
	v_exp_f32_e32 v130, v130
	s_nop 0
	v_add_f32_e32 v130, 1.0, v130
	v_rcp_f32_e32 v130, v130
	s_nop 0
	v_mul_f32_e32 v130, 0xc1000000, v130
	v_mul_f32_e32 v130, v86, v130
	v_add_f32_e32 v137, v130, v130
	v_mul_f32_e32 v247, 0x3fb8aa3b, v137
	v_exp_f32_e32 v247, v247
	v_fma_f32 v139, v137, s14, 0.5
	v_fma_f32 v139, v137, v139, 1.0
	v_cmp_nlt_f32_e32 vcc, s51, v137
	v_mul_f32_e64 v139, v139, -v137
	v_sub_f32_e32 v247, 1.0, v247
	v_cndmask_b32_e32 v139, v139, v247, vcc
	v_add_f32_e32 v131, v131, v91
	v_mul_f32_e32 v131, 0xbfb8aa3b, v131
	v_exp_f32_e32 v131, v131
	s_nop 0
	v_add_f32_e32 v131, 1.0, v131
	v_rcp_f32_e32 v131, v131
	s_nop 0
	v_mul_f32_e32 v131, 0xc1000000, v131
	v_mul_f32_e32 v131, v87, v131
	v_add_f32_e32 v144, v131, v131
	v_mul_f32_e32 v247, 0x3fb8aa3b, v144
	v_exp_f32_e32 v247, v247
	v_fma_f32 v137, v144, s14, 0.5
	v_fma_f32 v137, v144, v137, 1.0
	v_cmp_nlt_f32_e32 vcc, s51, v144
	v_mul_f32_e64 v137, v137, -v144
	v_sub_f32_e32 v247, 1.0, v247
	v_cndmask_b32_e32 v137, v137, v247, vcc
	v_add_f32_e32 v126, v126, v78
	v_mul_f32_e32 v126, 0xbfb8aa3b, v126
	v_exp_f32_e32 v126, v126
	v_max_f32_e32 v139, 0, v139
	v_add_f32_e32 v125, v125, v77
	v_add_f32_e32 v126, 1.0, v126
	v_mul_f32_e32 v125, 0xbfb8aa3b, v125
	v_exp_f32_e32 v125, v125
	v_rcp_f32_e32 v126, v126
	v_lshlrev_b32_e32 v144, 16, v143
	v_sqrt_f32_e32 v139, v139
	v_add_f32_e32 v125, 1.0, v125
	v_max_f32_e32 v138, 0, v138
	v_mul_f32_e32 v126, v126, v139
	v_mul_f32_e32 v139, v126, v144
	v_add_f32_e32 v126, v127, v79
	v_mul_f32_e32 v126, 0xbfb8aa3b, v126
	v_exp_f32_e32 v126, v126
	v_add_f32_e32 v124, v124, v76
	v_mul_f32_e32 v124, 0xbfb8aa3b, v124
	v_exp_f32_e32 v124, v124
	v_add_f32_e32 v126, 1.0, v126
	v_add_f32_e32 v124, 1.0, v124
	v_max_f32_e32 v137, 0, v137
	v_rcp_f32_e32 v126, v126
	v_add_f32_e32 v120, v120, v88
	v_mul_f32_e32 v120, 0xbfb8aa3b, v120
	v_exp_f32_e32 v120, v120
	v_rcp_f32_e32 v125, v125
	v_and_b32_e32 v127, 0xffff0000, v142
	v_sqrt_f32_e32 v138, v138
	v_add_f32_e32 v120, 1.0, v120
	v_mul_f32_e32 v125, v125, v138
	v_mul_f32_e32 v138, v125, v127
	v_lshlrev_b32_e32 v125, 16, v142
	v_rcp_f32_e32 v124, v124
	v_max_f32_e32 v127, 0, v136
	v_cmp_gt_f32_e32 vcc, s53, v127
	s_nop 0
	s_nop 0
	v_cndmask_b32_e64 v136, 0, 32, vcc
	v_ldexp_f32 v127, v127, v136
	v_cndmask_b32_e64 v136, 0, -16, vcc
	v_sqrt_f32_e32 v127, v127
	v_sqrt_f32_e32 v137, v137
	v_ldexp_f32 v127, v127, v136
	v_mul_f32_e32 v124, v124, v127
	v_mul_f32_e32 v136, v124, v125
	v_lshlrev_b64 v[124:125], 10, v[184:185]
	v_and_b32_e32 v127, 0xffff0000, v143
	v_mul_f32_e32 v126, v126, v137
	v_lshl_add_u64 v[124:125], v[124:125], 0, v[180:181]
	v_mul_f32_e32 v137, v126, v127
	v_cvt_pk_bf16_f32 v126, v128, v129
	v_lshlrev_b64 v[128:129], 1, v[124:125]
	v_or_b32_e32 v142, 32, v182
	v_cvt_pk_bf16_f32 v127, v130, v131
	v_lshl_add_u64 v[124:125], s[4:5], 0, v[128:129]
	v_ashrrev_i32_e32 v143, 31, v142
	global_store_dwordx2 v[124:125], v[126:127], off
	v_cvt_pk_bf16_f32 v130, v136, v138
	v_cvt_pk_bf16_f32 v131, v139, v137
	v_lshl_add_u64 v[126:127], s[0:1], 0, v[128:129]
	v_lshlrev_b64 v[128:129], 11, v[142:143]
	v_or_b32_e32 v136, 48, v182
	global_store_dwordx2 v[126:127], v[130:131], off
	v_lshl_add_u64 v[130:131], v[140:141], 0, v[128:129]
	v_ashrrev_i32_e32 v137, 31, v136
	global_load_dwordx2 v[144:145], v[130:131], off
	v_lshlrev_b64 v[130:131], 11, v[136:137]
	v_lshl_add_u64 v[138:139], v[140:141], 0, v[130:131]
	global_load_dwordx2 v[138:139], v[138:139], off
	v_rcp_f32_e32 v120, v120
	s_nop 0
	v_mul_f32_e32 v120, 0xc1000000, v120
	v_mul_f32_e32 v120, v84, v120
	v_add_f32_e32 v147, v120, v120
	v_mul_f32_e32 v247, 0x3fb8aa3b, v147
	v_exp_f32_e32 v247, v247
	v_fma_f32 v146, v147, s14, 0.5
	v_fma_f32 v146, v147, v146, 1.0
	v_cmp_nlt_f32_e32 vcc, s51, v147
	v_mul_f32_e64 v146, v146, -v147
	v_sub_f32_e32 v247, 1.0, v247
	v_cndmask_b32_e32 v146, v146, v247, vcc
	v_add_f32_e32 v121, v121, v89
	v_mul_f32_e32 v121, 0xbfb8aa3b, v121
	v_exp_f32_e32 v121, v121
	s_nop 0
	v_add_f32_e32 v121, 1.0, v121
	v_rcp_f32_e32 v121, v121
	s_nop 0
	v_mul_f32_e32 v121, 0xc1000000, v121
	v_mul_f32_e32 v121, v85, v121
	v_add_f32_e32 v147, v121, v121
	v_mul_f32_e32 v247, 0x3fb8aa3b, v147
	v_exp_f32_e32 v247, v247
	v_fma_f32 v148, v147, s14, 0.5
	v_fma_f32 v148, v147, v148, 1.0
	v_cmp_nlt_f32_e32 vcc, s51, v147
	v_mul_f32_e64 v148, v148, -v147
	v_sub_f32_e32 v247, 1.0, v247
	v_cndmask_b32_e32 v148, v148, v247, vcc
	v_add_f32_e32 v122, v122, v90
	v_mul_f32_e32 v122, 0xbfb8aa3b, v122
	v_exp_f32_e32 v122, v122
	s_nop 0
	v_add_f32_e32 v122, 1.0, v122
	v_rcp_f32_e32 v122, v122
	s_nop 0
	v_mul_f32_e32 v122, 0xc1000000, v122
	v_mul_f32_e32 v122, v86, v122
	v_add_f32_e32 v147, v122, v122
	v_mul_f32_e32 v247, 0x3fb8aa3b, v147
	v_exp_f32_e32 v247, v247
	v_fma_f32 v149, v147, s14, 0.5
	v_fma_f32 v149, v147, v149, 1.0
	v_cmp_nlt_f32_e32 vcc, s51, v147
	v_mul_f32_e64 v149, v149, -v147
	v_sub_f32_e32 v247, 1.0, v247
	v_cndmask_b32_e32 v149, v149, v247, vcc
	v_add_f32_e32 v123, v123, v91
	v_mul_f32_e32 v123, 0xbfb8aa3b, v123
	v_exp_f32_e32 v123, v123
	s_nop 0
	v_add_f32_e32 v123, 1.0, v123
	v_rcp_f32_e32 v123, v123
	s_nop 0
	v_mul_f32_e32 v123, 0xc1000000, v123
	v_mul_f32_e32 v123, v87, v123
	v_add_f32_e32 v150, v123, v123
	v_mul_f32_e32 v247, 0x3fb8aa3b, v150
	v_exp_f32_e32 v247, v247
	v_fma_f32 v147, v150, s14, 0.5
	v_fma_f32 v147, v150, v147, 1.0
	v_cmp_nlt_f32_e32 vcc, s51, v150
	v_mul_f32_e64 v147, v147, -v150
	v_sub_f32_e32 v247, 1.0, v247
	v_cndmask_b32_e32 v147, v147, v247, vcc
	v_add_f32_e32 v118, v118, v78
	v_mul_f32_e32 v118, 0xbfb8aa3b, v118
	v_exp_f32_e32 v118, v118
	v_max_f32_e32 v149, 0, v149
	v_add_f32_e32 v117, v117, v77
	v_add_f32_e32 v118, 1.0, v118
	v_mul_f32_e32 v117, 0xbfb8aa3b, v117
	v_exp_f32_e32 v117, v117
	v_rcp_f32_e32 v118, v118
	s_waitcnt vmcnt(0)
	v_lshlrev_b32_e32 v150, 16, v145
	v_sqrt_f32_e32 v149, v149
	v_add_f32_e32 v117, 1.0, v117
	v_max_f32_e32 v148, 0, v148
	v_mul_f32_e32 v118, v118, v149
	v_mul_f32_e32 v149, v118, v150
	v_add_f32_e32 v118, v119, v79
	v_mul_f32_e32 v118, 0xbfb8aa3b, v118
	v_exp_f32_e32 v118, v118
	v_add_f32_e32 v116, v116, v76
	v_mul_f32_e32 v116, 0xbfb8aa3b, v116
	v_exp_f32_e32 v116, v116
	v_add_f32_e32 v118, 1.0, v118
	v_add_f32_e32 v116, 1.0, v116
	v_add_f32_e32 v112, v112, v88
	v_mul_f32_e32 v112, 0xbfb8aa3b, v112
	v_rcp_f32_e32 v118, v118
	v_exp_f32_e32 v112, v112
	v_rcp_f32_e32 v117, v117
	v_and_b32_e32 v119, 0xffff0000, v144
	v_sqrt_f32_e32 v148, v148
	v_add_f32_e32 v112, 1.0, v112
	v_mul_f32_e32 v117, v117, v148
	v_mul_f32_e32 v148, v117, v119
	v_lshlrev_b32_e32 v117, 16, v144
	v_rcp_f32_e32 v116, v116
	v_max_f32_e32 v119, 0, v146
	v_sqrt_f32_e32 v119, v119
	s_nop 0
	v_mul_f32_e32 v116, v116, v119
	v_mul_f32_e32 v144, v116, v117
	v_lshlrev_b64 v[116:117], 10, v[142:143]
	v_max_f32_e32 v142, 0, v147
	v_and_b32_e32 v119, 0xffff0000, v145
	v_lshl_add_u64 v[116:117], v[116:117], 0, v[180:181]
	v_sqrt_f32_e32 v142, v142
	s_nop 0
	v_mul_f32_e32 v118, v118, v142
	v_mul_f32_e32 v142, v118, v119
	v_cvt_pk_bf16_f32 v118, v120, v121
	v_lshlrev_b64 v[120:121], 1, v[116:117]
	v_cvt_pk_bf16_f32 v119, v122, v123
	v_lshl_add_u64 v[116:117], s[4:5], 0, v[120:121]
	global_store_dwordx2 v[116:117], v[118:119], off
	v_lshl_add_u64 v[118:119], s[0:1], 0, v[120:121]
	v_cvt_pk_bf16_f32 v122, v144, v148
	v_cvt_pk_bf16_f32 v123, v149, v142
	global_store_dwordx2 v[118:119], v[122:123], off
	v_rcp_f32_e32 v112, v112
	s_nop 0
	v_mul_f32_e32 v112, 0xc1000000, v112
	v_mul_f32_e32 v112, v84, v112
	v_add_f32_e32 v121, v112, v112
	v_mul_f32_e32 v247, 0x3fb8aa3b, v121
	v_exp_f32_e32 v247, v247
	v_fma_f32 v120, v121, s14, 0.5
	v_fma_f32 v120, v121, v120, 1.0
	v_cmp_nlt_f32_e32 vcc, s51, v121
	v_mul_f32_e64 v120, v120, -v121
	v_sub_f32_e32 v247, 1.0, v247
	v_cndmask_b32_e32 v120, v120, v247, vcc
	v_add_f32_e32 v113, v113, v89
	v_mul_f32_e32 v113, 0xbfb8aa3b, v113
	v_exp_f32_e32 v113, v113
	s_nop 0
	v_add_f32_e32 v113, 1.0, v113
	v_rcp_f32_e32 v113, v113
	s_nop 0
	v_mul_f32_e32 v113, 0xc1000000, v113
	v_mul_f32_e32 v113, v85, v113
	v_add_f32_e32 v121, v113, v113
	v_mul_f32_e32 v247, 0x3fb8aa3b, v121
	v_exp_f32_e32 v247, v247
	v_fma_f32 v122, v121, s14, 0.5
	v_fma_f32 v122, v121, v122, 1.0
	v_cmp_nlt_f32_e32 vcc, s51, v121
	v_mul_f32_e64 v122, v122, -v121
	v_sub_f32_e32 v247, 1.0, v247
	v_cndmask_b32_e32 v122, v122, v247, vcc
	v_add_f32_e32 v114, v114, v90
	v_mul_f32_e32 v114, 0xbfb8aa3b, v114
	v_exp_f32_e32 v114, v114
	s_nop 0
	v_add_f32_e32 v114, 1.0, v114
	v_rcp_f32_e32 v114, v114
	s_nop 0
	v_mul_f32_e32 v114, 0xc1000000, v114
	v_mul_f32_e32 v114, v86, v114
	v_add_f32_e32 v121, v114, v114
	v_mul_f32_e32 v247, 0x3fb8aa3b, v121
	v_exp_f32_e32 v247, v247
	v_fma_f32 v123, v121, s14, 0.5
	v_fma_f32 v123, v121, v123, 1.0
	v_cmp_nlt_f32_e32 vcc, s51, v121
	v_mul_f32_e64 v123, v123, -v121
	v_sub_f32_e32 v247, 1.0, v247
	v_cndmask_b32_e32 v123, v123, v247, vcc
	v_add_f32_e32 v115, v115, v91
	v_mul_f32_e32 v115, 0xbfb8aa3b, v115
	v_exp_f32_e32 v115, v115
	s_nop 0
	v_add_f32_e32 v115, 1.0, v115
	v_rcp_f32_e32 v115, v115
	s_nop 0
	v_mul_f32_e32 v115, 0xc1000000, v115
	v_mul_f32_e32 v115, v87, v115
	v_add_f32_e32 v142, v115, v115
	v_mul_f32_e32 v247, 0x3fb8aa3b, v142
	v_exp_f32_e32 v247, v247
	v_fma_f32 v121, v142, s14, 0.5
	v_fma_f32 v121, v142, v121, 1.0
	v_cmp_nlt_f32_e32 vcc, s51, v142
	v_mul_f32_e64 v121, v121, -v142
	v_sub_f32_e32 v247, 1.0, v247
	v_cndmask_b32_e32 v121, v121, v247, vcc
	v_add_f32_e32 v110, v110, v78
	v_mul_f32_e32 v110, 0xbfb8aa3b, v110
	v_exp_f32_e32 v110, v110
	v_max_f32_e32 v123, 0, v123
	v_add_f32_e32 v109, v109, v77
	v_add_f32_e32 v110, 1.0, v110
	v_mul_f32_e32 v109, 0xbfb8aa3b, v109
	v_exp_f32_e32 v109, v109
	v_rcp_f32_e32 v110, v110
	v_lshlrev_b32_e32 v142, 16, v139
	v_sqrt_f32_e32 v123, v123
	v_add_f32_e32 v109, 1.0, v109
	v_max_f32_e32 v122, 0, v122
	v_mul_f32_e32 v110, v110, v123
	v_mul_f32_e32 v123, v110, v142
	v_add_f32_e32 v110, v111, v79
	v_mul_f32_e32 v110, 0xbfb8aa3b, v110
	v_exp_f32_e32 v110, v110
	v_add_f32_e32 v108, v108, v76
	v_mul_f32_e32 v108, 0xbfb8aa3b, v108
	v_exp_f32_e32 v108, v108
	v_add_f32_e32 v110, 1.0, v110
	v_add_f32_e32 v108, 1.0, v108
	v_max_f32_e32 v121, 0, v121
	v_rcp_f32_e32 v110, v110
	v_add_f32_e32 v104, v104, v88
	v_mul_f32_e32 v104, 0xbfb8aa3b, v104
	v_exp_f32_e32 v104, v104
	v_rcp_f32_e32 v109, v109
	v_and_b32_e32 v111, 0xffff0000, v138
	v_sqrt_f32_e32 v122, v122
	v_add_f32_e32 v104, 1.0, v104
	v_mul_f32_e32 v109, v109, v122
	v_mul_f32_e32 v122, v109, v111
	v_lshlrev_b32_e32 v109, 16, v138
	v_rcp_f32_e32 v108, v108
	v_max_f32_e32 v111, 0, v120
	v_sqrt_f32_e32 v111, v111
	s_nop 0
	v_mul_f32_e32 v108, v108, v111
	v_mul_f32_e32 v120, v108, v109
	v_lshlrev_b64 v[108:109], 10, v[136:137]
	v_sqrt_f32_e32 v121, v121
	v_and_b32_e32 v111, 0xffff0000, v139
	v_lshl_add_u64 v[108:109], v[108:109], 0, v[180:181]
	v_mul_f32_e32 v110, v110, v121
	v_mul_f32_e32 v121, v110, v111
	v_cvt_pk_bf16_f32 v110, v112, v113
	v_lshlrev_b64 v[112:113], 1, v[108:109]
	v_add_u32_e32 v136, 0x80, v182
	v_cvt_pk_bf16_f32 v111, v114, v115
	v_lshl_add_u64 v[108:109], s[4:5], 0, v[112:113]
	v_ashrrev_i32_e32 v137, 31, v136
	global_store_dwordx2 v[108:109], v[110:111], off
	v_cvt_pk_bf16_f32 v114, v120, v122
	v_cvt_pk_bf16_f32 v115, v123, v121
	v_lshl_add_u64 v[110:111], s[0:1], 0, v[112:113]
	v_lshlrev_b64 v[112:113], 11, v[136:137]
	v_add_u32_e32 v120, 0x90, v182
	global_store_dwordx2 v[110:111], v[114:115], off
	v_lshl_add_u64 v[114:115], v[140:141], 0, v[112:113]
	v_ashrrev_i32_e32 v121, 31, v120
	global_load_dwordx2 v[138:139], v[114:115], off
	v_lshlrev_b64 v[114:115], 11, v[120:121]
	v_lshl_add_u64 v[122:123], v[140:141], 0, v[114:115]
	global_load_dwordx2 v[122:123], v[122:123], off
	v_rcp_f32_e32 v104, v104
	s_nop 0
	v_mul_f32_e32 v104, 0xc1000000, v104
	v_mul_f32_e32 v104, v84, v104
	v_add_f32_e32 v143, v104, v104
	v_mul_f32_e32 v247, 0x3fb8aa3b, v143
	v_exp_f32_e32 v247, v247
	v_fma_f32 v142, v143, s14, 0.5
	v_fma_f32 v142, v143, v142, 1.0
	v_cmp_nlt_f32_e32 vcc, s51, v143
	v_mul_f32_e64 v142, v142, -v143
	v_sub_f32_e32 v247, 1.0, v247
	v_cndmask_b32_e32 v142, v142, v247, vcc
	v_add_f32_e32 v105, v105, v89
	v_mul_f32_e32 v105, 0xbfb8aa3b, v105
	v_exp_f32_e32 v105, v105
	s_nop 0
	v_add_f32_e32 v105, 1.0, v105
	v_rcp_f32_e32 v105, v105
	s_nop 0
	v_mul_f32_e32 v105, 0xc1000000, v105
	v_mul_f32_e32 v105, v85, v105
	v_add_f32_e32 v143, v105, v105
	v_mul_f32_e32 v247, 0x3fb8aa3b, v143
	v_exp_f32_e32 v247, v247
	v_fma_f32 v144, v143, s14, 0.5
	v_fma_f32 v144, v143, v144, 1.0
	v_cmp_nlt_f32_e32 vcc, s51, v143
	v_mul_f32_e64 v144, v144, -v143
	v_sub_f32_e32 v247, 1.0, v247
	v_cndmask_b32_e32 v144, v144, v247, vcc
	v_add_f32_e32 v106, v106, v90
	v_mul_f32_e32 v106, 0xbfb8aa3b, v106
	v_exp_f32_e32 v106, v106
	s_nop 0
	v_add_f32_e32 v106, 1.0, v106
	v_rcp_f32_e32 v106, v106
	s_nop 0
	v_mul_f32_e32 v106, 0xc1000000, v106
	v_mul_f32_e32 v106, v86, v106
	v_add_f32_e32 v143, v106, v106
	v_mul_f32_e32 v247, 0x3fb8aa3b, v143
	v_exp_f32_e32 v247, v247
	v_fma_f32 v145, v143, s14, 0.5
	v_fma_f32 v145, v143, v145, 1.0
	v_cmp_nlt_f32_e32 vcc, s51, v143
	v_mul_f32_e64 v145, v145, -v143
	v_sub_f32_e32 v247, 1.0, v247
	v_cndmask_b32_e32 v145, v145, v247, vcc
	v_add_f32_e32 v107, v107, v91
	v_mul_f32_e32 v107, 0xbfb8aa3b, v107
	v_exp_f32_e32 v107, v107
	s_nop 0
	v_add_f32_e32 v107, 1.0, v107
	v_rcp_f32_e32 v107, v107
	s_nop 0
	v_mul_f32_e32 v107, 0xc1000000, v107
	v_mul_f32_e32 v107, v87, v107
	v_add_f32_e32 v146, v107, v107
	v_mul_f32_e32 v247, 0x3fb8aa3b, v146
	v_exp_f32_e32 v247, v247
	v_fma_f32 v143, v146, s14, 0.5
	v_fma_f32 v143, v146, v143, 1.0
	v_cmp_nlt_f32_e32 vcc, s51, v146
	v_mul_f32_e64 v143, v143, -v146
	v_sub_f32_e32 v247, 1.0, v247
	v_cndmask_b32_e32 v143, v143, v247, vcc
	v_add_f32_e32 v102, v102, v78
	v_mul_f32_e32 v102, 0xbfb8aa3b, v102
	v_exp_f32_e32 v102, v102
	v_max_f32_e32 v145, 0, v145
	v_add_f32_e32 v101, v101, v77
	v_add_f32_e32 v102, 1.0, v102
	v_mul_f32_e32 v101, 0xbfb8aa3b, v101
	v_exp_f32_e32 v101, v101
	v_rcp_f32_e32 v102, v102
	s_waitcnt vmcnt(0)
	v_lshlrev_b32_e32 v146, 16, v139
	v_sqrt_f32_e32 v145, v145
	v_add_f32_e32 v101, 1.0, v101
	v_max_f32_e32 v144, 0, v144
	v_mul_f32_e32 v102, v102, v145
	v_mul_f32_e32 v145, v102, v146
	v_add_f32_e32 v102, v103, v79
	v_mul_f32_e32 v102, 0xbfb8aa3b, v102
	v_exp_f32_e32 v102, v102
	v_add_f32_e32 v100, v100, v76
	v_mul_f32_e32 v100, 0xbfb8aa3b, v100
	v_exp_f32_e32 v100, v100
	v_add_f32_e32 v102, 1.0, v102
	v_add_f32_e32 v100, 1.0, v100
	v_add_f32_e32 v96, v96, v88
	v_mul_f32_e32 v96, 0xbfb8aa3b, v96
	v_rcp_f32_e32 v102, v102
	v_exp_f32_e32 v96, v96
	v_rcp_f32_e32 v101, v101
	v_and_b32_e32 v103, 0xffff0000, v138
	v_sqrt_f32_e32 v144, v144
	v_add_f32_e32 v96, 1.0, v96
	v_mul_f32_e32 v101, v101, v144
	v_mul_f32_e32 v144, v101, v103
	v_lshlrev_b32_e32 v101, 16, v138
	v_rcp_f32_e32 v100, v100
	v_max_f32_e32 v103, 0, v142
	v_sqrt_f32_e32 v103, v103
	s_nop 0
	v_mul_f32_e32 v100, v100, v103
	v_mul_f32_e32 v138, v100, v101
	v_lshlrev_b64 v[100:101], 10, v[136:137]
	v_max_f32_e32 v136, 0, v143
	v_and_b32_e32 v103, 0xffff0000, v139
	v_lshl_add_u64 v[100:101], v[100:101], 0, v[180:181]
	v_sqrt_f32_e32 v136, v136
	s_nop 0
	v_mul_f32_e32 v102, v102, v136
	v_mul_f32_e32 v136, v102, v103
	v_cvt_pk_bf16_f32 v102, v104, v105
	v_lshlrev_b64 v[104:105], 1, v[100:101]
	v_cvt_pk_bf16_f32 v103, v106, v107
	v_lshl_add_u64 v[100:101], s[4:5], 0, v[104:105]
	global_store_dwordx2 v[100:101], v[102:103], off
	v_lshl_add_u64 v[102:103], s[0:1], 0, v[104:105]
	v_cvt_pk_bf16_f32 v106, v138, v144
	v_cvt_pk_bf16_f32 v107, v145, v136
	global_store_dwordx2 v[102:103], v[106:107], off
	v_rcp_f32_e32 v96, v96
	s_nop 0
	v_mul_f32_e32 v96, 0xc1000000, v96
	v_mul_f32_e32 v96, v84, v96
	v_add_f32_e32 v105, v96, v96
	v_mul_f32_e32 v247, 0x3fb8aa3b, v105
	v_exp_f32_e32 v247, v247
	v_fma_f32 v104, v105, s14, 0.5
	v_fma_f32 v104, v105, v104, 1.0
	v_cmp_nlt_f32_e32 vcc, s51, v105
	v_mul_f32_e64 v104, v104, -v105
	v_sub_f32_e32 v247, 1.0, v247
	v_cndmask_b32_e32 v104, v104, v247, vcc
	v_add_f32_e32 v97, v97, v89
	v_mul_f32_e32 v97, 0xbfb8aa3b, v97
	v_exp_f32_e32 v97, v97
	s_nop 0
	v_add_f32_e32 v97, 1.0, v97
	v_rcp_f32_e32 v97, v97
	s_nop 0
	v_mul_f32_e32 v97, 0xc1000000, v97
	v_mul_f32_e32 v97, v85, v97
	v_add_f32_e32 v105, v97, v97
	v_mul_f32_e32 v247, 0x3fb8aa3b, v105
	v_exp_f32_e32 v247, v247
	v_fma_f32 v106, v105, s14, 0.5
	v_fma_f32 v106, v105, v106, 1.0
	v_cmp_nlt_f32_e32 vcc, s51, v105
	v_mul_f32_e64 v106, v106, -v105
	v_sub_f32_e32 v247, 1.0, v247
	v_cndmask_b32_e32 v106, v106, v247, vcc
	v_add_f32_e32 v98, v98, v90
	v_mul_f32_e32 v98, 0xbfb8aa3b, v98
	v_exp_f32_e32 v98, v98
	s_nop 0
	v_add_f32_e32 v98, 1.0, v98
	v_rcp_f32_e32 v98, v98
	s_nop 0
	v_mul_f32_e32 v98, 0xc1000000, v98
	v_mul_f32_e32 v98, v86, v98
	v_add_f32_e32 v105, v98, v98
	v_mul_f32_e32 v247, 0x3fb8aa3b, v105
	v_exp_f32_e32 v247, v247
	v_fma_f32 v107, v105, s14, 0.5
	v_fma_f32 v107, v105, v107, 1.0
	v_cmp_nlt_f32_e32 vcc, s51, v105
	v_mul_f32_e64 v107, v107, -v105
	v_sub_f32_e32 v247, 1.0, v247
	v_cndmask_b32_e32 v107, v107, v247, vcc
	v_add_f32_e32 v99, v99, v91
	v_mul_f32_e32 v99, 0xbfb8aa3b, v99
	v_exp_f32_e32 v99, v99
	s_nop 0
	v_add_f32_e32 v99, 1.0, v99
	v_rcp_f32_e32 v99, v99
	s_nop 0
	v_mul_f32_e32 v99, 0xc1000000, v99
	v_mul_f32_e32 v99, v87, v99
	v_add_f32_e32 v136, v99, v99
	v_mul_f32_e32 v247, 0x3fb8aa3b, v136
	v_exp_f32_e32 v247, v247
	v_fma_f32 v105, v136, s14, 0.5
	v_fma_f32 v105, v136, v105, 1.0
	v_cmp_nlt_f32_e32 vcc, s51, v136
	v_mul_f32_e64 v105, v105, -v136
	v_sub_f32_e32 v247, 1.0, v247
	v_cndmask_b32_e32 v105, v105, v247, vcc
	v_add_f32_e32 v94, v94, v78
	v_mul_f32_e32 v94, 0xbfb8aa3b, v94
	v_exp_f32_e32 v94, v94
	v_max_f32_e32 v107, 0, v107
	v_add_f32_e32 v93, v93, v77
	v_add_f32_e32 v94, 1.0, v94
	v_mul_f32_e32 v93, 0xbfb8aa3b, v93
	v_exp_f32_e32 v93, v93
	v_rcp_f32_e32 v94, v94
	v_lshlrev_b32_e32 v136, 16, v123
	v_sqrt_f32_e32 v107, v107
	v_add_f32_e32 v93, 1.0, v93
	v_max_f32_e32 v106, 0, v106
	v_mul_f32_e32 v94, v94, v107
	v_mul_f32_e32 v107, v94, v136
	v_add_f32_e32 v94, v95, v79
	v_mul_f32_e32 v94, 0xbfb8aa3b, v94
	v_exp_f32_e32 v94, v94
	v_add_f32_e32 v92, v92, v76
	v_mul_f32_e32 v92, 0xbfb8aa3b, v92
	v_exp_f32_e32 v92, v92
	v_add_f32_e32 v94, 1.0, v94
	v_add_f32_e32 v92, 1.0, v92
	v_max_f32_e32 v105, 0, v105
	v_rcp_f32_e32 v94, v94
	v_add_f32_e32 v80, v80, v88
	v_mul_f32_e32 v80, 0xbfb8aa3b, v80
	v_exp_f32_e32 v80, v80
	v_rcp_f32_e32 v93, v93
	v_and_b32_e32 v95, 0xffff0000, v122
	v_sqrt_f32_e32 v106, v106
	v_add_f32_e32 v80, 1.0, v80
	v_mul_f32_e32 v93, v93, v106
	v_mul_f32_e32 v106, v93, v95
	v_lshlrev_b32_e32 v93, 16, v122
	v_rcp_f32_e32 v92, v92
	v_max_f32_e32 v95, 0, v104
	v_sqrt_f32_e32 v95, v95
	s_nop 0
	v_mul_f32_e32 v92, v92, v95
	v_mul_f32_e32 v104, v92, v93
	v_lshlrev_b64 v[92:93], 10, v[120:121]
	v_sqrt_f32_e32 v105, v105
	v_and_b32_e32 v95, 0xffff0000, v123
	v_lshl_add_u64 v[92:93], v[92:93], 0, v[180:181]
	v_mul_f32_e32 v94, v94, v105
	v_mul_f32_e32 v105, v94, v95
	v_cvt_pk_bf16_f32 v94, v96, v97
	v_lshlrev_b64 v[96:97], 1, v[92:93]
	v_add_u32_e32 v120, 0xa0, v182
	v_cvt_pk_bf16_f32 v95, v98, v99
	v_lshl_add_u64 v[92:93], s[4:5], 0, v[96:97]
	v_ashrrev_i32_e32 v121, 31, v120
	global_store_dwordx2 v[92:93], v[94:95], off
	v_cvt_pk_bf16_f32 v98, v104, v106
	v_cvt_pk_bf16_f32 v99, v107, v105
	v_lshl_add_u64 v[94:95], s[0:1], 0, v[96:97]
	v_lshlrev_b64 v[96:97], 11, v[120:121]
	v_add_u32_e32 v104, 0xb0, v182
	global_store_dwordx2 v[94:95], v[98:99], off
	v_lshl_add_u64 v[98:99], v[140:141], 0, v[96:97]
	v_ashrrev_i32_e32 v105, 31, v104
	global_load_dwordx2 v[122:123], v[98:99], off
	v_lshlrev_b64 v[98:99], 11, v[104:105]
	v_lshl_add_u64 v[106:107], v[140:141], 0, v[98:99]
	global_load_dwordx2 v[106:107], v[106:107], off
	v_rcp_f32_e32 v80, v80
	s_nop 0
	v_mul_f32_e32 v80, 0xc1000000, v80
	v_mul_f32_e32 v80, v84, v80
	v_add_f32_e32 v137, v80, v80
	v_mul_f32_e32 v247, 0x3fb8aa3b, v137
	v_exp_f32_e32 v247, v247
	v_fma_f32 v136, v137, s14, 0.5
	v_fma_f32 v136, v137, v136, 1.0
	v_cmp_nlt_f32_e32 vcc, s51, v137
	v_mul_f32_e64 v136, v136, -v137
	v_sub_f32_e32 v247, 1.0, v247
	v_cndmask_b32_e32 v136, v136, v247, vcc
	v_add_f32_e32 v81, v81, v89
	v_mul_f32_e32 v81, 0xbfb8aa3b, v81
	v_exp_f32_e32 v81, v81
	s_nop 0
	v_add_f32_e32 v81, 1.0, v81
	v_rcp_f32_e32 v81, v81
	s_nop 0
	v_mul_f32_e32 v81, 0xc1000000, v81
	v_mul_f32_e32 v81, v85, v81
	v_add_f32_e32 v137, v81, v81
	v_mul_f32_e32 v247, 0x3fb8aa3b, v137
	v_exp_f32_e32 v247, v247
	v_fma_f32 v138, v137, s14, 0.5
	v_fma_f32 v138, v137, v138, 1.0
	v_cmp_nlt_f32_e32 vcc, s51, v137
	v_mul_f32_e64 v138, v138, -v137
	v_sub_f32_e32 v247, 1.0, v247
	v_cndmask_b32_e32 v138, v138, v247, vcc
	v_add_f32_e32 v82, v82, v90
	v_mul_f32_e32 v82, 0xbfb8aa3b, v82
	v_exp_f32_e32 v82, v82
	s_nop 0
	v_add_f32_e32 v82, 1.0, v82
	v_rcp_f32_e32 v82, v82
	s_nop 0
	v_mul_f32_e32 v82, 0xc1000000, v82
	v_mul_f32_e32 v82, v86, v82
	v_add_f32_e32 v137, v82, v82
	v_mul_f32_e32 v247, 0x3fb8aa3b, v137
	v_exp_f32_e32 v247, v247
	v_fma_f32 v139, v137, s14, 0.5
	v_fma_f32 v139, v137, v139, 1.0
	v_cmp_nlt_f32_e32 vcc, s51, v137
	v_mul_f32_e64 v139, v139, -v137
	v_sub_f32_e32 v247, 1.0, v247
	v_cndmask_b32_e32 v139, v139, v247, vcc
	v_add_f32_e32 v83, v83, v91
	v_mul_f32_e32 v83, 0xbfb8aa3b, v83
	v_exp_f32_e32 v83, v83
	s_nop 0
	v_add_f32_e32 v83, 1.0, v83
	v_rcp_f32_e32 v83, v83
	s_nop 0
	v_mul_f32_e32 v83, 0xc1000000, v83
	v_mul_f32_e32 v83, v87, v83
	v_add_f32_e32 v140, v83, v83
	v_mul_f32_e32 v247, 0x3fb8aa3b, v140
	v_exp_f32_e32 v247, v247
	v_fma_f32 v137, v140, s14, 0.5
	v_fma_f32 v137, v140, v137, 1.0
	v_cmp_nlt_f32_e32 vcc, s51, v140
	v_mul_f32_e64 v137, v137, -v140
	v_sub_f32_e32 v247, 1.0, v247
	v_cndmask_b32_e32 v137, v137, v247, vcc
	v_add_f32_e32 v74, v74, v78
	v_mul_f32_e32 v74, 0xbfb8aa3b, v74
	v_exp_f32_e32 v74, v74
	v_max_f32_e32 v139, 0, v139
	v_add_f32_e32 v73, v73, v77
	v_add_f32_e32 v74, 1.0, v74
	v_mul_f32_e32 v73, 0xbfb8aa3b, v73
	v_exp_f32_e32 v73, v73
	v_rcp_f32_e32 v74, v74
	s_waitcnt vmcnt(0)
	v_lshlrev_b32_e32 v140, 16, v123
	v_sqrt_f32_e32 v139, v139
	v_add_f32_e32 v73, 1.0, v73
	v_max_f32_e32 v138, 0, v138
	v_mul_f32_e32 v74, v74, v139
	v_mul_f32_e32 v139, v74, v140
	v_add_f32_e32 v74, v75, v79
	v_mul_f32_e32 v74, 0xbfb8aa3b, v74
	v_exp_f32_e32 v74, v74
	v_add_f32_e32 v72, v72, v76
	v_mul_f32_e32 v72, 0xbfb8aa3b, v72
	v_exp_f32_e32 v72, v72
	v_add_f32_e32 v74, 1.0, v74
	v_add_f32_e32 v72, 1.0, v72
	v_add_f32_e32 v68, v68, v88
	v_mul_f32_e32 v68, 0xbfb8aa3b, v68
	v_rcp_f32_e32 v74, v74
	v_exp_f32_e32 v68, v68
	v_rcp_f32_e32 v73, v73
	v_and_b32_e32 v75, 0xffff0000, v122
	v_sqrt_f32_e32 v138, v138
	v_add_f32_e32 v68, 1.0, v68
	v_mul_f32_e32 v73, v73, v138
	v_mul_f32_e32 v138, v73, v75
	v_lshlrev_b32_e32 v73, 16, v122
	v_rcp_f32_e32 v72, v72
	v_max_f32_e32 v75, 0, v136
	v_sqrt_f32_e32 v75, v75
	s_nop 0
	v_mul_f32_e32 v72, v72, v75
	v_mul_f32_e32 v122, v72, v73
	v_lshlrev_b64 v[72:73], 10, v[120:121]
	v_max_f32_e32 v120, 0, v137
	v_lshl_add_u64 v[72:73], v[72:73], 0, v[180:181]
	v_and_b32_e32 v75, 0xffff0000, v123
	v_sqrt_f32_e32 v120, v120
	v_lshlrev_b64 v[72:73], 1, v[72:73]
	v_mul_f32_e32 v74, v74, v120
	v_mul_f32_e32 v120, v74, v75
	v_cvt_pk_bf16_f32 v74, v80, v81
	v_cvt_pk_bf16_f32 v75, v82, v83
	v_lshl_add_u64 v[80:81], s[4:5], 0, v[72:73]
	v_lshl_add_u64 v[82:83], s[0:1], 0, v[72:73]
	global_store_dwordx2 v[80:81], v[74:75], off
	v_cvt_pk_bf16_f32 v74, v122, v138
	v_cvt_pk_bf16_f32 v75, v139, v120
	global_store_dwordx2 v[82:83], v[74:75], off
	v_rcp_f32_e32 v68, v68
	s_nop 0
	v_mul_f32_e32 v68, 0xc1000000, v68
	v_mul_f32_e32 v68, v84, v68
	v_add_f32_e32 v73, v68, v68
	v_mul_f32_e32 v247, 0x3fb8aa3b, v73
	v_exp_f32_e32 v247, v247
	v_fma_f32 v72, v73, s14, 0.5
	v_fma_f32 v72, v73, v72, 1.0
	v_cmp_nlt_f32_e32 vcc, s51, v73
	v_mul_f32_e64 v72, v72, -v73
	v_sub_f32_e32 v247, 1.0, v247
	v_cndmask_b32_e32 v72, v72, v247, vcc
	v_add_f32_e32 v69, v69, v89
	v_mul_f32_e32 v69, 0xbfb8aa3b, v69
	v_exp_f32_e32 v69, v69
	s_nop 0
	v_add_f32_e32 v69, 1.0, v69
	v_rcp_f32_e32 v69, v69
	s_nop 0
	v_mul_f32_e32 v69, 0xc1000000, v69
	v_mul_f32_e32 v69, v85, v69
	v_add_f32_e32 v73, v69, v69
	v_mul_f32_e32 v247, 0x3fb8aa3b, v73
	v_exp_f32_e32 v247, v247
	v_fma_f32 v74, v73, s14, 0.5
	v_fma_f32 v74, v73, v74, 1.0
	v_cmp_nlt_f32_e32 vcc, s51, v73
	v_mul_f32_e64 v74, v74, -v73
	v_sub_f32_e32 v247, 1.0, v247
	v_cndmask_b32_e32 v74, v74, v247, vcc
	v_add_f32_e32 v70, v70, v90
	v_mul_f32_e32 v70, 0xbfb8aa3b, v70
	v_exp_f32_e32 v70, v70
	s_nop 0
	v_add_f32_e32 v70, 1.0, v70
	v_rcp_f32_e32 v70, v70
	s_nop 0
	v_mul_f32_e32 v70, 0xc1000000, v70
	v_mul_f32_e32 v70, v86, v70
	v_add_f32_e32 v73, v70, v70
	v_mul_f32_e32 v247, 0x3fb8aa3b, v73
	v_exp_f32_e32 v247, v247
	v_fma_f32 v75, v73, s14, 0.5
	v_fma_f32 v75, v73, v75, 1.0
	v_cmp_nlt_f32_e32 vcc, s51, v73
	v_mul_f32_e64 v75, v75, -v73
	v_sub_f32_e32 v247, 1.0, v247
	v_cndmask_b32_e32 v75, v75, v247, vcc
	v_add_f32_e32 v71, v71, v91
	v_mul_f32_e32 v71, 0xbfb8aa3b, v71
	v_exp_f32_e32 v71, v71
	s_nop 0
	v_add_f32_e32 v71, 1.0, v71
	v_rcp_f32_e32 v71, v71
	s_nop 0
	v_mul_f32_e32 v71, 0xc1000000, v71
	v_mul_f32_e32 v71, v87, v71
	v_add_f32_e32 v84, v71, v71
	v_mul_f32_e32 v247, 0x3fb8aa3b, v84
	v_exp_f32_e32 v247, v247
	v_fma_f32 v73, v84, s14, 0.5
	v_fma_f32 v73, v84, v73, 1.0
	v_cmp_nlt_f32_e32 vcc, s51, v84
	v_mul_f32_e64 v73, v73, -v84
	v_sub_f32_e32 v247, 1.0, v247
	v_cndmask_b32_e32 v73, v73, v247, vcc
	v_add_f32_e32 v66, v66, v78
	v_mul_f32_e32 v66, 0xbfb8aa3b, v66
	v_exp_f32_e32 v66, v66
	v_max_f32_e32 v75, 0, v75
	v_add_f32_e32 v65, v65, v77
	v_add_f32_e32 v66, 1.0, v66
	v_mul_f32_e32 v65, 0xbfb8aa3b, v65
	v_exp_f32_e32 v65, v65
	v_rcp_f32_e32 v66, v66
	v_lshlrev_b32_e32 v78, 16, v107
	v_sqrt_f32_e32 v75, v75
	v_add_f32_e32 v65, 1.0, v65
	v_max_f32_e32 v74, 0, v74
	v_mul_f32_e32 v66, v66, v75
	v_mul_f32_e32 v75, v66, v78
	v_add_f32_e32 v66, v67, v79
	v_mul_f32_e32 v66, 0xbfb8aa3b, v66
	v_exp_f32_e32 v66, v66
	v_add_f32_e32 v64, v64, v76
	v_mul_f32_e32 v64, 0xbfb8aa3b, v64
	v_exp_f32_e32 v64, v64
	v_add_f32_e32 v66, 1.0, v66
	v_add_f32_e32 v64, 1.0, v64
	v_max_f32_e32 v73, 0, v73
	v_rcp_f32_e32 v66, v66
	v_rcp_f32_e32 v65, v65
	v_and_b32_e32 v67, 0xffff0000, v106
	v_sqrt_f32_e32 v74, v74
	v_or_b32_e32 v84, 64, v180
	v_ashrrev_i32_e32 v85, 31, v84
	v_mul_f32_e32 v65, v65, v74
	v_mul_f32_e32 v74, v65, v67
	v_lshlrev_b32_e32 v65, 16, v106
	v_lshlrev_b64 v[84:85], 1, v[84:85]
	v_rcp_f32_e32 v64, v64
	v_max_f32_e32 v67, 0, v72
	v_sqrt_f32_e32 v67, v67
	v_sqrt_f32_e32 v73, v73
	v_mul_f32_e32 v64, v64, v67
	v_mul_f32_e32 v72, v64, v65
	v_lshlrev_b64 v[64:65], 10, v[104:105]
	v_lshl_add_u64 v[64:65], v[64:65], 0, v[180:181]
	v_and_b32_e32 v67, 0xffff0000, v107
	v_mul_f32_e32 v66, v66, v73
	v_lshlrev_b64 v[64:65], 1, v[64:65]
	v_mul_f32_e32 v73, v66, v67
	v_cvt_pk_bf16_f32 v66, v68, v69
	v_cvt_pk_bf16_f32 v67, v70, v71
	v_lshl_add_u64 v[76:77], s[4:5], 0, v[64:65]
	v_lshl_add_u64 v[78:79], s[0:1], 0, v[64:65]
	global_store_dwordx2 v[76:77], v[66:67], off
	v_cvt_pk_bf16_f32 v66, v72, v74
	v_cvt_pk_bf16_f32 v67, v75, v73
	global_store_dwordx2 v[78:79], v[66:67], off
	global_load_dwordx4 v[72:75], v[172:173], off offset:256
	s_nop 0
	global_load_dwordx4 v[64:67], v[158:159], off offset:256
	global_load_dwordx4 v[68:71], v[174:175], off offset:256
	v_readlane_b32 s0, v253, 45
	v_readlane_b32 s1, v253, 46
	s_waitcnt vmcnt(0)
	v_add_f32_e32 v60, v60, v72
	v_lshl_add_u64 v[86:87], s[0:1], 0, v[178:179]
	v_lshl_add_u64 v[86:87], v[86:87], 0, v[84:85]
	global_load_dwordx2 v[88:89], v[86:87], off
	v_lshl_add_u64 v[86:87], s[0:1], 0, v[176:177]
	v_lshl_add_u64 v[86:87], v[86:87], 0, v[84:85]
	global_load_dwordx2 v[86:87], v[86:87], off
	v_mul_f32_e32 v60, 0xbfb8aa3b, v60
	v_exp_f32_e32 v60, v60
	s_nop 0
	v_add_f32_e32 v60, 1.0, v60
	v_rcp_f32_e32 v60, v60
	s_nop 0
	v_mul_f32_e32 v60, 0xc1000000, v60
	v_mul_f32_e32 v60, v68, v60
	v_add_f32_e32 v91, v60, v60
	v_mul_f32_e32 v247, 0x3fb8aa3b, v91
	v_exp_f32_e32 v247, v247
	v_fma_f32 v90, v91, s14, 0.5
	v_fma_f32 v90, v91, v90, 1.0
	v_cmp_nlt_f32_e32 vcc, s51, v91
	v_mul_f32_e64 v90, v90, -v91
	v_sub_f32_e32 v247, 1.0, v247
	v_cndmask_b32_e32 v90, v90, v247, vcc
	v_add_f32_e32 v61, v61, v73
	v_mul_f32_e32 v61, 0xbfb8aa3b, v61
	v_exp_f32_e32 v61, v61
	s_nop 0
	v_add_f32_e32 v61, 1.0, v61
	v_rcp_f32_e32 v61, v61
	s_nop 0
	v_mul_f32_e32 v61, 0xc1000000, v61
	v_mul_f32_e32 v61, v69, v61
	v_add_f32_e32 v91, v61, v61
	v_mul_f32_e32 v247, 0x3fb8aa3b, v91
	v_exp_f32_e32 v247, v247
	v_fma_f32 v104, v91, s14, 0.5
	v_fma_f32 v104, v91, v104, 1.0
	v_cmp_nlt_f32_e32 vcc, s51, v91
	v_mul_f32_e64 v104, v104, -v91
	v_sub_f32_e32 v247, 1.0, v247
	v_cndmask_b32_e32 v104, v104, v247, vcc
	v_add_f32_e32 v62, v62, v74
	v_mul_f32_e32 v62, 0xbfb8aa3b, v62
	v_exp_f32_e32 v62, v62
	s_nop 0
	v_add_f32_e32 v62, 1.0, v62
	v_rcp_f32_e32 v62, v62
	s_nop 0
	v_mul_f32_e32 v62, 0xc1000000, v62
	v_mul_f32_e32 v62, v70, v62
	v_add_f32_e32 v91, v62, v62
	v_mul_f32_e32 v247, 0x3fb8aa3b, v91
	v_exp_f32_e32 v247, v247
	v_fma_f32 v105, v91, s14, 0.5
	v_fma_f32 v105, v91, v105, 1.0
	v_cmp_nlt_f32_e32 vcc, s51, v91
	v_mul_f32_e64 v105, v105, -v91
	v_sub_f32_e32 v247, 1.0, v247
	v_cndmask_b32_e32 v105, v105, v247, vcc
	v_add_f32_e32 v63, v63, v75
	v_mul_f32_e32 v63, 0xbfb8aa3b, v63
	v_exp_f32_e32 v63, v63
	s_nop 0
	v_add_f32_e32 v63, 1.0, v63
	v_rcp_f32_e32 v63, v63
	s_nop 0
	v_mul_f32_e32 v63, 0xc1000000, v63
	v_mul_f32_e32 v63, v71, v63
	v_add_f32_e32 v106, v63, v63
	v_mul_f32_e32 v247, 0x3fb8aa3b, v106
	v_exp_f32_e32 v247, v247
	v_fma_f32 v91, v106, s14, 0.5
	v_fma_f32 v91, v106, v91, 1.0
	v_cmp_nlt_f32_e32 vcc, s51, v106
	v_mul_f32_e64 v91, v91, -v106
	v_sub_f32_e32 v247, 1.0, v247
	v_cndmask_b32_e32 v91, v91, v247, vcc
	v_add_f32_e32 v58, v58, v66
	v_mul_f32_e32 v58, 0xbfb8aa3b, v58
	v_exp_f32_e32 v58, v58
	v_max_f32_e32 v105, 0, v105
	v_add_f32_e32 v59, v59, v67
	v_add_f32_e32 v58, 1.0, v58
	v_mul_f32_e32 v59, 0xbfb8aa3b, v59
	v_exp_f32_e32 v59, v59
	v_add_f32_e32 v57, v57, v65
	v_rcp_f32_e32 v58, v58
	v_add_f32_e32 v59, 1.0, v59
	v_sqrt_f32_e32 v105, v105
	s_waitcnt vmcnt(0)
	v_lshlrev_b32_e32 v106, 16, v89
	v_mul_f32_e32 v57, 0xbfb8aa3b, v57
	v_mul_f32_e32 v58, v58, v105
	v_mul_f32_e32 v58, v58, v106
	v_exp_f32_e32 v57, v57
	v_max_f32_e32 v104, 0, v104
	v_add_f32_e32 v57, 1.0, v57
	v_rcp_f32_e32 v59, v59
	v_add_f32_e32 v56, v56, v64
	v_mul_f32_e32 v56, 0xbfb8aa3b, v56
	v_exp_f32_e32 v56, v56
	v_rcp_f32_e32 v57, v57
	v_and_b32_e32 v105, 0xffff0000, v88
	v_sqrt_f32_e32 v104, v104
	v_add_f32_e32 v56, 1.0, v56
	v_add_f32_e32 v52, v52, v72
	v_mul_f32_e32 v57, v57, v104
	v_mul_f32_e32 v104, v57, v105
	v_lshlrev_b32_e32 v57, 16, v88
	v_mul_f32_e32 v52, 0xbfb8aa3b, v52
	v_exp_f32_e32 v52, v52
	v_rcp_f32_e32 v56, v56
	v_max_f32_e32 v88, 0, v90
	v_add_f32_e32 v52, 1.0, v52
	v_sqrt_f32_e32 v88, v88
	s_nop 0
	v_mul_f32_e32 v56, v56, v88
	v_mul_f32_e32 v88, v56, v57
	v_max_f32_e32 v57, 0, v91
	v_and_b32_e32 v56, 0xffff0000, v89
	v_sqrt_f32_e32 v57, v57
	s_nop 0
	v_mul_f32_e32 v57, v59, v57
	v_mul_f32_e32 v59, v57, v56
	v_cvt_pk_bf16_f32 v56, v60, v61
	v_cvt_pk_bf16_f32 v57, v62, v63
	global_store_dwordx2 v[132:133], v[56:57], off offset:128
	v_cvt_pk_bf16_f32 v56, v88, v104
	v_cvt_pk_bf16_f32 v57, v58, v59
	global_store_dwordx2 v[134:135], v[56:57], off offset:128
	v_rcp_f32_e32 v52, v52
	s_nop 0
	v_mul_f32_e32 v52, 0xc1000000, v52
	v_mul_f32_e32 v52, v68, v52
	v_add_f32_e32 v57, v52, v52
	v_mul_f32_e32 v247, 0x3fb8aa3b, v57
	v_exp_f32_e32 v247, v247
	v_fma_f32 v56, v57, s14, 0.5
	v_fma_f32 v56, v57, v56, 1.0
	v_cmp_nlt_f32_e32 vcc, s51, v57
	v_mul_f32_e64 v56, v56, -v57
	v_sub_f32_e32 v247, 1.0, v247
	v_cndmask_b32_e32 v56, v56, v247, vcc
	v_add_f32_e32 v53, v53, v73
	v_mul_f32_e32 v53, 0xbfb8aa3b, v53
	v_exp_f32_e32 v53, v53
	s_nop 0
	v_add_f32_e32 v53, 1.0, v53
	v_rcp_f32_e32 v53, v53
	s_nop 0
	v_mul_f32_e32 v53, 0xc1000000, v53
	v_mul_f32_e32 v53, v69, v53
	v_add_f32_e32 v57, v53, v53
	v_mul_f32_e32 v247, 0x3fb8aa3b, v57
	v_exp_f32_e32 v247, v247
	v_fma_f32 v58, v57, s14, 0.5
	v_fma_f32 v58, v57, v58, 1.0
	v_cmp_nlt_f32_e32 vcc, s51, v57
	v_mul_f32_e64 v58, v58, -v57
	v_sub_f32_e32 v247, 1.0, v247
	v_cndmask_b32_e32 v58, v58, v247, vcc
	v_add_f32_e32 v54, v54, v74
	v_mul_f32_e32 v54, 0xbfb8aa3b, v54
	v_exp_f32_e32 v54, v54
	s_nop 0
	v_add_f32_e32 v54, 1.0, v54
	v_rcp_f32_e32 v54, v54
	s_nop 0
	v_mul_f32_e32 v54, 0xc1000000, v54
	v_mul_f32_e32 v54, v70, v54
	v_add_f32_e32 v57, v54, v54
	v_mul_f32_e32 v247, 0x3fb8aa3b, v57
	v_exp_f32_e32 v247, v247
	v_fma_f32 v59, v57, s14, 0.5
	v_fma_f32 v59, v57, v59, 1.0
	v_cmp_nlt_f32_e32 vcc, s51, v57
	v_mul_f32_e64 v59, v59, -v57
	v_sub_f32_e32 v247, 1.0, v247
	v_cndmask_b32_e32 v59, v59, v247, vcc
	v_add_f32_e32 v55, v55, v75
	v_mul_f32_e32 v55, 0xbfb8aa3b, v55
	v_exp_f32_e32 v55, v55
	s_nop 0
	v_add_f32_e32 v55, 1.0, v55
	v_rcp_f32_e32 v55, v55
	s_nop 0
	v_mul_f32_e32 v55, 0xc1000000, v55
	v_mul_f32_e32 v55, v71, v55
	v_add_f32_e32 v60, v55, v55
	v_mul_f32_e32 v247, 0x3fb8aa3b, v60
	v_exp_f32_e32 v247, v247
	v_fma_f32 v57, v60, s14, 0.5
	v_fma_f32 v57, v60, v57, 1.0
	v_cmp_nlt_f32_e32 vcc, s51, v60
	v_mul_f32_e64 v57, v57, -v60
	v_sub_f32_e32 v247, 1.0, v247
	v_cndmask_b32_e32 v57, v57, v247, vcc
	v_add_f32_e32 v50, v50, v66
	v_mul_f32_e32 v50, 0xbfb8aa3b, v50
	v_exp_f32_e32 v50, v50
	v_max_f32_e32 v59, 0, v59
	v_add_f32_e32 v51, v51, v67
	v_add_f32_e32 v50, 1.0, v50
	v_mul_f32_e32 v51, 0xbfb8aa3b, v51
	v_exp_f32_e32 v51, v51
	v_add_f32_e32 v49, v49, v65
	v_rcp_f32_e32 v50, v50
	v_add_f32_e32 v51, 1.0, v51
	v_sqrt_f32_e32 v59, v59
	v_lshlrev_b32_e32 v60, 16, v87
	v_mul_f32_e32 v49, 0xbfb8aa3b, v49
	v_mul_f32_e32 v50, v50, v59
	v_mul_f32_e32 v50, v50, v60
	v_exp_f32_e32 v49, v49
	v_max_f32_e32 v58, 0, v58
	v_add_f32_e32 v49, 1.0, v49
	v_rcp_f32_e32 v51, v51
	v_add_f32_e32 v48, v48, v64
	v_mul_f32_e32 v48, 0xbfb8aa3b, v48
	v_exp_f32_e32 v48, v48
	v_rcp_f32_e32 v49, v49
	v_and_b32_e32 v59, 0xffff0000, v86
	v_sqrt_f32_e32 v58, v58
	v_add_f32_e32 v48, 1.0, v48
	v_mul_f32_e32 v49, v49, v58
	v_mul_f32_e32 v58, v49, v59
	v_max_f32_e32 v56, 0, v56
	v_lshlrev_b32_e32 v49, 16, v86
	v_readlane_b32 s0, v253, 45
	v_rcp_f32_e32 v48, v48
	v_readlane_b32 s1, v253, 46
	v_sqrt_f32_e32 v56, v56
	v_add_f32_e32 v44, v44, v72
	v_mul_f32_e32 v44, 0xbfb8aa3b, v44
	v_mul_f32_e32 v48, v48, v56
	v_mul_f32_e32 v56, v48, v49
	v_max_f32_e32 v49, 0, v57
	v_and_b32_e32 v48, 0xffff0000, v87
	v_exp_f32_e32 v44, v44
	v_sqrt_f32_e32 v49, v49
	v_add_f32_e32 v44, 1.0, v44
	v_mul_f32_e32 v49, v51, v49
	v_mul_f32_e32 v51, v49, v48
	v_cvt_pk_bf16_f32 v48, v52, v53
	v_cvt_pk_bf16_f32 v49, v54, v55
	global_store_dwordx2 v[124:125], v[48:49], off offset:128
	v_cvt_pk_bf16_f32 v48, v56, v58
	v_cvt_pk_bf16_f32 v49, v50, v51
	global_store_dwordx2 v[126:127], v[48:49], off offset:128
	v_lshl_add_u64 v[48:49], s[0:1], 0, v[128:129]
	v_lshl_add_u64 v[48:49], v[48:49], 0, v[84:85]
	global_load_dwordx2 v[50:51], v[48:49], off
	v_lshl_add_u64 v[48:49], s[0:1], 0, v[130:131]
	v_lshl_add_u64 v[48:49], v[48:49], 0, v[84:85]
	global_load_dwordx2 v[48:49], v[48:49], off
	v_rcp_f32_e32 v44, v44
	s_nop 0
	v_mul_f32_e32 v44, 0xc1000000, v44
	v_mul_f32_e32 v44, v68, v44
	v_add_f32_e32 v53, v44, v44
	v_mul_f32_e32 v247, 0x3fb8aa3b, v53
	v_exp_f32_e32 v247, v247
	v_fma_f32 v52, v53, s14, 0.5
	v_fma_f32 v52, v53, v52, 1.0
	v_cmp_nlt_f32_e32 vcc, s51, v53
	v_mul_f32_e64 v52, v52, -v53
	v_sub_f32_e32 v247, 1.0, v247
	v_cndmask_b32_e32 v52, v52, v247, vcc
	v_add_f32_e32 v45, v45, v73
	v_mul_f32_e32 v45, 0xbfb8aa3b, v45
	v_exp_f32_e32 v45, v45
	s_nop 0
	v_add_f32_e32 v45, 1.0, v45
	v_rcp_f32_e32 v45, v45
	s_nop 0
	v_mul_f32_e32 v45, 0xc1000000, v45
	v_mul_f32_e32 v45, v69, v45
	v_add_f32_e32 v53, v45, v45
	v_mul_f32_e32 v247, 0x3fb8aa3b, v53
	v_exp_f32_e32 v247, v247
	v_fma_f32 v54, v53, s14, 0.5
	v_fma_f32 v54, v53, v54, 1.0
	v_cmp_nlt_f32_e32 vcc, s51, v53
	v_mul_f32_e64 v54, v54, -v53
	v_sub_f32_e32 v247, 1.0, v247
	v_cndmask_b32_e32 v54, v54, v247, vcc
	v_add_f32_e32 v46, v46, v74
	v_mul_f32_e32 v46, 0xbfb8aa3b, v46
	v_exp_f32_e32 v46, v46
	s_nop 0
	v_add_f32_e32 v46, 1.0, v46
	v_rcp_f32_e32 v46, v46
	s_nop 0
	v_mul_f32_e32 v46, 0xc1000000, v46
	v_mul_f32_e32 v46, v70, v46
	v_add_f32_e32 v53, v46, v46
	v_mul_f32_e32 v247, 0x3fb8aa3b, v53
	v_exp_f32_e32 v247, v247
	v_fma_f32 v55, v53, s14, 0.5
	v_fma_f32 v55, v53, v55, 1.0
	v_cmp_nlt_f32_e32 vcc, s51, v53
	v_mul_f32_e64 v55, v55, -v53
	v_sub_f32_e32 v247, 1.0, v247
	v_cndmask_b32_e32 v55, v55, v247, vcc
	v_add_f32_e32 v47, v47, v75
	v_mul_f32_e32 v47, 0xbfb8aa3b, v47
	v_exp_f32_e32 v47, v47
	s_nop 0
	v_add_f32_e32 v47, 1.0, v47
	v_rcp_f32_e32 v47, v47
	s_nop 0
	v_mul_f32_e32 v47, 0xc1000000, v47
	v_mul_f32_e32 v47, v71, v47
	v_add_f32_e32 v56, v47, v47
	v_mul_f32_e32 v247, 0x3fb8aa3b, v56
	v_exp_f32_e32 v247, v247
	v_fma_f32 v53, v56, s14, 0.5
	v_fma_f32 v53, v56, v53, 1.0
	v_cmp_nlt_f32_e32 vcc, s51, v56
	v_mul_f32_e64 v53, v53, -v56
	v_sub_f32_e32 v247, 1.0, v247
	v_cndmask_b32_e32 v53, v53, v247, vcc
	v_add_f32_e32 v42, v42, v66
	v_mul_f32_e32 v42, 0xbfb8aa3b, v42
	v_exp_f32_e32 v42, v42
	v_max_f32_e32 v55, 0, v55
	v_add_f32_e32 v43, v43, v67
	v_add_f32_e32 v42, 1.0, v42
	v_mul_f32_e32 v43, 0xbfb8aa3b, v43
	v_exp_f32_e32 v43, v43
	v_add_f32_e32 v41, v41, v65
	v_rcp_f32_e32 v42, v42
	v_add_f32_e32 v43, 1.0, v43
	v_sqrt_f32_e32 v55, v55
	s_waitcnt vmcnt(0)
	v_lshlrev_b32_e32 v56, 16, v51
	v_mul_f32_e32 v41, 0xbfb8aa3b, v41
	v_mul_f32_e32 v42, v42, v55
	v_mul_f32_e32 v42, v42, v56
	v_exp_f32_e32 v41, v41
	v_max_f32_e32 v54, 0, v54
	v_add_f32_e32 v41, 1.0, v41
	v_rcp_f32_e32 v43, v43
	v_add_f32_e32 v40, v40, v64
	v_mul_f32_e32 v40, 0xbfb8aa3b, v40
	v_exp_f32_e32 v40, v40
	v_rcp_f32_e32 v41, v41
	v_and_b32_e32 v55, 0xffff0000, v50
	v_sqrt_f32_e32 v54, v54
	v_add_f32_e32 v40, 1.0, v40
	v_add_f32_e32 v36, v36, v72
	v_mul_f32_e32 v41, v41, v54
	v_mul_f32_e32 v54, v41, v55
	v_lshlrev_b32_e32 v41, 16, v50
	v_mul_f32_e32 v36, 0xbfb8aa3b, v36
	v_exp_f32_e32 v36, v36
	v_rcp_f32_e32 v40, v40
	v_max_f32_e32 v50, 0, v52
	v_add_f32_e32 v36, 1.0, v36
	v_sqrt_f32_e32 v50, v50
	s_nop 0
	v_mul_f32_e32 v40, v40, v50
	v_mul_f32_e32 v50, v40, v41
	v_max_f32_e32 v41, 0, v53
	v_and_b32_e32 v40, 0xffff0000, v51
	v_sqrt_f32_e32 v41, v41
	s_nop 0
	v_mul_f32_e32 v41, v43, v41
	v_mul_f32_e32 v43, v41, v40
	v_cvt_pk_bf16_f32 v40, v44, v45
	v_cvt_pk_bf16_f32 v41, v46, v47
	global_store_dwordx2 v[116:117], v[40:41], off offset:128
	v_cvt_pk_bf16_f32 v40, v50, v54
	v_cvt_pk_bf16_f32 v41, v42, v43
	global_store_dwordx2 v[118:119], v[40:41], off offset:128
	v_rcp_f32_e32 v36, v36
	s_nop 0
	v_mul_f32_e32 v36, 0xc1000000, v36
	v_mul_f32_e32 v36, v68, v36
	v_add_f32_e32 v41, v36, v36
	v_mul_f32_e32 v247, 0x3fb8aa3b, v41
	v_exp_f32_e32 v247, v247
	v_fma_f32 v40, v41, s14, 0.5
	v_fma_f32 v40, v41, v40, 1.0
	v_cmp_nlt_f32_e32 vcc, s51, v41
	v_mul_f32_e64 v40, v40, -v41
	v_sub_f32_e32 v247, 1.0, v247
	v_cndmask_b32_e32 v40, v40, v247, vcc
	v_add_f32_e32 v37, v37, v73
	v_mul_f32_e32 v37, 0xbfb8aa3b, v37
	v_exp_f32_e32 v37, v37
	s_nop 0
	v_add_f32_e32 v37, 1.0, v37
	v_rcp_f32_e32 v37, v37
	s_nop 0
	v_mul_f32_e32 v37, 0xc1000000, v37
	v_mul_f32_e32 v37, v69, v37
	v_add_f32_e32 v41, v37, v37
	v_mul_f32_e32 v247, 0x3fb8aa3b, v41
	v_exp_f32_e32 v247, v247
	v_fma_f32 v42, v41, s14, 0.5
	v_fma_f32 v42, v41, v42, 1.0
	v_cmp_nlt_f32_e32 vcc, s51, v41
	v_mul_f32_e64 v42, v42, -v41
	v_sub_f32_e32 v247, 1.0, v247
	v_cndmask_b32_e32 v42, v42, v247, vcc
	v_add_f32_e32 v38, v38, v74
	v_mul_f32_e32 v38, 0xbfb8aa3b, v38
	v_exp_f32_e32 v38, v38
	s_nop 0
	v_add_f32_e32 v38, 1.0, v38
	v_rcp_f32_e32 v38, v38
	s_nop 0
	v_mul_f32_e32 v38, 0xc1000000, v38
	v_mul_f32_e32 v38, v70, v38
	v_add_f32_e32 v41, v38, v38
	v_mul_f32_e32 v247, 0x3fb8aa3b, v41
	v_exp_f32_e32 v247, v247
	v_fma_f32 v43, v41, s14, 0.5
	v_fma_f32 v43, v41, v43, 1.0
	v_cmp_nlt_f32_e32 vcc, s51, v41
	v_mul_f32_e64 v43, v43, -v41
	v_sub_f32_e32 v247, 1.0, v247
	v_cndmask_b32_e32 v43, v43, v247, vcc
	v_add_f32_e32 v39, v39, v75
	v_mul_f32_e32 v39, 0xbfb8aa3b, v39
	v_exp_f32_e32 v39, v39
	s_nop 0
	v_add_f32_e32 v39, 1.0, v39
	v_rcp_f32_e32 v39, v39
	s_nop 0
	v_mul_f32_e32 v39, 0xc1000000, v39
	v_mul_f32_e32 v39, v71, v39
	v_add_f32_e32 v44, v39, v39
	v_mul_f32_e32 v247, 0x3fb8aa3b, v44
	v_exp_f32_e32 v247, v247
	v_fma_f32 v41, v44, s14, 0.5
	v_fma_f32 v41, v44, v41, 1.0
	v_cmp_nlt_f32_e32 vcc, s51, v44
	v_mul_f32_e64 v41, v41, -v44
	v_sub_f32_e32 v247, 1.0, v247
	v_cndmask_b32_e32 v41, v41, v247, vcc
	v_add_f32_e32 v34, v34, v66
	v_mul_f32_e32 v34, 0xbfb8aa3b, v34
	v_exp_f32_e32 v34, v34
	v_max_f32_e32 v43, 0, v43
	v_add_f32_e32 v35, v35, v67
	v_add_f32_e32 v34, 1.0, v34
	v_mul_f32_e32 v35, 0xbfb8aa3b, v35
	v_exp_f32_e32 v35, v35
	v_add_f32_e32 v33, v33, v65
	v_rcp_f32_e32 v34, v34
	v_add_f32_e32 v35, 1.0, v35
	v_sqrt_f32_e32 v43, v43
	v_lshlrev_b32_e32 v44, 16, v49
	v_mul_f32_e32 v33, 0xbfb8aa3b, v33
	v_mul_f32_e32 v34, v34, v43
	v_mul_f32_e32 v34, v34, v44
	v_exp_f32_e32 v33, v33
	v_max_f32_e32 v42, 0, v42
	v_add_f32_e32 v33, 1.0, v33
	v_rcp_f32_e32 v35, v35
	v_add_f32_e32 v32, v32, v64
	v_mul_f32_e32 v32, 0xbfb8aa3b, v32
	v_exp_f32_e32 v32, v32
	v_rcp_f32_e32 v33, v33
	v_and_b32_e32 v43, 0xffff0000, v48
	v_sqrt_f32_e32 v42, v42
	v_add_f32_e32 v32, 1.0, v32
	v_mul_f32_e32 v33, v33, v42
	v_mul_f32_e32 v42, v33, v43
	v_max_f32_e32 v40, 0, v40
	v_lshlrev_b32_e32 v33, 16, v48
	v_readlane_b32 s0, v253, 45
	v_rcp_f32_e32 v32, v32
	v_readlane_b32 s1, v253, 46
	v_sqrt_f32_e32 v40, v40
	v_add_f32_e32 v28, v28, v72
	v_mul_f32_e32 v28, 0xbfb8aa3b, v28
	v_mul_f32_e32 v32, v32, v40
	v_mul_f32_e32 v40, v32, v33
	v_max_f32_e32 v33, 0, v41
	v_and_b32_e32 v32, 0xffff0000, v49
	v_exp_f32_e32 v28, v28
	v_sqrt_f32_e32 v33, v33
	v_add_f32_e32 v28, 1.0, v28
	v_mul_f32_e32 v33, v35, v33
	v_mul_f32_e32 v35, v33, v32
	v_cvt_pk_bf16_f32 v32, v36, v37
	v_cvt_pk_bf16_f32 v33, v38, v39
	global_store_dwordx2 v[108:109], v[32:33], off offset:128
	v_cvt_pk_bf16_f32 v32, v40, v42
	v_cvt_pk_bf16_f32 v33, v34, v35
	global_store_dwordx2 v[110:111], v[32:33], off offset:128
	v_lshl_add_u64 v[32:33], s[0:1], 0, v[112:113]
	v_lshl_add_u64 v[32:33], v[32:33], 0, v[84:85]
	global_load_dwordx2 v[34:35], v[32:33], off
	v_lshl_add_u64 v[32:33], s[0:1], 0, v[114:115]
	v_lshl_add_u64 v[32:33], v[32:33], 0, v[84:85]
	global_load_dwordx2 v[32:33], v[32:33], off
	v_rcp_f32_e32 v28, v28
	s_nop 0
	v_mul_f32_e32 v28, 0xc1000000, v28
	v_mul_f32_e32 v28, v68, v28
	v_add_f32_e32 v37, v28, v28
	v_mul_f32_e32 v247, 0x3fb8aa3b, v37
	v_exp_f32_e32 v247, v247
	v_fma_f32 v36, v37, s14, 0.5
	v_fma_f32 v36, v37, v36, 1.0
	v_cmp_nlt_f32_e32 vcc, s51, v37
	v_mul_f32_e64 v36, v36, -v37
	v_sub_f32_e32 v247, 1.0, v247
	v_cndmask_b32_e32 v36, v36, v247, vcc
	v_add_f32_e32 v29, v29, v73
	v_mul_f32_e32 v29, 0xbfb8aa3b, v29
	v_exp_f32_e32 v29, v29
	s_nop 0
	v_add_f32_e32 v29, 1.0, v29
	v_rcp_f32_e32 v29, v29
	s_nop 0
	v_mul_f32_e32 v29, 0xc1000000, v29
	v_mul_f32_e32 v29, v69, v29
	v_add_f32_e32 v37, v29, v29
	v_mul_f32_e32 v247, 0x3fb8aa3b, v37
	v_exp_f32_e32 v247, v247
	v_fma_f32 v38, v37, s14, 0.5
	v_fma_f32 v38, v37, v38, 1.0
	v_cmp_nlt_f32_e32 vcc, s51, v37
	v_mul_f32_e64 v38, v38, -v37
	v_sub_f32_e32 v247, 1.0, v247
	v_cndmask_b32_e32 v38, v38, v247, vcc
	v_add_f32_e32 v30, v30, v74
	v_mul_f32_e32 v30, 0xbfb8aa3b, v30
	v_exp_f32_e32 v30, v30
	s_nop 0
	v_add_f32_e32 v30, 1.0, v30
	v_rcp_f32_e32 v30, v30
	s_nop 0
	v_mul_f32_e32 v30, 0xc1000000, v30
	v_mul_f32_e32 v30, v70, v30
	v_add_f32_e32 v37, v30, v30
	v_mul_f32_e32 v247, 0x3fb8aa3b, v37
	v_exp_f32_e32 v247, v247
	v_fma_f32 v39, v37, s14, 0.5
	v_fma_f32 v39, v37, v39, 1.0
	v_cmp_nlt_f32_e32 vcc, s51, v37
	v_mul_f32_e64 v39, v39, -v37
	v_sub_f32_e32 v247, 1.0, v247
	v_cndmask_b32_e32 v39, v39, v247, vcc
	v_add_f32_e32 v31, v31, v75
	v_mul_f32_e32 v31, 0xbfb8aa3b, v31
	v_exp_f32_e32 v31, v31
	s_nop 0
	v_add_f32_e32 v31, 1.0, v31
	v_rcp_f32_e32 v31, v31
	s_nop 0
	v_mul_f32_e32 v31, 0xc1000000, v31
	v_mul_f32_e32 v31, v71, v31
	v_add_f32_e32 v40, v31, v31
	v_mul_f32_e32 v247, 0x3fb8aa3b, v40
	v_exp_f32_e32 v247, v247
	v_fma_f32 v37, v40, s14, 0.5
	v_fma_f32 v37, v40, v37, 1.0
	v_cmp_nlt_f32_e32 vcc, s51, v40
	v_mul_f32_e64 v37, v37, -v40
	v_sub_f32_e32 v247, 1.0, v247
	v_cndmask_b32_e32 v37, v37, v247, vcc
	v_add_f32_e32 v26, v26, v66
	v_mul_f32_e32 v26, 0xbfb8aa3b, v26
	v_exp_f32_e32 v26, v26
	v_max_f32_e32 v39, 0, v39
	v_add_f32_e32 v27, v27, v67
	v_add_f32_e32 v26, 1.0, v26
	v_mul_f32_e32 v27, 0xbfb8aa3b, v27
	v_exp_f32_e32 v27, v27
	v_add_f32_e32 v25, v25, v65
	v_rcp_f32_e32 v26, v26
	v_add_f32_e32 v27, 1.0, v27
	v_sqrt_f32_e32 v39, v39
	s_waitcnt vmcnt(0)
	v_lshlrev_b32_e32 v40, 16, v35
	v_mul_f32_e32 v25, 0xbfb8aa3b, v25
	v_mul_f32_e32 v26, v26, v39
	v_mul_f32_e32 v26, v26, v40
	v_exp_f32_e32 v25, v25
	v_max_f32_e32 v38, 0, v38
	v_add_f32_e32 v25, 1.0, v25
	v_rcp_f32_e32 v27, v27
	v_add_f32_e32 v24, v24, v64
	v_mul_f32_e32 v24, 0xbfb8aa3b, v24
	v_exp_f32_e32 v24, v24
	v_rcp_f32_e32 v25, v25
	v_and_b32_e32 v39, 0xffff0000, v34
	v_sqrt_f32_e32 v38, v38
	v_add_f32_e32 v24, 1.0, v24
	v_add_f32_e32 v20, v20, v72
	v_mul_f32_e32 v25, v25, v38
	v_mul_f32_e32 v38, v25, v39
	v_lshlrev_b32_e32 v25, 16, v34
	v_mul_f32_e32 v20, 0xbfb8aa3b, v20
	v_exp_f32_e32 v20, v20
	v_rcp_f32_e32 v24, v24
	v_max_f32_e32 v34, 0, v36
	v_add_f32_e32 v20, 1.0, v20
	v_sqrt_f32_e32 v34, v34
	s_nop 0
	v_mul_f32_e32 v24, v24, v34
	v_mul_f32_e32 v34, v24, v25
	v_max_f32_e32 v25, 0, v37
	v_and_b32_e32 v24, 0xffff0000, v35
	v_sqrt_f32_e32 v25, v25
	s_nop 0
	v_mul_f32_e32 v25, v27, v25
	v_mul_f32_e32 v27, v25, v24
	v_cvt_pk_bf16_f32 v24, v28, v29
	v_cvt_pk_bf16_f32 v25, v30, v31
	global_store_dwordx2 v[100:101], v[24:25], off offset:128
	v_cvt_pk_bf16_f32 v24, v34, v38
	v_cvt_pk_bf16_f32 v25, v26, v27
	global_store_dwordx2 v[102:103], v[24:25], off offset:128
	v_rcp_f32_e32 v20, v20
	s_nop 0
	v_mul_f32_e32 v20, 0xc1000000, v20
	v_mul_f32_e32 v20, v68, v20
	v_add_f32_e32 v25, v20, v20
	v_mul_f32_e32 v247, 0x3fb8aa3b, v25
	v_exp_f32_e32 v247, v247
	v_fma_f32 v24, v25, s14, 0.5
	v_fma_f32 v24, v25, v24, 1.0
	v_cmp_nlt_f32_e32 vcc, s51, v25
	v_mul_f32_e64 v24, v24, -v25
	v_sub_f32_e32 v247, 1.0, v247
	v_cndmask_b32_e32 v24, v24, v247, vcc
	v_add_f32_e32 v21, v21, v73
	v_mul_f32_e32 v21, 0xbfb8aa3b, v21
	v_exp_f32_e32 v21, v21
	s_nop 0
	v_add_f32_e32 v21, 1.0, v21
	v_rcp_f32_e32 v21, v21
	s_nop 0
	v_mul_f32_e32 v21, 0xc1000000, v21
	v_mul_f32_e32 v21, v69, v21
	v_add_f32_e32 v25, v21, v21
	v_mul_f32_e32 v247, 0x3fb8aa3b, v25
	v_exp_f32_e32 v247, v247
	v_fma_f32 v26, v25, s14, 0.5
	v_fma_f32 v26, v25, v26, 1.0
	v_cmp_nlt_f32_e32 vcc, s51, v25
	v_mul_f32_e64 v26, v26, -v25
	v_sub_f32_e32 v247, 1.0, v247
	v_cndmask_b32_e32 v26, v26, v247, vcc
	v_add_f32_e32 v22, v22, v74
	v_mul_f32_e32 v22, 0xbfb8aa3b, v22
	v_exp_f32_e32 v22, v22
	s_nop 0
	v_add_f32_e32 v22, 1.0, v22
	v_rcp_f32_e32 v22, v22
	s_nop 0
	v_mul_f32_e32 v22, 0xc1000000, v22
	v_mul_f32_e32 v22, v70, v22
	v_add_f32_e32 v25, v22, v22
	v_mul_f32_e32 v247, 0x3fb8aa3b, v25
	v_exp_f32_e32 v247, v247
	v_fma_f32 v27, v25, s14, 0.5
	v_fma_f32 v27, v25, v27, 1.0
	v_cmp_nlt_f32_e32 vcc, s51, v25
	v_mul_f32_e64 v27, v27, -v25
	v_sub_f32_e32 v247, 1.0, v247
	v_cndmask_b32_e32 v27, v27, v247, vcc
	v_add_f32_e32 v23, v23, v75
	v_mul_f32_e32 v23, 0xbfb8aa3b, v23
	v_exp_f32_e32 v23, v23
	s_nop 0
	v_add_f32_e32 v23, 1.0, v23
	v_rcp_f32_e32 v23, v23
	s_nop 0
	v_mul_f32_e32 v23, 0xc1000000, v23
	v_mul_f32_e32 v23, v71, v23
	v_add_f32_e32 v28, v23, v23
	v_mul_f32_e32 v247, 0x3fb8aa3b, v28
	v_exp_f32_e32 v247, v247
	v_fma_f32 v25, v28, s14, 0.5
	v_fma_f32 v25, v28, v25, 1.0
	v_cmp_nlt_f32_e32 vcc, s51, v28
	v_mul_f32_e64 v25, v25, -v28
	v_sub_f32_e32 v247, 1.0, v247
	v_cndmask_b32_e32 v25, v25, v247, vcc
	v_add_f32_e32 v18, v18, v66
	v_mul_f32_e32 v18, 0xbfb8aa3b, v18
	v_exp_f32_e32 v18, v18
	v_max_f32_e32 v27, 0, v27
	v_add_f32_e32 v19, v19, v67
	v_add_f32_e32 v18, 1.0, v18
	v_mul_f32_e32 v19, 0xbfb8aa3b, v19
	v_exp_f32_e32 v19, v19
	v_add_f32_e32 v17, v17, v65
	v_rcp_f32_e32 v18, v18
	v_add_f32_e32 v19, 1.0, v19
	v_sqrt_f32_e32 v27, v27
	v_lshlrev_b32_e32 v28, 16, v33
	v_mul_f32_e32 v17, 0xbfb8aa3b, v17
	v_mul_f32_e32 v18, v18, v27
	v_mul_f32_e32 v18, v18, v28
	v_exp_f32_e32 v17, v17
	v_max_f32_e32 v26, 0, v26
	v_add_f32_e32 v17, 1.0, v17
	v_rcp_f32_e32 v19, v19
	v_add_f32_e32 v16, v16, v64
	v_mul_f32_e32 v16, 0xbfb8aa3b, v16
	v_exp_f32_e32 v16, v16
	v_rcp_f32_e32 v17, v17
	v_and_b32_e32 v27, 0xffff0000, v32
	v_sqrt_f32_e32 v26, v26
	v_add_f32_e32 v16, 1.0, v16
	v_mul_f32_e32 v17, v17, v26
	v_mul_f32_e32 v26, v17, v27
	v_max_f32_e32 v24, 0, v24
	v_lshlrev_b32_e32 v17, 16, v32
	v_readlane_b32 s0, v253, 45
	v_rcp_f32_e32 v16, v16
	v_readlane_b32 s1, v253, 46
	v_sqrt_f32_e32 v24, v24
	v_add_f32_e32 v12, v12, v72
	v_mul_f32_e32 v12, 0xbfb8aa3b, v12
	v_mul_f32_e32 v16, v16, v24
	v_mul_f32_e32 v24, v16, v17
	v_max_f32_e32 v17, 0, v25
	v_and_b32_e32 v16, 0xffff0000, v33
	v_exp_f32_e32 v12, v12
	v_sqrt_f32_e32 v17, v17
	v_add_f32_e32 v12, 1.0, v12
	v_mul_f32_e32 v17, v19, v17
	v_mul_f32_e32 v19, v17, v16
	v_cvt_pk_bf16_f32 v16, v20, v21
	v_cvt_pk_bf16_f32 v17, v22, v23
	global_store_dwordx2 v[92:93], v[16:17], off offset:128
	v_cvt_pk_bf16_f32 v16, v24, v26
	v_cvt_pk_bf16_f32 v17, v18, v19
	global_store_dwordx2 v[94:95], v[16:17], off offset:128
	v_lshl_add_u64 v[16:17], s[0:1], 0, v[96:97]
	v_lshl_add_u64 v[16:17], v[16:17], 0, v[84:85]
	global_load_dwordx2 v[18:19], v[16:17], off
	v_lshl_add_u64 v[16:17], s[0:1], 0, v[98:99]
	v_lshl_add_u64 v[16:17], v[16:17], 0, v[84:85]
	global_load_dwordx2 v[16:17], v[16:17], off
	v_rcp_f32_e32 v12, v12
	s_nop 0
	v_mul_f32_e32 v12, 0xc1000000, v12
	v_mul_f32_e32 v12, v68, v12
	v_add_f32_e32 v21, v12, v12
	v_mul_f32_e32 v247, 0x3fb8aa3b, v21
	v_exp_f32_e32 v247, v247
	v_fma_f32 v20, v21, s14, 0.5
	v_fma_f32 v20, v21, v20, 1.0
	v_cmp_nlt_f32_e32 vcc, s51, v21
	v_mul_f32_e64 v20, v20, -v21
	v_sub_f32_e32 v247, 1.0, v247
	v_cndmask_b32_e32 v20, v20, v247, vcc
	v_add_f32_e32 v13, v13, v73
	v_mul_f32_e32 v13, 0xbfb8aa3b, v13
	v_exp_f32_e32 v13, v13
	s_nop 0
	v_add_f32_e32 v13, 1.0, v13
	v_rcp_f32_e32 v13, v13
	s_nop 0
	v_mul_f32_e32 v13, 0xc1000000, v13
	v_mul_f32_e32 v13, v69, v13
	v_add_f32_e32 v21, v13, v13
	v_mul_f32_e32 v247, 0x3fb8aa3b, v21
	v_exp_f32_e32 v247, v247
	v_fma_f32 v22, v21, s14, 0.5
	v_fma_f32 v22, v21, v22, 1.0
	v_cmp_nlt_f32_e32 vcc, s51, v21
	v_mul_f32_e64 v22, v22, -v21
	v_sub_f32_e32 v247, 1.0, v247
	v_cndmask_b32_e32 v22, v22, v247, vcc
	v_add_f32_e32 v14, v14, v74
	v_mul_f32_e32 v14, 0xbfb8aa3b, v14
	v_exp_f32_e32 v14, v14
	s_nop 0
	v_add_f32_e32 v14, 1.0, v14
	v_rcp_f32_e32 v14, v14
	s_nop 0
	v_mul_f32_e32 v14, 0xc1000000, v14
	v_mul_f32_e32 v14, v70, v14
	v_add_f32_e32 v21, v14, v14
	v_mul_f32_e32 v247, 0x3fb8aa3b, v21
	v_exp_f32_e32 v247, v247
	v_fma_f32 v23, v21, s14, 0.5
	v_fma_f32 v23, v21, v23, 1.0
	v_cmp_nlt_f32_e32 vcc, s51, v21
	v_mul_f32_e64 v23, v23, -v21
	v_sub_f32_e32 v247, 1.0, v247
	v_cndmask_b32_e32 v23, v23, v247, vcc
	v_add_f32_e32 v15, v15, v75
	v_mul_f32_e32 v15, 0xbfb8aa3b, v15
	v_exp_f32_e32 v15, v15
	s_nop 0
	v_add_f32_e32 v15, 1.0, v15
	v_rcp_f32_e32 v15, v15
	s_nop 0
	v_mul_f32_e32 v15, 0xc1000000, v15
	v_mul_f32_e32 v15, v71, v15
	v_add_f32_e32 v24, v15, v15
	v_mul_f32_e32 v247, 0x3fb8aa3b, v24
	v_exp_f32_e32 v247, v247
	v_fma_f32 v21, v24, s14, 0.5
	v_fma_f32 v21, v24, v21, 1.0
	v_cmp_nlt_f32_e32 vcc, s51, v24
	v_mul_f32_e64 v21, v21, -v24
	v_sub_f32_e32 v247, 1.0, v247
	v_cndmask_b32_e32 v21, v21, v247, vcc
	v_add_f32_e32 v10, v10, v66
	v_mul_f32_e32 v10, 0xbfb8aa3b, v10
	v_exp_f32_e32 v10, v10
	v_max_f32_e32 v23, 0, v23
	v_add_f32_e32 v11, v11, v67
	v_add_f32_e32 v10, 1.0, v10
	v_mul_f32_e32 v11, 0xbfb8aa3b, v11
	v_exp_f32_e32 v11, v11
	v_add_f32_e32 v9, v9, v65
	v_rcp_f32_e32 v10, v10
	v_add_f32_e32 v11, 1.0, v11
	v_sqrt_f32_e32 v23, v23
	s_waitcnt vmcnt(0)
	v_lshlrev_b32_e32 v24, 16, v19
	v_mul_f32_e32 v9, 0xbfb8aa3b, v9
	v_mul_f32_e32 v10, v10, v23
	v_mul_f32_e32 v10, v10, v24
	v_exp_f32_e32 v9, v9
	v_max_f32_e32 v22, 0, v22
	v_add_f32_e32 v9, 1.0, v9
	v_rcp_f32_e32 v11, v11
	v_add_f32_e32 v8, v8, v64
	v_mul_f32_e32 v8, 0xbfb8aa3b, v8
	v_exp_f32_e32 v8, v8
	v_rcp_f32_e32 v9, v9
	v_and_b32_e32 v23, 0xffff0000, v18
	v_sqrt_f32_e32 v22, v22
	v_add_f32_e32 v8, 1.0, v8
	v_add_f32_e32 v4, v4, v72
	v_mul_f32_e32 v9, v9, v22
	v_mul_f32_e32 v22, v9, v23
	v_lshlrev_b32_e32 v9, 16, v18
	v_mul_f32_e32 v4, 0xbfb8aa3b, v4
	v_exp_f32_e32 v4, v4
	v_rcp_f32_e32 v8, v8
	v_max_f32_e32 v18, 0, v20
	v_add_f32_e32 v4, 1.0, v4
	v_sqrt_f32_e32 v18, v18
	s_nop 0
	v_mul_f32_e32 v8, v8, v18
	v_mul_f32_e32 v18, v8, v9
	v_max_f32_e32 v9, 0, v21
	v_and_b32_e32 v8, 0xffff0000, v19
	v_sqrt_f32_e32 v9, v9
	s_nop 0
	v_mul_f32_e32 v9, v11, v9
	v_mul_f32_e32 v11, v9, v8
	v_cvt_pk_bf16_f32 v8, v12, v13
	v_cvt_pk_bf16_f32 v9, v14, v15
	global_store_dwordx2 v[80:81], v[8:9], off offset:128
	v_cvt_pk_bf16_f32 v8, v18, v22
	v_cvt_pk_bf16_f32 v9, v10, v11
	global_store_dwordx2 v[82:83], v[8:9], off offset:128
	v_rcp_f32_e32 v4, v4
	s_nop 0
	v_mul_f32_e32 v4, 0xc1000000, v4
	v_mul_f32_e32 v4, v68, v4
	v_add_f32_e32 v9, v4, v4
	v_mul_f32_e32 v247, 0x3fb8aa3b, v9
	v_exp_f32_e32 v247, v247
	v_fma_f32 v8, v9, s14, 0.5
	v_fma_f32 v8, v9, v8, 1.0
	v_cmp_nlt_f32_e32 vcc, s51, v9
	v_mul_f32_e64 v8, v8, -v9
	v_sub_f32_e32 v247, 1.0, v247
	v_cndmask_b32_e32 v8, v8, v247, vcc
	v_add_f32_e32 v5, v5, v73
	v_mul_f32_e32 v5, 0xbfb8aa3b, v5
	v_exp_f32_e32 v5, v5
	s_nop 0
	v_add_f32_e32 v5, 1.0, v5
	v_rcp_f32_e32 v5, v5
	s_nop 0
	v_mul_f32_e32 v5, 0xc1000000, v5
	v_mul_f32_e32 v5, v69, v5
	v_add_f32_e32 v9, v5, v5
	v_mul_f32_e32 v247, 0x3fb8aa3b, v9
	v_exp_f32_e32 v247, v247
	v_fma_f32 v10, v9, s14, 0.5
	v_fma_f32 v10, v9, v10, 1.0
	v_cmp_nlt_f32_e32 vcc, s51, v9
	v_mul_f32_e64 v10, v10, -v9
	v_sub_f32_e32 v247, 1.0, v247
	v_cndmask_b32_e32 v10, v10, v247, vcc
	v_add_f32_e32 v6, v6, v74
	v_mul_f32_e32 v6, 0xbfb8aa3b, v6
	v_exp_f32_e32 v6, v6
	s_nop 0
	v_add_f32_e32 v6, 1.0, v6
	v_rcp_f32_e32 v6, v6
	s_nop 0
	v_mul_f32_e32 v6, 0xc1000000, v6
	v_mul_f32_e32 v6, v70, v6
	v_add_f32_e32 v9, v6, v6
	v_mul_f32_e32 v247, 0x3fb8aa3b, v9
	v_exp_f32_e32 v247, v247
	v_fma_f32 v11, v9, s14, 0.5
	v_fma_f32 v11, v9, v11, 1.0
	v_cmp_nlt_f32_e32 vcc, s51, v9
	v_mul_f32_e64 v11, v11, -v9
	v_sub_f32_e32 v247, 1.0, v247
	v_cndmask_b32_e32 v11, v11, v247, vcc
	v_add_f32_e32 v7, v7, v75
	v_mul_f32_e32 v7, 0xbfb8aa3b, v7
	v_exp_f32_e32 v7, v7
	s_nop 0
	v_add_f32_e32 v7, 1.0, v7
	v_rcp_f32_e32 v7, v7
	s_nop 0
	v_mul_f32_e32 v7, 0xc1000000, v7
	v_mul_f32_e32 v7, v71, v7
	v_add_f32_e32 v12, v7, v7
	v_cmp_nlt_f32_e32 vcc, s51, v12
	s_and_saveexec_b64 s[0:1], vcc
	s_xor_b64 s[0:1], exec, s[0:1]
	v_mul_f32_e32 v9, 0x3fb8aa3b, v12
	v_exp_f32_e32 v9, v9
	s_nop 0
	v_sub_f32_e32 v9, 1.0, v9
	s_andn2_saveexec_b64 s[0:1], s[0:1]
	s_cbranch_execz .LBB0_446
	v_fma_f32 v9, v12, s14, 0.5
	v_fma_f32 v9, v12, v9, 1.0
	v_mul_f32_e64 v9, v9, -v12
	s_branch .LBB0_446
